# GEMM K-loops: late LDS fragment reads (ks2,ks3 issued between MFMAs 5-8); HGRN: dead logf branches removed + next-chunk prefetch left in flight across the MFMA stage; attention: skip O rescale when al
# speedup vs baseline: 1.0334x; 1.0208x over previous
.LBB0_39:
	ds_read_b128 v[188:191], v160
	ds_read_b128 v[192:195], v160 offset:32
	ds_read_b128 v[196:199], v161 offset:36864
	ds_read_b128 v[200:203], v161 offset:36896
	ds_read_b128 v[204:207], v160 offset:4608
	ds_read_b128 v[208:211], v160 offset:4640
	ds_read_b128 v[212:215], v161 offset:41472
	ds_read_b128 v[216:219], v161 offset:41504
	s_add_i32 s47, s50, 2
	s_waitcnt lgkmcnt(5)
	v_mfma_f32_32x32x16_bf16 v[50:65], v[188:191], v[196:199], v[50:65]
	s_waitcnt vmcnt(15)
	ds_write_b128 v184, v[66:69] offset:18432
	s_cmp_lt_u32 s47, 41
	s_cselect_b64 s[52:53], -1, 0
	s_and_b64 s[20:21], s[52:53], exec
	s_cselect_b32 s20, 0, 0x1ffffd4
	s_add_i32 s20, s20, s50
	s_lshl_b32 s51, s20, 7
	s_waitcnt lgkmcnt(2)
	v_mfma_f32_32x32x16_bf16 v[34:49], v[188:191], v[212:215], v[34:49]
	s_waitcnt vmcnt(14)
	ds_write_b128 v184, v[74:77] offset:55296
	s_add_i32 s56, s51, 0x280
	s_and_b64 s[20:21], s[52:53], exec
	s_cselect_b32 s21, s27, s41
	s_cselect_b32 s20, s40, s31
	s_and_b32 s21, s21, 0xffff
	s_and_b64 s[52:53], s[52:53], exec
	s_waitcnt lgkmcnt(5)
	v_mfma_f32_32x32x16_bf16 v[16:31], v[204:207], v[196:199], v[16:31]
	s_waitcnt vmcnt(13)
	ds_write_b128 v185, v[70:73] offset:18432
	s_cselect_b32 s53, s30, s46
	s_cselect_b32 s52, s44, s45
	s_and_b32 s53, s53, 0xffff
	s_mov_b32 s54, s22
	s_mov_b32 s55, s23
	s_waitcnt lgkmcnt(4)
	v_mfma_f32_32x32x16_bf16 v[0:15], v[204:207], v[212:215], v[0:15]
	s_waitcnt vmcnt(12)
	ds_write_b128 v185, v[82:85] offset:55296
	s_waitcnt lgkmcnt(8)
	v_mfma_f32_32x32x16_bf16 v[50:65], v[192:195], v[200:203], v[50:65]
	ds_read_b128 v[220:223], v160 offset:64
	ds_read_b128 v[142:145], v160 offset:96
	s_waitcnt vmcnt(11)
	ds_write_b128 v186, v[78:81] offset:18432
	s_waitcnt lgkmcnt(7)
	v_mfma_f32_32x32x16_bf16 v[34:49], v[192:195], v[216:219], v[34:49]
	ds_read_b128 v[154:157], v161 offset:36928
	ds_read_b128 v[138:141], v161 offset:36960
	s_waitcnt vmcnt(10)
	ds_write_b128 v186, v[90:93] offset:55296
	s_waitcnt lgkmcnt(12)
	v_mfma_f32_32x32x16_bf16 v[16:31], v[208:211], v[200:203], v[16:31]
	ds_read_b128 v[146:149], v160 offset:4672
	ds_read_b128 v[130:133], v160 offset:4704
	s_waitcnt vmcnt(9)
	ds_write_b128 v187, v[86:89] offset:18432
	s_waitcnt lgkmcnt(13)
	v_mfma_f32_32x32x16_bf16 v[0:15], v[208:211], v[216:219], v[0:15]
	ds_read_b128 v[150:153], v161 offset:41536
	ds_read_b128 v[134:137], v161 offset:41568
	s_waitcnt vmcnt(8)
	ds_write_b128 v187, v[94:97] offset:55296
	s_waitcnt lgkmcnt(8)
	v_mfma_f32_32x32x16_bf16 v[50:65], v[220:223], v[154:157], v[50:65]
	buffer_load_dwordx4 v[66:69], v180, s[20:23], s56 offen
	s_waitcnt lgkmcnt(2)
	v_mfma_f32_32x32x16_bf16 v[34:49], v[220:223], v[150:153], v[34:49]
	buffer_load_dwordx4 v[74:77], v180, s[52:55], s56 offen
	s_add_i32 s56, s51, 0x2c280
	s_waitcnt lgkmcnt(5)
	v_mfma_f32_32x32x16_bf16 v[16:31], v[146:149], v[154:157], v[16:31]
	buffer_load_dwordx4 v[70:73], v180, s[20:23], s56 offen
	s_waitcnt lgkmcnt(2)
	v_mfma_f32_32x32x16_bf16 v[0:15], v[146:149], v[150:153], v[0:15]
	buffer_load_dwordx4 v[82:85], v180, s[52:55], s56 offen
	s_add_i32 s56, s51, 0x58280
	s_add_i32 s51, s51, 0x84280
	s_waitcnt lgkmcnt(7)
	v_mfma_f32_32x32x16_bf16 v[50:65], v[142:145], v[138:141], v[50:65]
	buffer_load_dwordx4 v[78:81], v180, s[20:23], s56 offen
	s_waitcnt lgkmcnt(1)
	v_mfma_f32_32x32x16_bf16 v[34:49], v[142:145], v[134:137], v[34:49]
	buffer_load_dwordx4 v[90:93], v180, s[52:55], s56 offen
	s_waitcnt lgkmcnt(4)
	v_mfma_f32_32x32x16_bf16 v[16:31], v[130:133], v[138:141], v[16:31]
	buffer_load_dwordx4 v[86:89], v180, s[20:23], s51 offen
	s_waitcnt lgkmcnt(1)
	v_mfma_f32_32x32x16_bf16 v[0:15], v[130:133], v[134:137], v[0:15]
	buffer_load_dwordx4 v[94:97], v180, s[52:55], s51 offen
	s_waitcnt lgkmcnt(0)
	s_barrier
	ds_read_b128 v[188:191], v160 offset:18432
	ds_read_b128 v[192:195], v160 offset:18464
	ds_read_b128 v[196:199], v161 offset:55296
	ds_read_b128 v[200:203], v161 offset:55328
	ds_read_b128 v[204:207], v160 offset:23040
	ds_read_b128 v[208:211], v160 offset:23072
	ds_read_b128 v[212:215], v161 offset:59904
	ds_read_b128 v[216:219], v161 offset:59936
	s_waitcnt lgkmcnt(5)
	v_mfma_f32_32x32x16_bf16 v[50:65], v[188:191], v[196:199], v[50:65]
	s_waitcnt vmcnt(15)
	ds_write_b128 v184, v[98:101]
	s_cmp_lt_u32 s47, 40
	s_cselect_b64 s[52:53], -1, 0
	s_and_b64 s[20:21], s[52:53], exec
	s_cselect_b32 s20, 0, 0x1ffffd4
	s_add_i32 s20, s20, s50
	s_lshl_b32 s56, s20, 7
	s_waitcnt lgkmcnt(2)
	v_mfma_f32_32x32x16_bf16 v[34:49], v[188:191], v[212:215], v[34:49]
	s_waitcnt vmcnt(14)
	ds_write_b128 v184, v[106:109] offset:36864
	s_add_i32 s57, s56, 0x300
	s_and_b64 s[20:21], s[52:53], exec
	s_cselect_b32 s21, s27, s41
	s_cselect_b32 s20, s40, s31
	s_and_b32 s21, s21, 0xffff
	s_and_b64 s[50:51], s[52:53], exec
	s_waitcnt lgkmcnt(5)
	v_mfma_f32_32x32x16_bf16 v[16:31], v[204:207], v[196:199], v[16:31]
	s_waitcnt vmcnt(13)
	ds_write_b128 v185, v[102:105]
	s_cselect_b32 s50, s30, s46
	s_cselect_b32 s52, s44, s45
	s_and_b32 s53, s50, 0xffff
	s_add_i32 s50, s56, 0x2c300
	s_waitcnt lgkmcnt(4)
	v_mfma_f32_32x32x16_bf16 v[0:15], v[204:207], v[212:215], v[0:15]
	s_waitcnt vmcnt(12)
	ds_write_b128 v185, v[114:117] offset:36864
	s_waitcnt lgkmcnt(8)
	v_mfma_f32_32x32x16_bf16 v[50:65], v[192:195], v[200:203], v[50:65]
	ds_read_b128 v[220:223], v160 offset:18496
	ds_read_b128 v[142:145], v160 offset:18528
	s_waitcnt vmcnt(11)
	ds_write_b128 v186, v[110:113]
	s_waitcnt lgkmcnt(7)
	v_mfma_f32_32x32x16_bf16 v[34:49], v[192:195], v[216:219], v[34:49]
	ds_read_b128 v[154:157], v161 offset:55360
	ds_read_b128 v[138:141], v161 offset:55392
	s_waitcnt vmcnt(10)
	ds_write_b128 v186, v[122:125] offset:36864
	s_waitcnt lgkmcnt(12)
	v_mfma_f32_32x32x16_bf16 v[16:31], v[208:211], v[200:203], v[16:31]
	ds_read_b128 v[146:149], v160 offset:23104
	ds_read_b128 v[130:133], v160 offset:23136
	s_waitcnt vmcnt(9)
	ds_write_b128 v187, v[118:121]
	s_waitcnt lgkmcnt(13)
	v_mfma_f32_32x32x16_bf16 v[0:15], v[208:211], v[216:219], v[0:15]
	ds_read_b128 v[150:153], v161 offset:59968
	ds_read_b128 v[134:137], v161 offset:60000
	s_waitcnt vmcnt(8)
	ds_write_b128 v187, v[126:129] offset:36864
	s_waitcnt lgkmcnt(8)
	v_mfma_f32_32x32x16_bf16 v[50:65], v[220:223], v[154:157], v[50:65]
	buffer_load_dwordx4 v[98:101], v180, s[20:23], s57 offen
	s_waitcnt lgkmcnt(2)
	v_mfma_f32_32x32x16_bf16 v[34:49], v[220:223], v[150:153], v[34:49]
	buffer_load_dwordx4 v[106:109], v180, s[52:55], s57 offen
	s_waitcnt lgkmcnt(5)
	v_mfma_f32_32x32x16_bf16 v[16:31], v[146:149], v[154:157], v[16:31]
	buffer_load_dwordx4 v[102:105], v180, s[20:23], s50 offen
	s_waitcnt lgkmcnt(2)
	v_mfma_f32_32x32x16_bf16 v[0:15], v[146:149], v[150:153], v[0:15]
	buffer_load_dwordx4 v[114:117], v180, s[52:55], s50 offen
	s_add_i32 s50, s56, 0x58300
	s_add_i32 s56, s56, 0x84300
	s_waitcnt lgkmcnt(7)
	v_mfma_f32_32x32x16_bf16 v[50:65], v[142:145], v[138:141], v[50:65]
	buffer_load_dwordx4 v[110:113], v180, s[20:23], s50 offen
	s_waitcnt lgkmcnt(1)
	v_mfma_f32_32x32x16_bf16 v[34:49], v[142:145], v[134:137], v[34:49]
	buffer_load_dwordx4 v[122:125], v180, s[52:55], s50 offen
	s_waitcnt lgkmcnt(4)
	v_mfma_f32_32x32x16_bf16 v[16:31], v[130:133], v[138:141], v[16:31]
	buffer_load_dwordx4 v[118:121], v180, s[20:23], s56 offen
	s_waitcnt lgkmcnt(1)
	v_mfma_f32_32x32x16_bf16 v[0:15], v[130:133], v[134:137], v[0:15]
	buffer_load_dwordx4 v[126:129], v180, s[52:55], s56 offen
	s_cmp_gt_u32 s47, 41
	s_mov_b32 s50, s47
	s_waitcnt lgkmcnt(0)
	s_barrier
	s_cbranch_scc0 .LBB0_39
	s_cmpk_lt_i32 s25, 0x80
	s_cselect_b32 s20, s0, 0
	s_add_i32 s21, s20, 0xffffe000
	s_lshr_b32 s21, s21, 10
	s_add_i32 s21, s21, 1
	s_cmpk_gt_i32 s20, 0x1fff
	v_readlane_b32 s30, v232, 27
	s_cselect_b32 s20, s21, 0
	s_mul_i32 s21, s30, 9
	s_add_i32 s20, s20, s21
	v_and_b32_e32 v32, 64, v32
	s_mul_hi_i32 s21, s20, 0x6000
	s_mulk_i32 s20, 0x6000
	s_add_u32 s20, s94, s20
	v_or3_b32 v32, s24, v32, v181
	v_add_u32_e32 v130, s0, v183
	s_addc_u32 s21, s95, s21
	v_lshlrev_b32_e32 v131, 2, v182
	v_or_b32_e32 v132, s38, v32
	s_add_u32 s20, s20, 0x6025000
	v_lshlrev_b32_e32 v142, 2, v32
	v_or_b32_e32 v130, v130, v131
	v_ashrrev_i32_e32 v133, 31, v132
	s_addc_u32 s21, s21, 0
	s_lshl_b64 s[0:1], s[0:1], 12
	v_lshlrev_b32_e32 v136, 3, v130
	v_or_b32_e32 v130, 0x80, v142
	v_lshlrev_b64 v[132:133], 2, v[132:133]
	v_lshl_add_u64 v[138:139], v[32:33], 0, s[38:39]
	s_add_u32 s0, s92, s0
	v_or_b32_e32 v137, v131, v183
	global_load_dword v131, v142, s[20:21]
	v_lshl_add_u64 v[134:135], s[14:15], 0, v[132:133]
	global_load_dword v130, v130, s[20:21]
	v_lshlrev_b64 v[138:139], 2, v[138:139]
	v_readlane_b32 s20, v235, 38
	s_addc_u32 s1, s93, s1
	global_load_dword v134, v[134:135], off
	v_lshl_add_u64 v[140:141], s[14:15], 0, v[138:139]
	v_lshl_add_u64 v[132:133], s[16:17], 0, v[132:133]
	v_lshl_add_u64 v[138:139], s[16:17], 0, v[138:139]
	v_readlane_b32 s21, v235, 39
	v_lshl_or_b32 v135, v137, 12, v142
	global_load_dword v133, v[132:133], off
	v_readlane_b32 s52, v233, 61
	global_load_dword v132, v[138:139], off offset:128
	global_load_dword v137, v135, s[0:1]
	global_load_dword v32, v[140:141], off offset:128
	v_readlane_b32 s31, v232, 28
	global_load_dwordx2 v[138:139], v136, s[20:21]
	global_load_dword v140, v135, s[0:1] offset:128
	v_readlane_b32 s62, v232, 7
	v_readlane_b32 s63, v232, 8
	s_and_b64 vcc, exec, s[42:43]
	s_mov_b32 s31, s37
	v_readlane_b32 s53, v233, 62
	v_readlane_b32 s56, v232, 1
	v_readlane_b32 s57, v232, 2
	v_readlane_b32 s58, v232, 3
	v_readlane_b32 s59, v232, 4
	v_readlane_b32 s60, v232, 5
	v_readlane_b32 s61, v232, 6
	v_readlane_b32 s64, v232, 9
	v_readlane_b32 s65, v232, 10
	v_readlane_b32 s66, v232, 11
	v_readlane_b32 s67, v232, 12
	v_readlane_b32 s63, v235, 21
	s_movk_i32 s51, 0x3fff
	v_readlane_b32 s62, v232, 31
	v_readlane_b32 s54, v233, 63
	v_readlane_b32 s55, v232, 0
	s_waitcnt vmcnt(1)
	v_sub_f32_e32 v137, v137, v138
	v_mul_f32_e32 v137, v139, v137
	s_waitcnt vmcnt(0)
	v_sub_f32_e32 v138, v140, v138
	v_fma_f32 v137, v134, v137, v133
	v_mul_f32_e32 v138, v139, v138
	v_fma_f32 v138, v32, v138, v132
	v_mul_f32_e32 v137, 0x3fd744fd, v137
	v_fmac_f32_e32 v137, v50, v131
	v_mul_f32_e32 v50, 0x3fd744fd, v138
	v_fmac_f32_e32 v50, v34, v130
	global_store_dword v135, v137, s[0:1]
	global_store_dword v135, v50, s[0:1] offset:128
	v_or_b32_e32 v34, 0x1000, v135
	global_load_dwordx2 v[138:139], v136, s[20:21] offset:8
	global_load_dword v50, v34, s[0:1]
	global_load_dword v137, v34, s[0:1] offset:128
	s_waitcnt vmcnt(1)
	v_sub_f32_e32 v50, v50, v138
	v_mul_f32_e32 v50, v139, v50
	v_fma_f32 v50, v134, v50, v133
	s_waitcnt vmcnt(0)
	v_sub_f32_e32 v137, v137, v138
	v_mul_f32_e32 v137, v139, v137
	v_mul_f32_e32 v50, 0x3fd744fd, v50
	v_fma_f32 v137, v32, v137, v132
	v_fmac_f32_e32 v50, v51, v131
	global_store_dword v34, v50, s[0:1]
	v_mul_f32_e32 v50, 0x3fd744fd, v137
	v_fmac_f32_e32 v50, v35, v130
	global_store_dword v34, v50, s[0:1] offset:128
	v_or_b32_e32 v50, 0x2000, v135
	global_load_dwordx2 v[34:35], v136, s[20:21] offset:16
	global_load_dword v51, v50, s[0:1]
	global_load_dword v137, v50, s[0:1] offset:128
	s_waitcnt vmcnt(1)
	v_sub_f32_e32 v51, v51, v34
	s_waitcnt vmcnt(0)
	v_sub_f32_e32 v34, v137, v34
	v_mul_f32_e32 v51, v35, v51
	v_mul_f32_e32 v34, v35, v34
	v_fma_f32 v51, v134, v51, v133
	v_fma_f32 v34, v32, v34, v132
	v_mul_f32_e32 v35, 0x3fd744fd, v51
	v_mul_f32_e32 v34, 0x3fd744fd, v34
	v_fmac_f32_e32 v35, v52, v131
	v_fmac_f32_e32 v34, v36, v130
	global_store_dword v50, v35, s[0:1]
	global_store_dword v50, v34, s[0:1] offset:128
	v_or_b32_e32 v36, 0x3000, v135
	global_load_dwordx2 v[34:35], v136, s[20:21] offset:24
	global_load_dword v50, v36, s[0:1]
	global_load_dword v51, v36, s[0:1] offset:128
	s_waitcnt vmcnt(1)
	v_sub_f32_e32 v50, v50, v34
	s_waitcnt vmcnt(0)
	v_sub_f32_e32 v34, v51, v34
	v_mul_f32_e32 v50, v35, v50
	v_mul_f32_e32 v34, v35, v34
	v_fma_f32 v50, v134, v50, v133
	v_fma_f32 v34, v32, v34, v132
	v_mul_f32_e32 v35, 0x3fd744fd, v50
	v_mul_f32_e32 v34, 0x3fd744fd, v34
	v_fmac_f32_e32 v35, v53, v131
	v_fmac_f32_e32 v34, v37, v130
	global_store_dword v36, v35, s[0:1]
	global_store_dword v36, v34, s[0:1] offset:128
	v_or_b32_e32 v36, 0x8000, v135
	global_load_dwordx2 v[34:35], v136, s[20:21] offset:64
	global_load_dword v37, v36, s[0:1]
	global_load_dword v50, v36, s[0:1] offset:128
	s_waitcnt vmcnt(1)
	v_sub_f32_e32 v37, v37, v34
	s_waitcnt vmcnt(0)
	v_sub_f32_e32 v34, v50, v34
	v_mul_f32_e32 v37, v35, v37
	v_mul_f32_e32 v34, v35, v34
	v_fma_f32 v37, v134, v37, v133
	v_fma_f32 v34, v32, v34, v132
	v_mul_f32_e32 v35, 0x3fd744fd, v37
	v_mul_f32_e32 v34, 0x3fd744fd, v34
	v_fmac_f32_e32 v35, v54, v131
	v_fmac_f32_e32 v34, v38, v130
	global_store_dword v36, v35, s[0:1]
	global_store_dword v36, v34, s[0:1] offset:128
	v_or_b32_e32 v36, 0x9000, v135
	global_load_dwordx2 v[34:35], v136, s[20:21] offset:72
	global_load_dword v37, v36, s[0:1]
	global_load_dword v38, v36, s[0:1] offset:128
	s_waitcnt vmcnt(1)
	v_sub_f32_e32 v37, v37, v34
	s_waitcnt vmcnt(0)
	v_sub_f32_e32 v34, v38, v34
	v_mul_f32_e32 v37, v35, v37
	v_mul_f32_e32 v34, v35, v34
	v_fma_f32 v37, v134, v37, v133
	v_fma_f32 v34, v32, v34, v132
	v_mul_f32_e32 v35, 0x3fd744fd, v37
	v_mul_f32_e32 v34, 0x3fd744fd, v34
	v_fmac_f32_e32 v35, v55, v131
	v_fmac_f32_e32 v34, v39, v130
	global_store_dword v36, v35, s[0:1]
	global_store_dword v36, v34, s[0:1] offset:128
	v_or_b32_e32 v36, 0xa000, v135
	global_load_dwordx2 v[34:35], v136, s[20:21] offset:80
	global_load_dword v37, v36, s[0:1]
	global_load_dword v38, v36, s[0:1] offset:128
	s_waitcnt vmcnt(1)
	v_sub_f32_e32 v37, v37, v34
	s_waitcnt vmcnt(0)
	v_sub_f32_e32 v34, v38, v34
	v_mul_f32_e32 v37, v35, v37
	v_mul_f32_e32 v34, v35, v34
	v_fma_f32 v37, v134, v37, v133
	v_fma_f32 v34, v32, v34, v132
	v_mul_f32_e32 v35, 0x3fd744fd, v37
	v_mul_f32_e32 v34, 0x3fd744fd, v34
	v_fmac_f32_e32 v35, v56, v131
	v_fmac_f32_e32 v34, v40, v130
	global_store_dword v36, v35, s[0:1]
	global_store_dword v36, v34, s[0:1] offset:128
	v_or_b32_e32 v36, 0xb000, v135
	global_load_dwordx2 v[34:35], v136, s[20:21] offset:88
	global_load_dword v37, v36, s[0:1]
	global_load_dword v38, v36, s[0:1] offset:128
	s_waitcnt vmcnt(1)
	v_sub_f32_e32 v37, v37, v34
	s_waitcnt vmcnt(0)
	v_sub_f32_e32 v34, v38, v34
	v_mul_f32_e32 v37, v35, v37
	v_mul_f32_e32 v34, v35, v34
	v_fma_f32 v37, v134, v37, v133
	v_fma_f32 v34, v32, v34, v132
	v_mul_f32_e32 v35, 0x3fd744fd, v37
	v_mul_f32_e32 v34, 0x3fd744fd, v34
	v_fmac_f32_e32 v35, v57, v131
	v_fmac_f32_e32 v34, v41, v130
	global_store_dword v36, v35, s[0:1]
	global_store_dword v36, v34, s[0:1] offset:128
	v_or_b32_e32 v36, 0x10000, v135
	global_load_dwordx2 v[34:35], v136, s[20:21] offset:128
	global_load_dword v37, v36, s[0:1]
	global_load_dword v38, v36, s[0:1] offset:128
	s_waitcnt vmcnt(1)
	v_sub_f32_e32 v37, v37, v34
	s_waitcnt vmcnt(0)
	v_sub_f32_e32 v34, v38, v34
	v_mul_f32_e32 v37, v35, v37
	v_mul_f32_e32 v34, v35, v34
	v_fma_f32 v37, v134, v37, v133
	v_fma_f32 v34, v32, v34, v132
	v_mul_f32_e32 v35, 0x3fd744fd, v37
	v_mul_f32_e32 v34, 0x3fd744fd, v34
	v_fmac_f32_e32 v35, v58, v131
	v_fmac_f32_e32 v34, v42, v130
	global_store_dword v36, v35, s[0:1]
	global_store_dword v36, v34, s[0:1] offset:128
	v_or_b32_e32 v36, 0x11000, v135
	global_load_dwordx2 v[34:35], v136, s[20:21] offset:136
	global_load_dword v37, v36, s[0:1]
	global_load_dword v38, v36, s[0:1] offset:128
	s_waitcnt vmcnt(1)
	v_sub_f32_e32 v37, v37, v34
	s_waitcnt vmcnt(0)
	v_sub_f32_e32 v34, v38, v34
	v_mul_f32_e32 v37, v35, v37
	v_mul_f32_e32 v34, v35, v34
	v_fma_f32 v37, v134, v37, v133
	v_fma_f32 v34, v32, v34, v132
	v_mul_f32_e32 v35, 0x3fd744fd, v37
	v_mul_f32_e32 v34, 0x3fd744fd, v34
	v_fmac_f32_e32 v35, v59, v131
	v_fmac_f32_e32 v34, v43, v130
	global_store_dword v36, v35, s[0:1]
	global_store_dword v36, v34, s[0:1] offset:128
	v_or_b32_e32 v36, 0x12000, v135
	global_load_dwordx2 v[34:35], v136, s[20:21] offset:144
	global_load_dword v37, v36, s[0:1]
	global_load_dword v38, v36, s[0:1] offset:128
	s_waitcnt vmcnt(1)
	v_sub_f32_e32 v37, v37, v34
	s_waitcnt vmcnt(0)
	v_sub_f32_e32 v34, v38, v34
	v_mul_f32_e32 v37, v35, v37
	v_mul_f32_e32 v34, v35, v34
	v_fma_f32 v37, v134, v37, v133
	v_fma_f32 v34, v32, v34, v132
	v_mul_f32_e32 v35, 0x3fd744fd, v37
	v_mul_f32_e32 v34, 0x3fd744fd, v34
	v_fmac_f32_e32 v35, v60, v131
	v_fmac_f32_e32 v34, v44, v130
	global_store_dword v36, v35, s[0:1]
	global_store_dword v36, v34, s[0:1] offset:128
	v_or_b32_e32 v36, 0x13000, v135
	global_load_dwordx2 v[34:35], v136, s[20:21] offset:152
	global_load_dword v37, v36, s[0:1]
	global_load_dword v38, v36, s[0:1] offset:128
	s_waitcnt vmcnt(1)
	v_sub_f32_e32 v37, v37, v34
	s_waitcnt vmcnt(0)
	v_sub_f32_e32 v34, v38, v34
	v_mul_f32_e32 v37, v35, v37
	v_mul_f32_e32 v34, v35, v34
	v_fma_f32 v37, v134, v37, v133
	v_fma_f32 v34, v32, v34, v132
	v_mul_f32_e32 v35, 0x3fd744fd, v37
	v_mul_f32_e32 v34, 0x3fd744fd, v34
	v_fmac_f32_e32 v35, v61, v131
	v_fmac_f32_e32 v34, v45, v130
	global_store_dword v36, v35, s[0:1]
	global_store_dword v36, v34, s[0:1] offset:128
	v_or_b32_e32 v36, 0x18000, v135
	global_load_dwordx2 v[34:35], v136, s[20:21] offset:192
	global_load_dword v37, v36, s[0:1]
	global_load_dword v38, v36, s[0:1] offset:128
	s_waitcnt vmcnt(1)
	v_sub_f32_e32 v37, v37, v34
	s_waitcnt vmcnt(0)
	v_sub_f32_e32 v34, v38, v34
	v_mul_f32_e32 v37, v35, v37
	v_mul_f32_e32 v34, v35, v34
	v_fma_f32 v37, v134, v37, v133
	v_fma_f32 v34, v32, v34, v132
	v_mul_f32_e32 v35, 0x3fd744fd, v37
	v_mul_f32_e32 v34, 0x3fd744fd, v34
	v_fmac_f32_e32 v35, v62, v131
	v_fmac_f32_e32 v34, v46, v130
	global_store_dword v36, v35, s[0:1]
	global_store_dword v36, v34, s[0:1] offset:128
	v_or_b32_e32 v36, 0x19000, v135
	global_load_dwordx2 v[34:35], v136, s[20:21] offset:200
	global_load_dword v37, v36, s[0:1]
	global_load_dword v38, v36, s[0:1] offset:128
	s_waitcnt vmcnt(1)
	v_sub_f32_e32 v37, v37, v34
	s_waitcnt vmcnt(0)
	v_sub_f32_e32 v34, v38, v34
	v_mul_f32_e32 v37, v35, v37
	v_mul_f32_e32 v34, v35, v34
	v_fma_f32 v37, v134, v37, v133
	v_fma_f32 v34, v32, v34, v132
	v_mul_f32_e32 v35, 0x3fd744fd, v37
	v_mul_f32_e32 v34, 0x3fd744fd, v34
	v_fmac_f32_e32 v35, v63, v131
	v_fmac_f32_e32 v34, v47, v130
	global_store_dword v36, v35, s[0:1]
	global_store_dword v36, v34, s[0:1] offset:128
	v_or_b32_e32 v36, 0x1a000, v135
	global_load_dwordx2 v[34:35], v136, s[20:21] offset:208
	global_load_dword v37, v36, s[0:1]
	global_load_dword v38, v36, s[0:1] offset:128
	s_waitcnt vmcnt(1)
	v_sub_f32_e32 v37, v37, v34
	s_waitcnt vmcnt(0)
	v_sub_f32_e32 v34, v38, v34
	v_mul_f32_e32 v37, v35, v37
	v_mul_f32_e32 v34, v35, v34
	v_fma_f32 v37, v134, v37, v133
	v_fma_f32 v34, v32, v34, v132
	v_mul_f32_e32 v35, 0x3fd744fd, v37
	v_mul_f32_e32 v34, 0x3fd744fd, v34
	v_fmac_f32_e32 v35, v64, v131
	v_fmac_f32_e32 v34, v48, v130
	global_store_dword v36, v35, s[0:1]
	global_store_dword v36, v34, s[0:1] offset:128
	v_or_b32_e32 v36, 0x1b000, v135
	global_load_dwordx2 v[34:35], v136, s[20:21] offset:216
	global_load_dword v37, v36, s[0:1]
	global_load_dword v38, v36, s[0:1] offset:128
	s_waitcnt vmcnt(1)
	v_sub_f32_e32 v37, v37, v34
	s_waitcnt vmcnt(0)
	v_sub_f32_e32 v34, v38, v34
	v_mul_f32_e32 v37, v35, v37
	v_mul_f32_e32 v34, v35, v34
	v_fma_f32 v37, v134, v37, v133
	v_fma_f32 v34, v32, v34, v132
	v_mul_f32_e32 v35, 0x3fd744fd, v37
	v_mul_f32_e32 v34, 0x3fd744fd, v34
	v_fmac_f32_e32 v35, v65, v131
	v_fmac_f32_e32 v34, v49, v130
	global_store_dword v36, v35, s[0:1]
	global_store_dword v36, v34, s[0:1] offset:128
	v_or_b32_e32 v36, 0x20000, v135
	global_load_dwordx2 v[34:35], v136, s[20:21] offset:256
	global_load_dword v37, v36, s[0:1]
	global_load_dword v38, v36, s[0:1] offset:128
	s_waitcnt vmcnt(1)
	v_sub_f32_e32 v37, v37, v34
	v_mul_f32_e32 v37, v35, v37
	s_waitcnt vmcnt(0)
	v_sub_f32_e32 v34, v38, v34
	v_fma_f32 v37, v134, v37, v133
	v_mul_f32_e32 v34, v35, v34
	v_fma_f32 v34, v32, v34, v132
	v_mul_f32_e32 v35, 0x3fd744fd, v37
	v_fmac_f32_e32 v35, v16, v131
	v_mul_f32_e32 v16, 0x3fd744fd, v34
	v_fmac_f32_e32 v16, v0, v130
	global_store_dword v36, v35, s[0:1]
	global_store_dword v36, v16, s[0:1] offset:128
	v_or_b32_e32 v0, 0x21000, v135
	global_load_dwordx2 v[34:35], v136, s[20:21] offset:264
	global_load_dword v16, v0, s[0:1]
	global_load_dword v36, v0, s[0:1] offset:128
	s_waitcnt vmcnt(1)
	v_sub_f32_e32 v16, v16, v34
	v_mul_f32_e32 v16, v35, v16
	v_fma_f32 v16, v134, v16, v133
	s_waitcnt vmcnt(0)
	v_sub_f32_e32 v34, v36, v34
	v_mul_f32_e32 v34, v35, v34
	v_mul_f32_e32 v16, 0x3fd744fd, v16
	v_fma_f32 v34, v32, v34, v132
	v_fmac_f32_e32 v16, v17, v131
	global_store_dword v0, v16, s[0:1]
	v_mul_f32_e32 v16, 0x3fd744fd, v34
	v_fmac_f32_e32 v16, v1, v130
	global_store_dword v0, v16, s[0:1] offset:128
	v_or_b32_e32 v16, 0x22000, v135
	global_load_dwordx2 v[0:1], v136, s[20:21] offset:272
	global_load_dword v17, v16, s[0:1]
	global_load_dword v34, v16, s[0:1] offset:128
	s_waitcnt vmcnt(1)
	v_sub_f32_e32 v17, v17, v0
	s_waitcnt vmcnt(0)
	v_sub_f32_e32 v0, v34, v0
	v_mul_f32_e32 v17, v1, v17
	v_mul_f32_e32 v0, v1, v0
	v_fma_f32 v17, v134, v17, v133
	v_fma_f32 v0, v32, v0, v132
	v_mul_f32_e32 v1, 0x3fd744fd, v17
	v_mul_f32_e32 v0, 0x3fd744fd, v0
	v_fmac_f32_e32 v1, v18, v131
	v_fmac_f32_e32 v0, v2, v130
	global_store_dword v16, v1, s[0:1]
	global_store_dword v16, v0, s[0:1] offset:128
	v_or_b32_e32 v2, 0x23000, v135
	global_load_dwordx2 v[0:1], v136, s[20:21] offset:280
	global_load_dword v16, v2, s[0:1]
	global_load_dword v17, v2, s[0:1] offset:128
	s_waitcnt vmcnt(1)
	v_sub_f32_e32 v16, v16, v0
	s_waitcnt vmcnt(0)
	v_sub_f32_e32 v0, v17, v0
	v_mul_f32_e32 v16, v1, v16
	v_mul_f32_e32 v0, v1, v0
	v_fma_f32 v16, v134, v16, v133
	v_fma_f32 v0, v32, v0, v132
	v_mul_f32_e32 v1, 0x3fd744fd, v16
	v_mul_f32_e32 v0, 0x3fd744fd, v0
	v_fmac_f32_e32 v1, v19, v131
	v_fmac_f32_e32 v0, v3, v130
	global_store_dword v2, v1, s[0:1]
	global_store_dword v2, v0, s[0:1] offset:128
	v_or_b32_e32 v2, 0x28000, v135
	global_load_dwordx2 v[0:1], v136, s[20:21] offset:320
	global_load_dword v3, v2, s[0:1]
	global_load_dword v16, v2, s[0:1] offset:128
	s_waitcnt vmcnt(1)
	v_sub_f32_e32 v3, v3, v0
	s_waitcnt vmcnt(0)
	v_sub_f32_e32 v0, v16, v0
	v_mul_f32_e32 v3, v1, v3
	v_mul_f32_e32 v0, v1, v0
	v_fma_f32 v3, v134, v3, v133
	v_fma_f32 v0, v32, v0, v132
	v_mul_f32_e32 v1, 0x3fd744fd, v3
	v_mul_f32_e32 v0, 0x3fd744fd, v0
	v_fmac_f32_e32 v1, v20, v131
	v_fmac_f32_e32 v0, v4, v130
	global_store_dword v2, v1, s[0:1]
	global_store_dword v2, v0, s[0:1] offset:128
	v_or_b32_e32 v2, 0x29000, v135
	global_load_dwordx2 v[0:1], v136, s[20:21] offset:328
	global_load_dword v3, v2, s[0:1]
	global_load_dword v4, v2, s[0:1] offset:128
	s_waitcnt vmcnt(1)
	v_sub_f32_e32 v3, v3, v0
	s_waitcnt vmcnt(0)
	v_sub_f32_e32 v0, v4, v0
	v_mul_f32_e32 v3, v1, v3
	v_mul_f32_e32 v0, v1, v0
	v_fma_f32 v3, v134, v3, v133
	v_fma_f32 v0, v32, v0, v132
	v_mul_f32_e32 v1, 0x3fd744fd, v3
	v_mul_f32_e32 v0, 0x3fd744fd, v0
	v_fmac_f32_e32 v1, v21, v131
	v_fmac_f32_e32 v0, v5, v130
	global_store_dword v2, v1, s[0:1]
	global_store_dword v2, v0, s[0:1] offset:128
	v_or_b32_e32 v2, 0x2a000, v135
	global_load_dwordx2 v[0:1], v136, s[20:21] offset:336
	global_load_dword v3, v2, s[0:1]
	global_load_dword v4, v2, s[0:1] offset:128
	s_waitcnt vmcnt(1)
	v_sub_f32_e32 v3, v3, v0
	s_waitcnt vmcnt(0)
	v_sub_f32_e32 v0, v4, v0
	v_mul_f32_e32 v3, v1, v3
	v_mul_f32_e32 v0, v1, v0
	v_fma_f32 v3, v134, v3, v133
	v_fma_f32 v0, v32, v0, v132
	v_mul_f32_e32 v1, 0x3fd744fd, v3
	v_mul_f32_e32 v0, 0x3fd744fd, v0
	v_fmac_f32_e32 v1, v22, v131
	v_fmac_f32_e32 v0, v6, v130
	global_store_dword v2, v1, s[0:1]
	global_store_dword v2, v0, s[0:1] offset:128
	v_or_b32_e32 v2, 0x2b000, v135
	global_load_dwordx2 v[0:1], v136, s[20:21] offset:344
	global_load_dword v3, v2, s[0:1]
	global_load_dword v4, v2, s[0:1] offset:128
	s_waitcnt vmcnt(1)
	v_sub_f32_e32 v3, v3, v0
	s_waitcnt vmcnt(0)
	v_sub_f32_e32 v0, v4, v0
	v_mul_f32_e32 v3, v1, v3
	v_mul_f32_e32 v0, v1, v0
	v_fma_f32 v3, v134, v3, v133
	v_fma_f32 v0, v32, v0, v132
	v_mul_f32_e32 v1, 0x3fd744fd, v3
	v_mul_f32_e32 v0, 0x3fd744fd, v0
	v_fmac_f32_e32 v1, v23, v131
	v_fmac_f32_e32 v0, v7, v130
	global_store_dword v2, v1, s[0:1]
	global_store_dword v2, v0, s[0:1] offset:128
	v_or_b32_e32 v2, 0x30000, v135
	global_load_dwordx2 v[0:1], v136, s[20:21] offset:384
	global_load_dword v3, v2, s[0:1]
	global_load_dword v4, v2, s[0:1] offset:128
	s_waitcnt vmcnt(1)
	v_sub_f32_e32 v3, v3, v0
	s_waitcnt vmcnt(0)
	v_sub_f32_e32 v0, v4, v0
	v_mul_f32_e32 v3, v1, v3
	v_mul_f32_e32 v0, v1, v0
	v_fma_f32 v3, v134, v3, v133
	v_fma_f32 v0, v32, v0, v132
	v_mul_f32_e32 v1, 0x3fd744fd, v3
	v_mul_f32_e32 v0, 0x3fd744fd, v0
	v_fmac_f32_e32 v1, v24, v131
	v_fmac_f32_e32 v0, v8, v130
	global_store_dword v2, v1, s[0:1]
	global_store_dword v2, v0, s[0:1] offset:128
	v_or_b32_e32 v2, 0x31000, v135
	global_load_dwordx2 v[0:1], v136, s[20:21] offset:392
	global_load_dword v3, v2, s[0:1]
	global_load_dword v4, v2, s[0:1] offset:128
	s_waitcnt vmcnt(1)
	v_sub_f32_e32 v3, v3, v0
	s_waitcnt vmcnt(0)
	v_sub_f32_e32 v0, v4, v0
	v_mul_f32_e32 v3, v1, v3
	v_mul_f32_e32 v0, v1, v0
	v_fma_f32 v3, v134, v3, v133
	v_fma_f32 v0, v32, v0, v132
	v_mul_f32_e32 v1, 0x3fd744fd, v3
	v_mul_f32_e32 v0, 0x3fd744fd, v0
	v_fmac_f32_e32 v1, v25, v131
	v_fmac_f32_e32 v0, v9, v130
	global_store_dword v2, v1, s[0:1]
	global_store_dword v2, v0, s[0:1] offset:128
	v_or_b32_e32 v2, 0x32000, v135
	global_load_dwordx2 v[0:1], v136, s[20:21] offset:400
	global_load_dword v3, v2, s[0:1]
	global_load_dword v4, v2, s[0:1] offset:128
	s_waitcnt vmcnt(1)
	v_sub_f32_e32 v3, v3, v0
	s_waitcnt vmcnt(0)
	v_sub_f32_e32 v0, v4, v0
	v_mul_f32_e32 v3, v1, v3
	v_mul_f32_e32 v0, v1, v0
	v_fma_f32 v3, v134, v3, v133
	v_fma_f32 v0, v32, v0, v132
	v_mul_f32_e32 v1, 0x3fd744fd, v3
	v_mul_f32_e32 v0, 0x3fd744fd, v0
	v_fmac_f32_e32 v1, v26, v131
	v_fmac_f32_e32 v0, v10, v130
	global_store_dword v2, v1, s[0:1]
	global_store_dword v2, v0, s[0:1] offset:128
	v_or_b32_e32 v2, 0x33000, v135
	global_load_dwordx2 v[0:1], v136, s[20:21] offset:408
	global_load_dword v3, v2, s[0:1]
	global_load_dword v4, v2, s[0:1] offset:128
	s_waitcnt vmcnt(1)
	v_sub_f32_e32 v3, v3, v0
	s_waitcnt vmcnt(0)
	v_sub_f32_e32 v0, v4, v0
	v_mul_f32_e32 v3, v1, v3
	v_mul_f32_e32 v0, v1, v0
	v_fma_f32 v3, v134, v3, v133
	v_fma_f32 v0, v32, v0, v132
	v_mul_f32_e32 v1, 0x3fd744fd, v3
	v_mul_f32_e32 v0, 0x3fd744fd, v0
	v_fmac_f32_e32 v1, v27, v131
	v_fmac_f32_e32 v0, v11, v130
	global_store_dword v2, v1, s[0:1]
	global_store_dword v2, v0, s[0:1] offset:128
	v_or_b32_e32 v2, 0x38000, v135
	global_load_dwordx2 v[0:1], v136, s[20:21] offset:448
	global_load_dword v3, v2, s[0:1]
	global_load_dword v4, v2, s[0:1] offset:128
	s_waitcnt vmcnt(1)
	v_sub_f32_e32 v3, v3, v0
	s_waitcnt vmcnt(0)
	v_sub_f32_e32 v0, v4, v0
	v_mul_f32_e32 v3, v1, v3
	v_mul_f32_e32 v0, v1, v0
	v_fma_f32 v3, v134, v3, v133
	v_fma_f32 v0, v32, v0, v132
	v_mul_f32_e32 v1, 0x3fd744fd, v3
	v_mul_f32_e32 v0, 0x3fd744fd, v0
	v_fmac_f32_e32 v1, v28, v131
	v_fmac_f32_e32 v0, v12, v130
	global_store_dword v2, v1, s[0:1]
	global_store_dword v2, v0, s[0:1] offset:128
	v_or_b32_e32 v2, 0x39000, v135
	global_load_dwordx2 v[0:1], v136, s[20:21] offset:456
	global_load_dword v3, v2, s[0:1]
	global_load_dword v4, v2, s[0:1] offset:128
	s_waitcnt vmcnt(1)
	v_sub_f32_e32 v3, v3, v0
	s_waitcnt vmcnt(0)
	v_sub_f32_e32 v0, v4, v0
	v_mul_f32_e32 v3, v1, v3
	v_mul_f32_e32 v0, v1, v0
	v_fma_f32 v3, v134, v3, v133
	v_fma_f32 v0, v32, v0, v132
	v_mul_f32_e32 v1, 0x3fd744fd, v3
	v_mul_f32_e32 v0, 0x3fd744fd, v0
	v_fmac_f32_e32 v1, v29, v131
	v_fmac_f32_e32 v0, v13, v130
	global_store_dword v2, v1, s[0:1]
	global_store_dword v2, v0, s[0:1] offset:128
	v_or_b32_e32 v2, 0x3a000, v135
	global_load_dwordx2 v[0:1], v136, s[20:21] offset:464
	global_load_dword v3, v2, s[0:1]
	global_load_dword v4, v2, s[0:1] offset:128
	s_waitcnt vmcnt(1)
	v_sub_f32_e32 v3, v3, v0
	s_waitcnt vmcnt(0)
	v_sub_f32_e32 v0, v4, v0
	v_mul_f32_e32 v3, v1, v3
	v_mul_f32_e32 v0, v1, v0
	v_fma_f32 v3, v134, v3, v133
	v_fma_f32 v0, v32, v0, v132
	v_mul_f32_e32 v1, 0x3fd744fd, v3
	v_mul_f32_e32 v0, 0x3fd744fd, v0
	v_fmac_f32_e32 v1, v30, v131
	v_fmac_f32_e32 v0, v14, v130
	global_store_dword v2, v1, s[0:1]
	global_store_dword v2, v0, s[0:1] offset:128
	v_or_b32_e32 v2, 0x3b000, v135
	global_load_dwordx2 v[0:1], v136, s[20:21] offset:472
	global_load_dword v3, v2, s[0:1]
	s_mov_b64 s[20:21], 0
	s_waitcnt vmcnt(0)
	v_sub_f32_e32 v3, v3, v0
	v_mul_f32_e32 v3, v1, v3
	v_fmac_f32_e32 v133, v134, v3
	global_load_dword v3, v2, s[0:1] offset:128
	s_waitcnt vmcnt(0)
	v_sub_f32_e32 v0, v3, v0
	v_mul_f32_e32 v0, v1, v0
	v_fmac_f32_e32 v132, v32, v0
	v_mul_f32_e32 v0, 0x3fd744fd, v133
	v_fmac_f32_e32 v0, v31, v131
	global_store_dword v2, v0, s[0:1]
	v_mul_f32_e32 v0, 0x3fd744fd, v132
	v_fmac_f32_e32 v0, v15, v130
	global_store_dword v2, v0, s[0:1] offset:128
	s_cbranch_vccz .LBB0_34

.LBB0_56:
	ds_read_b128 v[188:191], v160
	ds_read_b128 v[192:195], v160 offset:32
	ds_read_b128 v[196:199], v161 offset:36864
	ds_read_b128 v[200:203], v161 offset:36896
	ds_read_b128 v[204:207], v160 offset:4608
	ds_read_b128 v[208:211], v160 offset:4640
	ds_read_b128 v[212:215], v161 offset:41472
	ds_read_b128 v[216:219], v161 offset:41504
	s_add_i32 s42, s43, 2
	s_waitcnt lgkmcnt(5)
	v_mfma_f32_32x32x16_bf16 v[50:65], v[188:191], v[196:199], v[50:65]
	s_waitcnt vmcnt(15)
	ds_write_b128 v184, v[66:69] offset:18432
	s_cmp_lt_u32 s42, 13
	s_cselect_b64 s[46:47], -1, 0
	s_and_b64 s[20:21], s[46:47], exec
	s_cselect_b32 s20, 0, 0x1fffff0
	s_add_i32 s20, s20, s43
	s_lshl_b32 s45, s20, 7
	s_waitcnt lgkmcnt(2)
	v_mfma_f32_32x32x16_bf16 v[34:49], v[188:191], v[212:215], v[34:49]
	s_waitcnt vmcnt(14)
	ds_write_b128 v184, v[74:77] offset:55296
	s_add_i32 s50, s45, 0x280
	s_and_b64 s[20:21], s[46:47], exec
	s_cselect_b32 s21, s31, s38
	s_cselect_b32 s20, s40, s37
	s_and_b32 s21, s21, 0xffff
	s_and_b64 s[46:47], s[46:47], exec
	s_waitcnt lgkmcnt(5)
	v_mfma_f32_32x32x16_bf16 v[16:31], v[204:207], v[196:199], v[16:31]
	s_waitcnt vmcnt(13)
	ds_write_b128 v185, v[70:73] offset:18432
	s_cselect_b32 s46, s36, s41
	s_cselect_b32 s52, s44, s39
	s_and_b32 s53, s46, 0xffff
	s_mov_b32 s54, s22
	s_mov_b32 s55, s23
	s_add_i32 s46, s45, 0x10280
	s_waitcnt lgkmcnt(4)
	v_mfma_f32_32x32x16_bf16 v[0:15], v[204:207], v[212:215], v[0:15]
	s_waitcnt vmcnt(12)
	ds_write_b128 v185, v[82:85] offset:55296
	s_waitcnt lgkmcnt(8)
	v_mfma_f32_32x32x16_bf16 v[50:65], v[192:195], v[200:203], v[50:65]
	ds_read_b128 v[220:223], v160 offset:64
	ds_read_b128 v[142:145], v160 offset:96
	s_waitcnt vmcnt(11)
	ds_write_b128 v186, v[78:81] offset:18432
	s_waitcnt lgkmcnt(7)
	v_mfma_f32_32x32x16_bf16 v[34:49], v[192:195], v[216:219], v[34:49]
	ds_read_b128 v[154:157], v161 offset:36928
	ds_read_b128 v[138:141], v161 offset:36960
	s_waitcnt vmcnt(10)
	ds_write_b128 v186, v[90:93] offset:55296
	s_waitcnt lgkmcnt(12)
	v_mfma_f32_32x32x16_bf16 v[16:31], v[208:211], v[200:203], v[16:31]
	ds_read_b128 v[146:149], v160 offset:4672
	ds_read_b128 v[130:133], v160 offset:4704
	s_waitcnt vmcnt(9)
	ds_write_b128 v187, v[86:89] offset:18432
	s_waitcnt lgkmcnt(13)
	v_mfma_f32_32x32x16_bf16 v[0:15], v[208:211], v[216:219], v[0:15]
	ds_read_b128 v[150:153], v161 offset:41536
	ds_read_b128 v[134:137], v161 offset:41568
	s_waitcnt vmcnt(8)
	ds_write_b128 v187, v[94:97] offset:55296
	s_waitcnt lgkmcnt(8)
	v_mfma_f32_32x32x16_bf16 v[50:65], v[220:223], v[154:157], v[50:65]
	buffer_load_dwordx4 v[66:69], v32, s[20:23], s50 offen
	s_waitcnt lgkmcnt(2)
	v_mfma_f32_32x32x16_bf16 v[34:49], v[220:223], v[150:153], v[34:49]
	buffer_load_dwordx4 v[74:77], v32, s[52:55], s50 offen
	s_waitcnt lgkmcnt(5)
	v_mfma_f32_32x32x16_bf16 v[16:31], v[146:149], v[154:157], v[16:31]
	buffer_load_dwordx4 v[70:73], v32, s[20:23], s46 offen
	s_waitcnt lgkmcnt(2)
	v_mfma_f32_32x32x16_bf16 v[0:15], v[146:149], v[150:153], v[0:15]
	buffer_load_dwordx4 v[82:85], v32, s[52:55], s46 offen
	s_add_i32 s46, s45, 0x20280
	s_add_i32 s45, s45, 0x30280
	s_waitcnt lgkmcnt(7)
	v_mfma_f32_32x32x16_bf16 v[50:65], v[142:145], v[138:141], v[50:65]
	buffer_load_dwordx4 v[78:81], v32, s[20:23], s46 offen
	s_waitcnt lgkmcnt(1)
	v_mfma_f32_32x32x16_bf16 v[34:49], v[142:145], v[134:137], v[34:49]
	buffer_load_dwordx4 v[90:93], v32, s[52:55], s46 offen
	s_waitcnt lgkmcnt(4)
	v_mfma_f32_32x32x16_bf16 v[16:31], v[130:133], v[138:141], v[16:31]
	buffer_load_dwordx4 v[86:89], v32, s[20:23], s45 offen
	s_waitcnt lgkmcnt(1)
	v_mfma_f32_32x32x16_bf16 v[0:15], v[130:133], v[134:137], v[0:15]
	buffer_load_dwordx4 v[94:97], v32, s[52:55], s45 offen
	s_waitcnt lgkmcnt(0)
	s_barrier
	ds_read_b128 v[188:191], v160 offset:18432
	ds_read_b128 v[192:195], v160 offset:18464
	ds_read_b128 v[196:199], v161 offset:55296
	ds_read_b128 v[200:203], v161 offset:55328
	ds_read_b128 v[204:207], v160 offset:23040
	ds_read_b128 v[208:211], v160 offset:23072
	ds_read_b128 v[212:215], v161 offset:59904
	ds_read_b128 v[216:219], v161 offset:59936
	s_waitcnt lgkmcnt(5)
	v_mfma_f32_32x32x16_bf16 v[50:65], v[188:191], v[196:199], v[50:65]
	s_waitcnt vmcnt(15)
	ds_write_b128 v184, v[98:101]
	s_cmp_lt_u32 s42, 12
	s_cselect_b64 s[46:47], -1, 0
	s_and_b64 s[20:21], s[46:47], exec
	s_cselect_b32 s20, 0, 0x1fffff0
	s_add_i32 s20, s20, s43
	s_lshl_b32 s43, s20, 7
	s_waitcnt lgkmcnt(2)
	v_mfma_f32_32x32x16_bf16 v[34:49], v[188:191], v[212:215], v[34:49]
	s_waitcnt vmcnt(14)
	ds_write_b128 v184, v[106:109] offset:36864
	s_add_i32 s45, s43, 0x300
	s_and_b64 s[20:21], s[46:47], exec
	s_cselect_b32 s21, s31, s38
	s_cselect_b32 s20, s40, s37
	s_and_b32 s21, s21, 0xffff
	s_and_b64 s[46:47], s[46:47], exec
	s_waitcnt lgkmcnt(5)
	v_mfma_f32_32x32x16_bf16 v[16:31], v[204:207], v[196:199], v[16:31]
	s_waitcnt vmcnt(13)
	ds_write_b128 v185, v[102:105]
	s_cselect_b32 s46, s36, s41
	s_cselect_b32 s52, s44, s39
	s_and_b32 s53, s46, 0xffff
	s_waitcnt lgkmcnt(4)
	v_mfma_f32_32x32x16_bf16 v[0:15], v[204:207], v[212:215], v[0:15]
	s_waitcnt vmcnt(12)
	ds_write_b128 v185, v[114:117] offset:36864
	s_waitcnt lgkmcnt(8)
	v_mfma_f32_32x32x16_bf16 v[50:65], v[192:195], v[200:203], v[50:65]
	ds_read_b128 v[220:223], v160 offset:18496
	ds_read_b128 v[142:145], v160 offset:18528
	s_waitcnt vmcnt(11)
	ds_write_b128 v186, v[110:113]
	s_waitcnt lgkmcnt(7)
	v_mfma_f32_32x32x16_bf16 v[34:49], v[192:195], v[216:219], v[34:49]
	ds_read_b128 v[154:157], v161 offset:55360
	ds_read_b128 v[138:141], v161 offset:55392
	s_waitcnt vmcnt(10)
	ds_write_b128 v186, v[122:125] offset:36864
	s_waitcnt lgkmcnt(12)
	v_mfma_f32_32x32x16_bf16 v[16:31], v[208:211], v[200:203], v[16:31]
	ds_read_b128 v[146:149], v160 offset:23104
	ds_read_b128 v[130:133], v160 offset:23136
	s_waitcnt vmcnt(9)
	ds_write_b128 v187, v[118:121]
	s_waitcnt lgkmcnt(13)
	v_mfma_f32_32x32x16_bf16 v[0:15], v[208:211], v[216:219], v[0:15]
	ds_read_b128 v[150:153], v161 offset:59968
	ds_read_b128 v[134:137], v161 offset:60000
	s_waitcnt vmcnt(8)
	ds_write_b128 v187, v[126:129] offset:36864
	s_waitcnt lgkmcnt(8)
	v_mfma_f32_32x32x16_bf16 v[50:65], v[220:223], v[154:157], v[50:65]
	buffer_load_dwordx4 v[98:101], v32, s[20:23], s45 offen
	s_waitcnt lgkmcnt(2)
	v_mfma_f32_32x32x16_bf16 v[34:49], v[220:223], v[150:153], v[34:49]
	buffer_load_dwordx4 v[106:109], v32, s[52:55], s45 offen
	s_add_i32 s45, s43, 0x10300
	s_waitcnt lgkmcnt(5)
	v_mfma_f32_32x32x16_bf16 v[16:31], v[146:149], v[154:157], v[16:31]
	buffer_load_dwordx4 v[102:105], v32, s[20:23], s45 offen
	s_waitcnt lgkmcnt(2)
	v_mfma_f32_32x32x16_bf16 v[0:15], v[146:149], v[150:153], v[0:15]
	buffer_load_dwordx4 v[114:117], v32, s[52:55], s45 offen
	s_add_i32 s45, s43, 0x20300
	s_add_i32 s43, s43, 0x30300
	s_waitcnt lgkmcnt(7)
	v_mfma_f32_32x32x16_bf16 v[50:65], v[142:145], v[138:141], v[50:65]
	buffer_load_dwordx4 v[110:113], v32, s[20:23], s45 offen
	s_waitcnt lgkmcnt(1)
	v_mfma_f32_32x32x16_bf16 v[34:49], v[142:145], v[134:137], v[34:49]
	buffer_load_dwordx4 v[122:125], v32, s[52:55], s45 offen
	s_waitcnt lgkmcnt(4)
	v_mfma_f32_32x32x16_bf16 v[16:31], v[130:133], v[138:141], v[16:31]
	buffer_load_dwordx4 v[118:121], v32, s[20:23], s43 offen
	s_waitcnt lgkmcnt(1)
	v_mfma_f32_32x32x16_bf16 v[0:15], v[130:133], v[134:137], v[0:15]
	buffer_load_dwordx4 v[126:129], v32, s[52:55], s43 offen
	s_cmp_gt_u32 s42, 13
	s_mov_b32 s43, s42
	s_waitcnt lgkmcnt(0)
	s_barrier
	s_cbranch_scc0 .LBB0_56
	v_add_u32_e32 v32, s28, v183
	s_lshl_b32 s20, s30, 6
	v_lshlrev_b32_e32 v130, 5, v181
	v_lshl_or_b32 v32, v182, 2, v32
	v_mul_lo_u32 v32, v32, s97
	v_or3_b32 v130, v130, s20, v180
	v_add_lshl_u32 v32, v130, v32, 1
	v_mul_f32_e32 v130, 0xbfb8aa3b, v50
	v_exp_f32_e32 v130, v130
	v_readlane_b32 s20, v235, 34
	v_readlane_b32 s21, v235, 35
	v_readlane_b32 s52, v233, 61
	v_add_f32_e32 v130, 1.0, v130
	v_rcp_f32_e32 v130, v130
	v_readlane_b32 s62, v232, 7
	v_readlane_b32 s63, v232, 8
	s_and_b64 vcc, exec, s[0:1]
	v_mul_f32_e32 v50, v50, v130
	v_mul_f32_e32 v34, v34, v50
	v_mul_f32_e32 v50, 0xbfb8aa3b, v51
	v_exp_f32_e32 v50, v50
	v_cvt_pk_bf16_f32 v34, v34, s0
	global_store_short v32, v34, s[20:21]
	v_add_u32_e32 v34, 0x1600, v32
	v_add_f32_e32 v50, 1.0, v50
	v_rcp_f32_e32 v50, v50
	s_mov_b32 s37, s29
	v_readlane_b32 s53, v233, 62
	v_readlane_b32 s56, v232, 1
	v_mul_f32_e32 v50, v51, v50
	v_mul_f32_e32 v35, v35, v50
	v_cvt_pk_bf16_f32 v35, v35, s0
	global_store_short v34, v35, s[20:21]
	v_mul_f32_e32 v35, 0xbfb8aa3b, v52
	v_exp_f32_e32 v35, v35
	v_add_u32_e32 v34, 0x2c00, v32
	v_readlane_b32 s57, v232, 2
	v_readlane_b32 s58, v232, 3
	v_add_f32_e32 v35, 1.0, v35
	v_rcp_f32_e32 v35, v35
	v_readlane_b32 s59, v232, 4
	v_readlane_b32 s60, v232, 5
	v_readlane_b32 s61, v232, 6
	v_mul_f32_e32 v35, v52, v35
	v_mul_f32_e32 v35, v36, v35
	v_cvt_pk_bf16_f32 v35, v35, s0
	global_store_short v34, v35, s[20:21]
	v_mul_f32_e32 v35, 0xbfb8aa3b, v53
	v_exp_f32_e32 v35, v35
	v_add_u32_e32 v34, 0x4200, v32
	v_readlane_b32 s64, v232, 9
	v_readlane_b32 s65, v232, 10
	v_add_f32_e32 v35, 1.0, v35
	v_rcp_f32_e32 v35, v35
	v_readlane_b32 s66, v232, 11
	v_readlane_b32 s67, v232, 12
	v_readlane_b32 s63, v235, 21
	v_mul_f32_e32 v35, v53, v35
	v_mul_f32_e32 v35, v37, v35
	v_cvt_pk_bf16_f32 v35, v35, s0
	global_store_short v34, v35, s[20:21]
	v_mul_f32_e32 v35, 0xbfb8aa3b, v54
	v_exp_f32_e32 v35, v35
	v_add_u32_e32 v34, 0xb000, v32
	v_readlane_b32 s62, v232, 31
	v_readlane_b32 s54, v233, 63
	v_add_f32_e32 v35, 1.0, v35
	v_rcp_f32_e32 v35, v35
	v_readlane_b32 s55, v232, 0
	v_mul_f32_e32 v35, v54, v35
	v_mul_f32_e32 v35, v38, v35
	v_cvt_pk_bf16_f32 v35, v35, s0
	global_store_short v34, v35, s[20:21]
	v_mul_f32_e32 v35, 0xbfb8aa3b, v55
	v_exp_f32_e32 v35, v35
	v_add_u32_e32 v34, 0xc600, v32
	v_add_f32_e32 v35, 1.0, v35
	v_rcp_f32_e32 v35, v35
	s_nop 0
	v_mul_f32_e32 v35, v55, v35
	v_mul_f32_e32 v35, v39, v35
	v_cvt_pk_bf16_f32 v35, v35, s0
	global_store_short v34, v35, s[20:21]
	v_mul_f32_e32 v35, 0xbfb8aa3b, v56
	v_exp_f32_e32 v35, v35
	v_add_u32_e32 v34, 0xdc00, v32
	v_add_f32_e32 v35, 1.0, v35
	v_rcp_f32_e32 v35, v35
	s_nop 0
	v_mul_f32_e32 v35, v56, v35
	v_mul_f32_e32 v35, v40, v35
	v_cvt_pk_bf16_f32 v35, v35, s0
	global_store_short v34, v35, s[20:21]
	v_mul_f32_e32 v35, 0xbfb8aa3b, v57
	v_exp_f32_e32 v35, v35
	v_add_u32_e32 v34, 0xf200, v32
	v_add_f32_e32 v35, 1.0, v35
	v_rcp_f32_e32 v35, v35
	s_nop 0
	v_mul_f32_e32 v35, v57, v35
	v_mul_f32_e32 v35, v41, v35
	v_cvt_pk_bf16_f32 v35, v35, s0
	global_store_short v34, v35, s[20:21]
	v_mul_f32_e32 v35, 0xbfb8aa3b, v58
	v_exp_f32_e32 v35, v35
	v_add_u32_e32 v34, 0x16000, v32
	v_add_f32_e32 v35, 1.0, v35
	v_rcp_f32_e32 v35, v35
	s_nop 0
	v_mul_f32_e32 v35, v58, v35
	v_mul_f32_e32 v35, v42, v35
	v_cvt_pk_bf16_f32 v35, v35, s0
	global_store_short v34, v35, s[20:21]
	v_mul_f32_e32 v35, 0xbfb8aa3b, v59
	v_exp_f32_e32 v35, v35
	v_add_u32_e32 v34, 0x17600, v32
	v_add_f32_e32 v35, 1.0, v35
	v_rcp_f32_e32 v35, v35
	s_nop 0
	v_mul_f32_e32 v35, v59, v35
	v_mul_f32_e32 v35, v43, v35
	v_cvt_pk_bf16_f32 v35, v35, s0
	global_store_short v34, v35, s[20:21]
	v_mul_f32_e32 v35, 0xbfb8aa3b, v60
	v_exp_f32_e32 v35, v35
	v_add_u32_e32 v34, 0x18c00, v32
	v_add_f32_e32 v35, 1.0, v35
	v_rcp_f32_e32 v35, v35
	s_nop 0
	v_mul_f32_e32 v35, v60, v35
	v_mul_f32_e32 v35, v44, v35
	v_cvt_pk_bf16_f32 v35, v35, s0
	global_store_short v34, v35, s[20:21]
	v_mul_f32_e32 v35, 0xbfb8aa3b, v61
	v_exp_f32_e32 v35, v35
	v_add_u32_e32 v34, 0x1a200, v32
	v_add_f32_e32 v35, 1.0, v35
	v_rcp_f32_e32 v35, v35
	s_nop 0
	v_mul_f32_e32 v35, v61, v35
	v_mul_f32_e32 v35, v45, v35
	v_cvt_pk_bf16_f32 v35, v35, s0
	global_store_short v34, v35, s[20:21]
	v_mul_f32_e32 v35, 0xbfb8aa3b, v62
	v_exp_f32_e32 v35, v35
	v_add_u32_e32 v34, 0x21000, v32
	v_add_f32_e32 v35, 1.0, v35
	v_rcp_f32_e32 v35, v35
	s_nop 0
	v_mul_f32_e32 v35, v62, v35
	v_mul_f32_e32 v35, v46, v35
	v_cvt_pk_bf16_f32 v35, v35, s0
	global_store_short v34, v35, s[20:21]
	v_mul_f32_e32 v35, 0xbfb8aa3b, v63
	v_exp_f32_e32 v35, v35
	v_add_u32_e32 v34, 0x22600, v32
	v_add_f32_e32 v35, 1.0, v35
	v_rcp_f32_e32 v35, v35
	s_nop 0
	v_mul_f32_e32 v35, v63, v35
	v_mul_f32_e32 v35, v47, v35
	v_cvt_pk_bf16_f32 v35, v35, s0
	global_store_short v34, v35, s[20:21]
	v_mul_f32_e32 v35, 0xbfb8aa3b, v64
	v_exp_f32_e32 v35, v35
	v_add_u32_e32 v34, 0x23c00, v32
	v_add_f32_e32 v35, 1.0, v35
	v_rcp_f32_e32 v35, v35
	s_nop 0
	v_mul_f32_e32 v35, v64, v35
	v_mul_f32_e32 v35, v48, v35
	v_cvt_pk_bf16_f32 v35, v35, s0
	global_store_short v34, v35, s[20:21]
	v_mul_f32_e32 v35, 0xbfb8aa3b, v65
	v_exp_f32_e32 v35, v35
	v_add_u32_e32 v34, 0x25200, v32
	v_add_f32_e32 v35, 1.0, v35
	v_rcp_f32_e32 v35, v35
	s_nop 0
	v_mul_f32_e32 v35, v65, v35
	v_mul_f32_e32 v35, v49, v35
	v_cvt_pk_bf16_f32 v35, v35, s0
	global_store_short v34, v35, s[20:21]
	v_mul_f32_e32 v35, 0xbfb8aa3b, v16
	v_exp_f32_e32 v35, v35
	v_add_u32_e32 v34, 0x2c000, v32
	v_add_f32_e32 v35, 1.0, v35
	v_rcp_f32_e32 v35, v35
	s_nop 0
	v_mul_f32_e32 v16, v16, v35
	v_mul_f32_e32 v0, v0, v16
	v_mul_f32_e32 v16, 0xbfb8aa3b, v17
	v_exp_f32_e32 v16, v16
	v_cvt_pk_bf16_f32 v0, v0, s0
	global_store_short v34, v0, s[20:21]
	v_add_u32_e32 v0, 0x2d600, v32
	v_add_f32_e32 v16, 1.0, v16
	v_rcp_f32_e32 v16, v16
	s_nop 0
	v_mul_f32_e32 v16, v17, v16
	v_mul_f32_e32 v1, v1, v16
	v_cvt_pk_bf16_f32 v1, v1, s0
	global_store_short v0, v1, s[20:21]
	v_mul_f32_e32 v1, 0xbfb8aa3b, v18
	v_exp_f32_e32 v1, v1
	v_add_u32_e32 v0, 0x2ec00, v32
	v_add_f32_e32 v1, 1.0, v1
	v_rcp_f32_e32 v1, v1
	s_nop 0
	v_mul_f32_e32 v1, v18, v1
	v_mul_f32_e32 v1, v2, v1
	v_cvt_pk_bf16_f32 v1, v1, s0
	global_store_short v0, v1, s[20:21]
	v_mul_f32_e32 v1, 0xbfb8aa3b, v19
	v_exp_f32_e32 v1, v1
	v_add_u32_e32 v0, 0x30200, v32
	v_add_f32_e32 v1, 1.0, v1
	v_rcp_f32_e32 v1, v1
	s_nop 0
	v_mul_f32_e32 v1, v19, v1
	v_mul_f32_e32 v1, v3, v1
	v_cvt_pk_bf16_f32 v1, v1, s0
	global_store_short v0, v1, s[20:21]
	v_mul_f32_e32 v1, 0xbfb8aa3b, v20
	v_exp_f32_e32 v1, v1
	v_add_u32_e32 v0, 0x37000, v32
	v_add_f32_e32 v1, 1.0, v1
	v_rcp_f32_e32 v1, v1
	s_nop 0
	v_mul_f32_e32 v1, v20, v1
	v_mul_f32_e32 v1, v4, v1
	v_cvt_pk_bf16_f32 v1, v1, s0
	global_store_short v0, v1, s[20:21]
	v_mul_f32_e32 v1, 0xbfb8aa3b, v21
	v_exp_f32_e32 v1, v1
	v_add_u32_e32 v0, 0x38600, v32
	v_add_f32_e32 v1, 1.0, v1
	v_rcp_f32_e32 v1, v1
	s_nop 0
	v_mul_f32_e32 v1, v21, v1
	v_mul_f32_e32 v1, v5, v1
	v_cvt_pk_bf16_f32 v1, v1, s0
	global_store_short v0, v1, s[20:21]
	v_mul_f32_e32 v1, 0xbfb8aa3b, v22
	v_exp_f32_e32 v1, v1
	v_add_u32_e32 v0, 0x39c00, v32
	v_add_f32_e32 v1, 1.0, v1
	v_rcp_f32_e32 v1, v1
	s_nop 0
	v_mul_f32_e32 v1, v22, v1
	v_mul_f32_e32 v1, v6, v1
	v_cvt_pk_bf16_f32 v1, v1, s0
	global_store_short v0, v1, s[20:21]
	v_mul_f32_e32 v1, 0xbfb8aa3b, v23
	v_exp_f32_e32 v1, v1
	v_add_u32_e32 v0, 0x3b200, v32
	v_add_f32_e32 v1, 1.0, v1
	v_rcp_f32_e32 v1, v1
	s_nop 0
	v_mul_f32_e32 v1, v23, v1
	v_mul_f32_e32 v1, v7, v1
	v_cvt_pk_bf16_f32 v1, v1, s0
	global_store_short v0, v1, s[20:21]
	v_mul_f32_e32 v1, 0xbfb8aa3b, v24
	v_exp_f32_e32 v1, v1
	v_add_u32_e32 v0, 0x42000, v32
	v_add_f32_e32 v1, 1.0, v1
	v_rcp_f32_e32 v1, v1
	s_nop 0
	v_mul_f32_e32 v1, v24, v1
	v_mul_f32_e32 v1, v8, v1
	v_cvt_pk_bf16_f32 v1, v1, s0
	global_store_short v0, v1, s[20:21]
	v_mul_f32_e32 v1, 0xbfb8aa3b, v25
	v_exp_f32_e32 v1, v1
	v_add_u32_e32 v0, 0x43600, v32
	v_add_f32_e32 v1, 1.0, v1
	v_rcp_f32_e32 v1, v1
	s_nop 0
	v_mul_f32_e32 v1, v25, v1
	v_mul_f32_e32 v1, v9, v1
	v_cvt_pk_bf16_f32 v1, v1, s0
	global_store_short v0, v1, s[20:21]
	v_mul_f32_e32 v1, 0xbfb8aa3b, v26
	v_exp_f32_e32 v1, v1
	v_add_u32_e32 v0, 0x44c00, v32
	v_add_f32_e32 v1, 1.0, v1
	v_rcp_f32_e32 v1, v1
	s_nop 0
	v_mul_f32_e32 v1, v26, v1
	v_mul_f32_e32 v1, v10, v1
	v_cvt_pk_bf16_f32 v1, v1, s0
	global_store_short v0, v1, s[20:21]
	v_mul_f32_e32 v1, 0xbfb8aa3b, v27
	v_exp_f32_e32 v1, v1
	v_add_u32_e32 v0, 0x46200, v32
	v_add_f32_e32 v1, 1.0, v1
	v_rcp_f32_e32 v1, v1
	s_nop 0
	v_mul_f32_e32 v1, v27, v1
	v_mul_f32_e32 v1, v11, v1
	v_cvt_pk_bf16_f32 v1, v1, s0
	global_store_short v0, v1, s[20:21]
	v_mul_f32_e32 v1, 0xbfb8aa3b, v28
	v_exp_f32_e32 v1, v1
	v_add_u32_e32 v0, 0x4d000, v32
	v_add_f32_e32 v1, 1.0, v1
	v_rcp_f32_e32 v1, v1
	s_nop 0
	v_mul_f32_e32 v1, v28, v1
	v_mul_f32_e32 v1, v12, v1
	v_cvt_pk_bf16_f32 v1, v1, s0
	global_store_short v0, v1, s[20:21]
	v_mul_f32_e32 v1, 0xbfb8aa3b, v29
	v_exp_f32_e32 v1, v1
	v_add_u32_e32 v0, 0x4e600, v32
	v_add_f32_e32 v1, 1.0, v1
	v_rcp_f32_e32 v1, v1
	s_nop 0
	v_mul_f32_e32 v1, v29, v1
	v_mul_f32_e32 v1, v13, v1
	v_cvt_pk_bf16_f32 v1, v1, s0
	global_store_short v0, v1, s[20:21]
	v_mul_f32_e32 v1, 0xbfb8aa3b, v30
	v_exp_f32_e32 v1, v1
	v_add_u32_e32 v0, 0x4fc00, v32
	v_add_f32_e32 v1, 1.0, v1
	v_rcp_f32_e32 v1, v1
	s_nop 0
	v_mul_f32_e32 v1, v30, v1
	v_mul_f32_e32 v1, v14, v1
	v_cvt_pk_bf16_f32 v1, v1, s0
	global_store_short v0, v1, s[20:21]
	v_mul_f32_e32 v1, 0xbfb8aa3b, v31
	v_exp_f32_e32 v1, v1
	v_add_u32_e32 v0, 0x51200, v32
	v_add_f32_e32 v1, 1.0, v1
	v_rcp_f32_e32 v1, v1
	s_nop 0
	v_mul_f32_e32 v1, v31, v1
	v_mul_f32_e32 v1, v15, v1
	v_cvt_pk_bf16_f32 v1, v1, s0
	global_store_short v0, v1, s[20:21]
	s_mov_b64 s[20:21], 0
	s_cbranch_vccz .LBB0_51

.LBB0_77:
	ds_read_b128 v[188:191], v160
	ds_read_b128 v[192:195], v160 offset:32
	ds_read_b128 v[196:199], v161 offset:36864
	ds_read_b128 v[200:203], v161 offset:36896
	ds_read_b128 v[204:207], v160 offset:4608
	ds_read_b128 v[208:211], v160 offset:4640
	ds_read_b128 v[212:215], v161 offset:41472
	ds_read_b128 v[216:219], v161 offset:41504
	s_add_i32 s37, s38, 2
	s_waitcnt lgkmcnt(5)
	v_mfma_f32_32x32x16_bf16 v[50:65], v[188:191], v[196:199], v[50:65]
	s_waitcnt vmcnt(15)
	ds_write_b128 v184, v[66:69] offset:18432
	s_cmp_lt_u32 s37, 13
	s_cselect_b64 s[46:47], -1, 0
	s_and_b64 s[20:21], s[46:47], exec
	s_cselect_b32 s20, 0, 0x1fffff0
	s_add_i32 s20, s20, s38
	s_lshl_b32 s39, s20, 7
	s_waitcnt lgkmcnt(2)
	v_mfma_f32_32x32x16_bf16 v[34:49], v[188:191], v[212:215], v[34:49]
	s_waitcnt vmcnt(14)
	ds_write_b128 v184, v[74:77] offset:55296
	s_add_i32 s45, s39, 0x280
	s_and_b64 s[20:21], s[46:47], exec
	s_cselect_b32 s21, s27, s1
	s_cselect_b32 s20, s40, s0
	s_and_b32 s21, s21, 0xffff
	s_and_b64 s[46:47], s[46:47], exec
	s_waitcnt lgkmcnt(5)
	v_mfma_f32_32x32x16_bf16 v[16:31], v[204:207], v[196:199], v[16:31]
	s_waitcnt vmcnt(13)
	ds_write_b128 v185, v[70:73] offset:18432
	s_cselect_b32 s46, s30, s36
	s_cselect_b32 s60, s44, s31
	s_and_b32 s61, s46, 0xffff
	s_mov_b32 s62, s22
	s_mov_b32 s63, s23
	s_waitcnt lgkmcnt(4)
	v_mfma_f32_32x32x16_bf16 v[0:15], v[204:207], v[212:215], v[0:15]
	s_waitcnt vmcnt(12)
	ds_write_b128 v185, v[82:85] offset:55296
	s_waitcnt lgkmcnt(8)
	v_mfma_f32_32x32x16_bf16 v[50:65], v[192:195], v[200:203], v[50:65]
	ds_read_b128 v[220:223], v160 offset:64
	ds_read_b128 v[142:145], v160 offset:96
	s_waitcnt vmcnt(11)
	ds_write_b128 v186, v[78:81] offset:18432
	s_waitcnt lgkmcnt(7)
	v_mfma_f32_32x32x16_bf16 v[34:49], v[192:195], v[216:219], v[34:49]
	ds_read_b128 v[154:157], v161 offset:36928
	ds_read_b128 v[138:141], v161 offset:36960
	s_waitcnt vmcnt(10)
	ds_write_b128 v186, v[90:93] offset:55296
	s_waitcnt lgkmcnt(12)
	v_mfma_f32_32x32x16_bf16 v[16:31], v[208:211], v[200:203], v[16:31]
	ds_read_b128 v[146:149], v160 offset:4672
	ds_read_b128 v[130:133], v160 offset:4704
	s_waitcnt vmcnt(9)
	ds_write_b128 v187, v[86:89] offset:18432
	s_waitcnt lgkmcnt(13)
	v_mfma_f32_32x32x16_bf16 v[0:15], v[208:211], v[216:219], v[0:15]
	ds_read_b128 v[150:153], v161 offset:41536
	ds_read_b128 v[134:137], v161 offset:41568
	s_waitcnt vmcnt(8)
	ds_write_b128 v187, v[94:97] offset:55296
	s_waitcnt lgkmcnt(8)
	v_mfma_f32_32x32x16_bf16 v[50:65], v[220:223], v[154:157], v[50:65]
	buffer_load_dwordx4 v[66:69], v180, s[20:23], s45 offen
	s_waitcnt lgkmcnt(2)
	v_mfma_f32_32x32x16_bf16 v[34:49], v[220:223], v[150:153], v[34:49]
	buffer_load_dwordx4 v[74:77], v180, s[60:63], s45 offen
	s_add_i32 s45, s39, 0x10280
	s_waitcnt lgkmcnt(5)
	v_mfma_f32_32x32x16_bf16 v[16:31], v[146:149], v[154:157], v[16:31]
	buffer_load_dwordx4 v[70:73], v180, s[20:23], s45 offen
	s_waitcnt lgkmcnt(2)
	v_mfma_f32_32x32x16_bf16 v[0:15], v[146:149], v[150:153], v[0:15]
	buffer_load_dwordx4 v[82:85], v180, s[60:63], s45 offen
	s_add_i32 s45, s39, 0x20280
	s_add_i32 s39, s39, 0x30280
	s_waitcnt lgkmcnt(7)
	v_mfma_f32_32x32x16_bf16 v[50:65], v[142:145], v[138:141], v[50:65]
	buffer_load_dwordx4 v[78:81], v180, s[20:23], s45 offen
	s_waitcnt lgkmcnt(1)
	v_mfma_f32_32x32x16_bf16 v[34:49], v[142:145], v[134:137], v[34:49]
	buffer_load_dwordx4 v[90:93], v180, s[60:63], s45 offen
	s_waitcnt lgkmcnt(4)
	v_mfma_f32_32x32x16_bf16 v[16:31], v[130:133], v[138:141], v[16:31]
	buffer_load_dwordx4 v[86:89], v180, s[20:23], s39 offen
	s_waitcnt lgkmcnt(1)
	v_mfma_f32_32x32x16_bf16 v[0:15], v[130:133], v[134:137], v[0:15]
	buffer_load_dwordx4 v[94:97], v180, s[60:63], s39 offen
	s_waitcnt lgkmcnt(0)
	s_barrier
	ds_read_b128 v[188:191], v160 offset:18432
	ds_read_b128 v[192:195], v160 offset:18464
	ds_read_b128 v[196:199], v161 offset:55296
	ds_read_b128 v[200:203], v161 offset:55328
	ds_read_b128 v[204:207], v160 offset:23040
	ds_read_b128 v[208:211], v160 offset:23072
	ds_read_b128 v[212:215], v161 offset:59904
	ds_read_b128 v[216:219], v161 offset:59936
	s_waitcnt lgkmcnt(5)
	v_mfma_f32_32x32x16_bf16 v[50:65], v[188:191], v[196:199], v[50:65]
	s_waitcnt vmcnt(15)
	ds_write_b128 v184, v[98:101]
	s_cmp_lt_u32 s37, 12
	s_cselect_b64 s[46:47], -1, 0
	s_and_b64 s[20:21], s[46:47], exec
	s_cselect_b32 s20, 0, 0x1fffff0
	s_add_i32 s20, s20, s38
	s_lshl_b32 s45, s20, 7
	s_waitcnt lgkmcnt(2)
	v_mfma_f32_32x32x16_bf16 v[34:49], v[188:191], v[212:215], v[34:49]
	s_waitcnt vmcnt(14)
	ds_write_b128 v184, v[106:109] offset:36864
	s_add_i32 s57, s45, 0x300
	s_and_b64 s[20:21], s[46:47], exec
	s_cselect_b32 s21, s27, s1
	s_cselect_b32 s20, s40, s0
	s_and_b32 s21, s21, 0xffff
	s_and_b64 s[38:39], s[46:47], exec
	s_waitcnt lgkmcnt(5)
	v_mfma_f32_32x32x16_bf16 v[16:31], v[204:207], v[196:199], v[16:31]
	s_waitcnt vmcnt(13)
	ds_write_b128 v185, v[102:105]
	s_cselect_b32 s38, s30, s36
	s_cselect_b32 s60, s44, s31
	s_and_b32 s61, s38, 0xffff
	s_add_i32 s38, s45, 0x10300
	s_waitcnt lgkmcnt(4)
	v_mfma_f32_32x32x16_bf16 v[0:15], v[204:207], v[212:215], v[0:15]
	s_waitcnt vmcnt(12)
	ds_write_b128 v185, v[114:117] offset:36864
	s_waitcnt lgkmcnt(8)
	v_mfma_f32_32x32x16_bf16 v[50:65], v[192:195], v[200:203], v[50:65]
	ds_read_b128 v[220:223], v160 offset:18496
	ds_read_b128 v[142:145], v160 offset:18528
	s_waitcnt vmcnt(11)
	ds_write_b128 v186, v[110:113]
	s_waitcnt lgkmcnt(7)
	v_mfma_f32_32x32x16_bf16 v[34:49], v[192:195], v[216:219], v[34:49]
	ds_read_b128 v[154:157], v161 offset:55360
	ds_read_b128 v[138:141], v161 offset:55392
	s_waitcnt vmcnt(10)
	ds_write_b128 v186, v[122:125] offset:36864
	s_waitcnt lgkmcnt(12)
	v_mfma_f32_32x32x16_bf16 v[16:31], v[208:211], v[200:203], v[16:31]
	ds_read_b128 v[146:149], v160 offset:23104
	ds_read_b128 v[130:133], v160 offset:23136
	s_waitcnt vmcnt(9)
	ds_write_b128 v187, v[118:121]
	s_waitcnt lgkmcnt(13)
	v_mfma_f32_32x32x16_bf16 v[0:15], v[208:211], v[216:219], v[0:15]
	ds_read_b128 v[150:153], v161 offset:59968
	ds_read_b128 v[134:137], v161 offset:60000
	s_waitcnt vmcnt(8)
	ds_write_b128 v187, v[126:129] offset:36864
	s_waitcnt lgkmcnt(8)
	v_mfma_f32_32x32x16_bf16 v[50:65], v[220:223], v[154:157], v[50:65]
	buffer_load_dwordx4 v[98:101], v180, s[20:23], s57 offen
	s_waitcnt lgkmcnt(2)
	v_mfma_f32_32x32x16_bf16 v[34:49], v[220:223], v[150:153], v[34:49]
	buffer_load_dwordx4 v[106:109], v180, s[60:63], s57 offen
	s_waitcnt lgkmcnt(5)
	v_mfma_f32_32x32x16_bf16 v[16:31], v[146:149], v[154:157], v[16:31]
	buffer_load_dwordx4 v[102:105], v180, s[20:23], s38 offen
	s_waitcnt lgkmcnt(2)
	v_mfma_f32_32x32x16_bf16 v[0:15], v[146:149], v[150:153], v[0:15]
	buffer_load_dwordx4 v[114:117], v180, s[60:63], s38 offen
	s_add_i32 s38, s45, 0x20300
	s_add_i32 s45, s45, 0x30300
	s_waitcnt lgkmcnt(7)
	v_mfma_f32_32x32x16_bf16 v[50:65], v[142:145], v[138:141], v[50:65]
	buffer_load_dwordx4 v[110:113], v180, s[20:23], s38 offen
	s_waitcnt lgkmcnt(1)
	v_mfma_f32_32x32x16_bf16 v[34:49], v[142:145], v[134:137], v[34:49]
	buffer_load_dwordx4 v[122:125], v180, s[60:63], s38 offen
	s_waitcnt lgkmcnt(4)
	v_mfma_f32_32x32x16_bf16 v[16:31], v[130:133], v[138:141], v[16:31]
	buffer_load_dwordx4 v[118:121], v180, s[20:23], s45 offen
	s_waitcnt lgkmcnt(1)
	v_mfma_f32_32x32x16_bf16 v[0:15], v[130:133], v[134:137], v[0:15]
	buffer_load_dwordx4 v[126:129], v180, s[60:63], s45 offen
	s_cmp_gt_u32 s37, 13
	s_mov_b32 s38, s37
	s_waitcnt lgkmcnt(0)
	s_barrier
	s_cbranch_scc0 .LBB0_77
	s_and_b64 vcc, exec, s[50:51]
	s_cbranch_vccz .LBB0_147
	s_lshl_b64 s[20:21], s[28:29], 12
	s_add_u32 s0, s92, s20
	s_addc_u32 s1, s93, s21
	s_cbranch_execnz .LBB0_81

.LBB0_177:
	s_bitcmp1_b32 s47, 0
	s_cselect_b32 s52, 0x4800, 0
	s_add_i32 s46, s47, 1
	s_cmp_lt_u32 s46, s44
	s_cselect_b32 s47, s46, s47
	s_cmp_lt_u32 s47, s25
	s_cselect_b64 s[48:49], -1, 0
	s_and_b64 s[50:51], s[48:49], exec
	s_cselect_b32 s51, s41, s43
	s_cselect_b32 s50, s40, s42
	s_sub_i32 s53, s47, s25
	s_min_u32 s47, s47, s53
	s_lshl_b32 s47, s47, 6
	s_and_b64 s[48:49], s[48:49], exec
	v_or_b32_e32 v34, s52, v32
	v_add_u32_e32 v38, s47, v98
	v_add_u32_e32 v40, s47, v100
	s_cselect_b32 s48, 0, 0x400
	v_lshl_add_u32 v36, v109, 1, v34
	v_ashrrev_i32_e32 v39, 31, v38
	v_ashrrev_i32_e32 v41, 31, v40
	s_add_i32 s48, s47, s48
	v_lshl_add_u32 v34, v112, 1, v34
	s_waitcnt vmcnt(0)
	ds_write_b128 v36, v[90:93]
	ds_write_b128 v36, v[94:97] offset:9216
	ds_write_b128 v34, v[86:89]
	ds_write_b128 v34, v[82:85] offset:9216
	v_lshl_add_u64 v[36:37], s[50:51], 0, v[32:33]
	v_lshlrev_b64 v[38:39], 9, v[38:39]
	v_lshlrev_b64 v[40:41], 9, v[40:41]
	s_ashr_i32 s49, s48, 31
	v_lshl_add_u64 v[38:39], v[36:37], 0, v[38:39]
	v_lshl_add_u64 v[36:37], v[36:37], 0, v[40:41]
	v_lshl_add_u64 v[40:41], s[48:49], 1, v[102:103]
	s_waitcnt lgkmcnt(0)
	s_barrier
	global_load_dwordx4 v[90:93], v[38:39], off
	global_load_dwordx4 v[86:89], v[36:37], off
	v_lshl_add_u64 v[36:37], v[106:107], 1, v[40:41]
	v_lshl_add_u64 v[38:39], v[104:105], 1, v[40:41]
	global_load_dwordx4 v[94:97], v[36:37], off
	global_load_dwordx4 v[82:85], v[38:39], off
	v_mov_b32_e32 v115, v35
	s_setprio 1
	v_lshlrev_b32_e32 v34, 1, v99
	v_add3_u32 v126, s52, v101, v34
	ds_read_b128 v[34:37], v126
	ds_read_b128 v[116:119], v126 offset:32
	ds_read_b128 v[50:53], v126 offset:4608
	s_waitcnt lgkmcnt(2)
	v_mfma_f32_32x32x16_bf16 v[34:49], v[34:37], v[66:69], 0
	s_waitcnt lgkmcnt(1)
	v_mfma_f32_32x32x16_bf16 v[34:49], v[116:119], v[70:73], v[34:49]
	ds_read_b128 v[116:119], v126 offset:4640
	s_waitcnt lgkmcnt(1)
	v_mfma_f32_32x32x16_bf16 v[50:65], v[50:53], v[66:69], 0
	s_waitcnt lgkmcnt(0)
	v_mfma_f32_32x32x16_bf16 v[50:65], v[116:119], v[70:73], v[50:65]
	ds_read_b128 v[116:119], v126 offset:64
	s_waitcnt lgkmcnt(0)
	v_mfma_f32_32x32x16_bf16 v[34:49], v[116:119], v[74:77], v[34:49]
	ds_read_b128 v[116:119], v126 offset:4672
	s_waitcnt lgkmcnt(0)
	v_mfma_f32_32x32x16_bf16 v[50:65], v[116:119], v[74:77], v[50:65]
	ds_read_b128 v[116:119], v126 offset:96
	s_waitcnt lgkmcnt(0)
	v_mfma_f32_32x32x16_bf16 v[34:49], v[116:119], v[78:81], v[34:49]
	ds_read_b128 v[116:119], v126 offset:4704
	s_waitcnt lgkmcnt(0)
	v_mfma_f32_32x32x16_bf16 v[50:65], v[116:119], v[78:81], v[50:65]
	s_setprio 0
	s_nop 7
	v_mul_f32_e32 v116, 0x3e38aa3b, v34
	s_nop 1
	v_mul_f32_e32 v117, 0x3e38aa3b, v50
	v_max_f32_e32 v116, v116, v117
	v_mul_f32_e32 v117, 0x3e38aa3b, v35
	v_mul_f32_e32 v118, 0x3e38aa3b, v51
	v_max_f32_e32 v117, v117, v118
	v_max3_f32 v116, v116, s54, v117
	v_mul_f32_e32 v117, 0x3e38aa3b, v36
	v_mul_f32_e32 v118, 0x3e38aa3b, v52
	v_max_f32_e32 v117, v117, v118
	v_mul_f32_e32 v118, 0x3e38aa3b, v37
	v_mul_f32_e32 v119, 0x3e38aa3b, v53
	v_max_f32_e32 v118, v118, v119
	v_max3_f32 v116, v116, v117, v118
	v_mul_f32_e32 v117, 0x3e38aa3b, v38
	v_mul_f32_e32 v118, 0x3e38aa3b, v54
	v_max_f32_e32 v117, v117, v118
	v_mul_f32_e32 v118, 0x3e38aa3b, v39
	v_mul_f32_e32 v119, 0x3e38aa3b, v55
	v_max_f32_e32 v118, v118, v119
	v_max3_f32 v116, v116, v117, v118
	v_mul_f32_e32 v117, 0x3e38aa3b, v40
	v_mul_f32_e32 v118, 0x3e38aa3b, v56
	v_max_f32_e32 v117, v117, v118
	v_mul_f32_e32 v118, 0x3e38aa3b, v41
	v_mul_f32_e32 v119, 0x3e38aa3b, v57
	v_max_f32_e32 v118, v118, v119
	v_max3_f32 v116, v116, v117, v118
	v_mul_f32_e32 v117, 0x3e38aa3b, v42
	v_mul_f32_e32 v118, 0x3e38aa3b, v58
	v_max_f32_e32 v117, v117, v118
	v_mul_f32_e32 v118, 0x3e38aa3b, v43
	v_mul_f32_e32 v119, 0x3e38aa3b, v59
	v_max_f32_e32 v118, v118, v119
	v_max3_f32 v116, v116, v117, v118
	v_mul_f32_e32 v117, 0x3e38aa3b, v44
	v_mul_f32_e32 v118, 0x3e38aa3b, v60
	v_max_f32_e32 v117, v117, v118
	v_mul_f32_e32 v118, 0x3e38aa3b, v45
	v_mul_f32_e32 v119, 0x3e38aa3b, v61
	v_max_f32_e32 v118, v118, v119
	v_max3_f32 v116, v116, v117, v118
	v_mul_f32_e32 v117, 0x3e38aa3b, v46
	v_mul_f32_e32 v118, 0x3e38aa3b, v62
	v_max_f32_e32 v117, v117, v118
	v_mul_f32_e32 v118, 0x3e38aa3b, v47
	v_mul_f32_e32 v119, 0x3e38aa3b, v63
	v_max_f32_e32 v118, v118, v119
	v_max3_f32 v116, v116, v117, v118
	v_mul_f32_e32 v117, 0x3e38aa3b, v48
	v_mul_f32_e32 v118, 0x3e38aa3b, v64
	v_max_f32_e32 v117, v117, v118
	v_mul_f32_e32 v118, 0x3e38aa3b, v49
	v_mul_f32_e32 v119, 0x3e38aa3b, v65
	v_max_f32_e32 v118, v118, v119
	v_max3_f32 v116, v116, v117, v118
	v_mov_b32_e32 v117, v116
	s_nop 1
	v_permlane32_swap_b32_e32 v116, v117
	v_max_f32_e32 v117, v117, v117
	v_max_f32_e32 v116, v116, v116
	v_max_f32_e32 v116, v116, v117
	v_add_f32_e32 v117, 0x41000000, v114
	v_cmp_gt_f32_e32 vcc, v116, v117
	s_nop 1
	v_cndmask_b32_e32 v127, v114, v116, vcc
	v_fma_f32 v34, v34, s78, -v127
	v_exp_f32_e32 v128, v34
	v_fma_f32 v34, v50, s78, -v127
	v_exp_f32_e32 v129, v34
	v_fma_f32 v34, v35, s78, -v127
	v_exp_f32_e32 v116, v34
	v_fma_f32 v34, v51, s78, -v127
	v_exp_f32_e32 v34, v34
	v_add_f32_e32 v117, v128, v129
	v_mov_b32_e32 v35, v33
	v_pk_add_f32 v[50:51], v[116:117], v[34:35]
	v_fma_f32 v35, v36, s78, -v127
	v_exp_f32_e32 v117, v35
	v_fma_f32 v35, v52, s78, -v127
	v_exp_f32_e32 v130, v35
	v_fma_f32 v35, v37, s78, -v127
	v_pk_add_f32 v[50:51], v[50:51], v[50:51] op_sel_hi:[0,1]
	v_exp_f32_e32 v118, v35
	v_fma_f32 v35, v53, s78, -v127
	v_exp_f32_e32 v50, v35
	v_add_f32_e32 v119, v117, v130
	v_fma_f32 v35, v38, s78, -v127
	v_pk_add_f32 v[36:37], v[118:119], v[50:51]
	v_exp_f32_e32 v51, v35
	v_fma_f32 v35, v54, s78, -v127
	v_exp_f32_e32 v119, v35
	v_fma_f32 v35, v39, s78, -v127
	v_pk_add_f32 v[52:53], v[36:37], v[36:37] op_sel_hi:[0,1]
	v_exp_f32_e32 v120, v35
	v_fma_f32 v35, v55, s78, -v127
	v_exp_f32_e32 v52, v35
	v_add_f32_e32 v121, v51, v119
	v_fma_f32 v35, v40, s78, -v127
	v_pk_add_f32 v[36:37], v[120:121], v[52:53]
	v_exp_f32_e32 v53, v35
	v_fma_f32 v35, v56, s78, -v127
	v_exp_f32_e32 v121, v35
	v_fma_f32 v35, v41, s78, -v127
	v_pk_add_f32 v[54:55], v[36:37], v[36:37] op_sel_hi:[0,1]
	v_exp_f32_e32 v56, v35
	v_fma_f32 v35, v57, s78, -v127
	v_exp_f32_e32 v54, v35
	v_add_f32_e32 v57, v53, v121
	v_fma_f32 v35, v42, s78, -v127
	v_pk_add_f32 v[36:37], v[56:57], v[54:55]
	v_exp_f32_e32 v55, v35
	v_fma_f32 v35, v58, s78, -v127
	v_exp_f32_e32 v131, v35
	v_fma_f32 v35, v43, s78, -v127
	v_pk_add_f32 v[36:37], v[36:37], v[36:37] op_sel_hi:[0,1]
	v_exp_f32_e32 v122, v35
	v_fma_f32 v35, v59, s78, -v127
	v_exp_f32_e32 v36, v35
	v_add_f32_e32 v123, v55, v131
	v_fma_f32 v35, v44, s78, -v127
	v_pk_add_f32 v[38:39], v[122:123], v[36:37]
	v_exp_f32_e32 v37, v35
	v_fma_f32 v35, v60, s78, -v127
	v_exp_f32_e32 v123, v35
	v_fma_f32 v35, v45, s78, -v127
	v_pk_add_f32 v[38:39], v[38:39], v[38:39] op_sel_hi:[0,1]
	v_exp_f32_e32 v60, v35
	v_fma_f32 v35, v61, s78, -v127
	v_exp_f32_e32 v38, v35
	v_add_f32_e32 v61, v37, v123
	v_fma_f32 v35, v46, s78, -v127
	v_pk_add_f32 v[40:41], v[60:61], v[38:39]
	v_exp_f32_e32 v39, v35
	v_fma_f32 v35, v62, s78, -v127
	v_exp_f32_e32 v61, v35
	v_fma_f32 v35, v47, s78, -v127
	v_pk_add_f32 v[40:41], v[40:41], v[40:41] op_sel_hi:[0,1]
	v_exp_f32_e32 v62, v35
	v_fma_f32 v35, v63, s78, -v127
	v_exp_f32_e32 v40, v35
	v_add_f32_e32 v63, v39, v61
	v_fma_f32 v35, v48, s78, -v127
	v_pk_add_f32 v[42:43], v[62:63], v[40:41]
	v_exp_f32_e32 v41, v35
	v_fma_f32 v35, v64, s78, -v127
	v_exp_f32_e32 v63, v35
	v_fma_f32 v35, v49, s78, -v127
	v_pk_add_f32 v[124:125], v[42:43], v[42:43] op_sel_hi:[0,1]
	v_exp_f32_e32 v64, v35
	v_fma_f32 v35, v65, s78, -v127
	v_exp_f32_e32 v124, v35
	v_add_f32_e32 v65, v41, v63
	v_sub_f32_e32 v35, v114, v127
	v_exp_f32_e32 v44, v35
	v_pk_add_f32 v[42:43], v[64:65], v[124:125]
	v_pk_add_f32 v[42:43], v[42:43], v[42:43] op_sel:[0,1] op_sel_hi:[1,0]
	v_mov_b32_e32 v35, v42
	s_nop 1
	v_permlane32_swap_b32_e32 v42, v35
	v_add_f32_e32 v35, v42, v35
	v_fmac_f32_e32 v35, v115, v44
	v_cmp_neq_f32_e32 vcc, 1.0, v44
	s_cbranch_vccz .Lattn_norescale_d64
	v_pk_mul_f32 v[14:15], v[14:15], v[44:45] op_sel_hi:[1,0]
	v_pk_mul_f32 v[12:13], v[12:13], v[44:45] op_sel_hi:[1,0]
	v_pk_mul_f32 v[10:11], v[10:11], v[44:45] op_sel_hi:[1,0]
	v_pk_mul_f32 v[8:9], v[8:9], v[44:45] op_sel_hi:[1,0]
	v_pk_mul_f32 v[6:7], v[6:7], v[44:45] op_sel_hi:[1,0]
	v_pk_mul_f32 v[4:5], v[4:5], v[44:45] op_sel_hi:[1,0]
	v_pk_mul_f32 v[2:3], v[2:3], v[44:45] op_sel_hi:[1,0]
	v_pk_mul_f32 v[0:1], v[0:1], v[44:45] op_sel_hi:[1,0]
	v_pk_mul_f32 v[30:31], v[30:31], v[44:45] op_sel_hi:[1,0]
	v_pk_mul_f32 v[28:29], v[28:29], v[44:45] op_sel_hi:[1,0]
	v_pk_mul_f32 v[26:27], v[26:27], v[44:45] op_sel_hi:[1,0]
	v_pk_mul_f32 v[24:25], v[24:25], v[44:45] op_sel_hi:[1,0]
	v_pk_mul_f32 v[22:23], v[22:23], v[44:45] op_sel_hi:[1,0]
	v_pk_mul_f32 v[20:21], v[20:21], v[44:45] op_sel_hi:[1,0]
	v_pk_mul_f32 v[18:19], v[18:19], v[44:45] op_sel_hi:[1,0]
	v_pk_mul_f32 v[16:17], v[16:17], v[44:45] op_sel_hi:[1,0]
.Lattn_norescale_d64:
	s_setprio 1
	v_add_u32_e32 v65, v126, v113
	v_cvt_pk_bf16_f32 v44, v51, v120
	v_add_u32_e32 v51, 0x2000, v65
	v_cvt_pk_bf16_f32 v45, v53, v56
	ds_read2_b64 v[46:49], v51 offset0:128 offset1:130
	ds_read2_b64 v[56:59], v51 offset0:132 offset1:134
	v_cvt_pk_bf16_f32 v42, v128, v116
	v_cvt_pk_bf16_f32 v43, v117, v118
	v_add_u32_e32 v53, 0x3000, v65
	v_cvt_pk_bf16_f32 v36, v131, v36
	s_waitcnt lgkmcnt(1)
	v_mfma_f32_32x32x16_bf16 v[0:15], v[46:49], v[42:45], v[0:15]
	ds_read2_b64 v[46:49], v53 offset0:192 offset1:194
	s_waitcnt lgkmcnt(0)
	v_mfma_f32_32x32x16_bf16 v[16:31], v[46:49], v[42:45], v[16:31]
	ds_read2_b64 v[46:49], v53 offset0:196 offset1:198
	v_cvt_pk_bf16_f32 v42, v55, v122
	v_cvt_pk_bf16_f32 v43, v37, v60
	v_cvt_pk_bf16_f32 v44, v39, v62
	v_cvt_pk_bf16_f32 v45, v41, v64
	v_cvt_pk_bf16_f32 v37, v123, v38
	v_cvt_pk_bf16_f32 v38, v61, v40
	s_waitcnt lgkmcnt(0)
	v_mfma_f32_32x32x16_bf16 v[16:31], v[46:49], v[42:45], v[16:31]
	ds_read2_b64 v[46:49], v51 offset0:136 offset1:138
	v_cvt_pk_bf16_f32 v39, v63, v124
	v_mfma_f32_32x32x16_bf16 v[0:15], v[56:59], v[42:45], v[0:15]
	v_cvt_pk_bf16_f32 v42, v129, v34
	v_cvt_pk_bf16_f32 v43, v130, v50
	v_cvt_pk_bf16_f32 v44, v119, v52
	v_cvt_pk_bf16_f32 v45, v121, v54
	s_waitcnt lgkmcnt(0)
	s_nop 0
	v_mfma_f32_32x32x16_bf16 v[0:15], v[46:49], v[42:45], v[0:15]
	ds_read2_b64 v[46:49], v53 offset0:200 offset1:202
	s_waitcnt lgkmcnt(0)
	v_mfma_f32_32x32x16_bf16 v[16:31], v[46:49], v[42:45], v[16:31]
	ds_read2_b64 v[40:43], v51 offset0:140 offset1:142
	s_waitcnt lgkmcnt(0)
	v_mfma_f32_32x32x16_bf16 v[0:15], v[40:43], v[36:39], v[0:15]
	ds_read2_b64 v[40:43], v53 offset0:204 offset1:206
	s_waitcnt lgkmcnt(0)
	v_mfma_f32_32x32x16_bf16 v[16:31], v[40:43], v[36:39], v[16:31]
	s_setprio 0
	s_cmp_lg_u32 s45, s46
	v_mov_b32_e32 v114, v127
	s_mov_b32 s47, s46
	s_cbranch_scc1 .LBB0_177
	s_lshl_b64 s[40:41], s[2:3], 11
	s_add_u32 s40, s94, s40
	s_addc_u32 s41, s95, s41
	s_lshl_b32 s29, s29, 1
	s_add_u32 s29, s40, s29
	s_addc_u32 s41, s41, 0
	v_readlane_b32 s52, v233, 61
	s_add_u32 s40, s29, 0x60fd400
	v_readlane_b32 s62, v232, 7
	v_readlane_b32 s63, v232, 8
	v_lshlrev_b32_e32 v112, 2, v108
	s_addc_u32 s41, s41, 0
	s_mov_b64 s[42:43], 0
	v_readlane_b32 s53, v233, 62
	v_readlane_b32 s58, v232, 3
	v_readlane_b32 s59, v232, 4
	v_readlane_b32 s60, v232, 5
	v_readlane_b32 s61, v232, 6
	v_readlane_b32 s64, v232, 9
	v_readlane_b32 s65, v232, 10
	v_readlane_b32 s66, v232, 11
	v_readlane_b32 s67, v232, 12
	v_readlane_b32 s63, v235, 21
	v_readlane_b32 s62, v232, 31
	s_barrier
	v_readlane_b32 s54, v233, 63
	v_readlane_b32 s55, v232, 0
	v_readlane_b32 s56, v232, 1
	v_readlane_b32 s57, v232, 2

.LBB0_185:
	s_bitcmp1_b32 s44, 0
	s_cselect_b32 s43, 0x5800, 0
	s_add_i32 s42, s44, 1
	s_cmp_lt_u32 s42, s41
	s_cselect_b32 s48, s42, s44
	s_cmp_lt_u32 s48, s25
	s_cselect_b64 s[44:45], -1, 0
	s_and_b64 s[46:47], s[44:45], exec
	s_cselect_b32 s47, s39, s30
	s_cselect_b32 s46, s38, s28
	s_sub_i32 s49, s48, s25
	v_or_b32_e32 v34, s43, v32
	s_min_u32 s48, s48, s49
	v_add3_u32 v36, s43, v113, v126
	v_add_u32_e32 v37, v34, v119
	s_lshl_b32 s48, s48, 6
	v_add_u32_e32 v38, v34, v128
	v_add_u32_e32 v39, v34, v129
	v_add_u32_e32 v34, v34, v130
	s_waitcnt vmcnt(1)
	ds_write_b128 v37, v[102:105]
	ds_write_b128 v38, v[98:101] offset:13312
	ds_write_b128 v39, v[90:93]
	ds_write_b128 v34, v[94:97] offset:13312
	s_waitcnt vmcnt(0)
	ds_write_b128 v36, v[106:109] offset:128
	v_lshl_add_u64 v[36:37], s[46:47], 0, v[32:33]
	s_and_b64 s[46:47], s[44:45], exec
	v_add_u32_e32 v38, s48, v114
	v_add_u32_e32 v40, s48, v116
	s_cselect_b32 s46, 0, 0x400
	v_ashrrev_i32_e32 v39, 31, v38
	v_ashrrev_i32_e32 v41, 31, v40
	s_add_i32 s46, s48, s46
	v_add_u32_e32 v42, s48, v118
	v_lshlrev_b64 v[38:39], 10, v[38:39]
	v_lshlrev_b64 v[40:41], 10, v[40:41]
	s_ashr_i32 s47, s46, 31
	v_ashrrev_i32_e32 v43, 31, v42
	v_lshl_add_u64 v[38:39], v[36:37], 0, v[38:39]
	v_lshl_add_u64 v[36:37], v[36:37], 0, v[40:41]
	v_lshl_add_u64 v[40:41], s[46:47], 1, v[120:121]
	s_and_b64 s[44:45], s[44:45], exec
	s_waitcnt lgkmcnt(0)
	s_barrier
	v_lshlrev_b64 v[42:43], 6, v[42:43]
	global_load_dwordx4 v[102:105], v[38:39], off
	global_load_dwordx4 v[90:93], v[36:37], off
	v_lshl_add_u64 v[36:37], v[124:125], 1, v[40:41]
	s_cselect_b32 s45, s37, s40
	s_cselect_b32 s44, s36, s31
	v_mov_b32_e32 v127, v33
	v_lshl_add_u64 v[38:39], v[122:123], 1, v[40:41]
	global_load_dwordx4 v[98:101], v[36:37], off
	global_load_dwordx4 v[94:97], v[38:39], off
	v_lshl_add_u64 v[36:37], s[44:45], 0, v[42:43]
	v_lshl_add_u64 v[36:37], v[36:37], 0, v[126:127]
	global_load_dwordx4 v[106:109], v[36:37], off
	v_mov_b32_e32 v127, v35
	s_setprio 1
	v_add3_u32 v133, s43, v115, v131
	ds_read_b128 v[34:37], v133
	ds_read_b128 v[134:137], v133 offset:32
	ds_read_b128 v[50:53], v133 offset:6656
	s_waitcnt lgkmcnt(2)
	v_mfma_f32_32x32x16_bf16 v[34:49], v[34:37], v[66:69], 0
	s_waitcnt lgkmcnt(1)
	v_mfma_f32_32x32x16_bf16 v[34:49], v[134:137], v[70:73], v[34:49]
	ds_read_b128 v[134:137], v133 offset:6688
	s_waitcnt lgkmcnt(1)
	v_mfma_f32_32x32x16_bf16 v[50:65], v[50:53], v[66:69], 0
	s_waitcnt lgkmcnt(0)
	v_mfma_f32_32x32x16_bf16 v[50:65], v[134:137], v[70:73], v[50:65]
	ds_read_b128 v[134:137], v133 offset:64
	s_waitcnt lgkmcnt(0)
	v_mfma_f32_32x32x16_bf16 v[34:49], v[134:137], v[74:77], v[34:49]
	ds_read_b128 v[134:137], v133 offset:6720
	s_waitcnt lgkmcnt(0)
	v_mfma_f32_32x32x16_bf16 v[50:65], v[134:137], v[74:77], v[50:65]
	ds_read_b128 v[134:137], v133 offset:96
	s_waitcnt lgkmcnt(0)
	v_mfma_f32_32x32x16_bf16 v[34:49], v[134:137], v[78:81], v[34:49]
	ds_read_b128 v[134:137], v133 offset:6752
	s_waitcnt lgkmcnt(0)
	v_mfma_f32_32x32x16_bf16 v[50:65], v[134:137], v[78:81], v[50:65]
	ds_read_b128 v[134:137], v133 offset:128
	s_waitcnt lgkmcnt(0)
	v_mfma_f32_32x32x16_bf16 v[34:49], v[134:137], v[82:85], v[34:49]
	ds_read_b128 v[134:137], v133 offset:6784
	s_waitcnt lgkmcnt(0)
	v_mfma_f32_32x32x16_bf16 v[50:65], v[134:137], v[82:85], v[50:65]
	ds_read_b128 v[134:137], v133 offset:160
	s_waitcnt lgkmcnt(0)
	v_mfma_f32_32x32x16_bf16 v[34:49], v[134:137], v[86:89], v[34:49]
	ds_read_b128 v[134:137], v133 offset:6816
	s_waitcnt lgkmcnt(0)
	v_mfma_f32_32x32x16_bf16 v[50:65], v[134:137], v[86:89], v[50:65]
	s_setprio 0
	s_nop 7
	v_mul_f32_e32 v133, 0x3e16c740, v34
	s_nop 1
	v_mul_f32_e32 v134, 0x3e16c740, v50
	v_max_f32_e32 v133, v133, v134
	v_mul_f32_e32 v134, 0x3e16c740, v35
	v_mul_f32_e32 v135, 0x3e16c740, v51
	v_max_f32_e32 v134, v134, v135
	v_max3_f32 v133, v133, s50, v134
	v_mul_f32_e32 v134, 0x3e16c740, v36
	v_mul_f32_e32 v135, 0x3e16c740, v52
	v_max_f32_e32 v134, v134, v135
	v_mul_f32_e32 v135, 0x3e16c740, v37
	v_mul_f32_e32 v136, 0x3e16c740, v53
	v_max_f32_e32 v135, v135, v136
	v_max3_f32 v133, v133, v134, v135
	v_mul_f32_e32 v134, 0x3e16c740, v38
	v_mul_f32_e32 v135, 0x3e16c740, v54
	v_max_f32_e32 v134, v134, v135
	v_mul_f32_e32 v135, 0x3e16c740, v39
	v_mul_f32_e32 v136, 0x3e16c740, v55
	v_max_f32_e32 v135, v135, v136
	v_max3_f32 v133, v133, v134, v135
	v_mul_f32_e32 v134, 0x3e16c740, v40
	v_mul_f32_e32 v135, 0x3e16c740, v56
	v_max_f32_e32 v134, v134, v135
	v_mul_f32_e32 v135, 0x3e16c740, v41
	v_mul_f32_e32 v136, 0x3e16c740, v57
	v_max_f32_e32 v135, v135, v136
	v_max3_f32 v133, v133, v134, v135
	v_mul_f32_e32 v134, 0x3e16c740, v42
	v_mul_f32_e32 v135, 0x3e16c740, v58
	v_max_f32_e32 v134, v134, v135
	v_mul_f32_e32 v135, 0x3e16c740, v43
	v_mul_f32_e32 v136, 0x3e16c740, v59
	v_max_f32_e32 v135, v135, v136
	v_max3_f32 v133, v133, v134, v135
	v_mul_f32_e32 v134, 0x3e16c740, v44
	v_mul_f32_e32 v135, 0x3e16c740, v60
	v_max_f32_e32 v134, v134, v135
	v_mul_f32_e32 v135, 0x3e16c740, v45
	v_mul_f32_e32 v136, 0x3e16c740, v61
	v_max_f32_e32 v135, v135, v136
	v_max3_f32 v133, v133, v134, v135
	v_mul_f32_e32 v134, 0x3e16c740, v46
	v_mul_f32_e32 v135, 0x3e16c740, v62
	v_max_f32_e32 v134, v134, v135
	v_mul_f32_e32 v135, 0x3e16c740, v47
	v_mul_f32_e32 v136, 0x3e16c740, v63
	v_max_f32_e32 v135, v135, v136
	v_max3_f32 v133, v133, v134, v135
	v_mul_f32_e32 v134, 0x3e16c740, v48
	v_mul_f32_e32 v135, 0x3e16c740, v64
	v_max_f32_e32 v134, v134, v135
	v_mul_f32_e32 v135, 0x3e16c740, v49
	v_mul_f32_e32 v136, 0x3e16c740, v65
	v_max_f32_e32 v135, v135, v136
	v_max3_f32 v133, v133, v134, v135
	v_mov_b32_e32 v134, v133
	s_nop 1
	v_permlane32_swap_b32_e32 v133, v134
	v_max_f32_e32 v134, v134, v134
	v_max_f32_e32 v133, v133, v133
	v_max_f32_e32 v133, v133, v134
	v_add_f32_e32 v134, 0x41000000, v132
	v_cmp_gt_f32_e32 vcc, v133, v134
	s_nop 1
	v_cndmask_b32_e32 v133, v132, v133, vcc
	v_fma_f32 v34, v34, s73, -v133
	v_exp_f32_e32 v146, v34
	v_fma_f32 v34, v50, s73, -v133
	v_exp_f32_e32 v147, v34
	v_fma_f32 v34, v35, s73, -v133
	v_exp_f32_e32 v134, v34
	v_fma_f32 v34, v51, s73, -v133
	v_exp_f32_e32 v34, v34
	v_add_f32_e32 v135, v146, v147
	v_mov_b32_e32 v35, v33
	v_pk_add_f32 v[50:51], v[134:135], v[34:35]
	v_fma_f32 v35, v36, s73, -v133
	v_exp_f32_e32 v135, v35
	v_fma_f32 v35, v52, s73, -v133
	v_exp_f32_e32 v148, v35
	v_fma_f32 v35, v37, s73, -v133
	v_pk_add_f32 v[50:51], v[50:51], v[50:51] op_sel_hi:[0,1]
	v_exp_f32_e32 v136, v35
	v_fma_f32 v35, v53, s73, -v133
	v_exp_f32_e32 v50, v35
	v_add_f32_e32 v137, v135, v148
	v_fma_f32 v35, v38, s73, -v133
	v_pk_add_f32 v[36:37], v[136:137], v[50:51]
	v_exp_f32_e32 v51, v35
	v_fma_f32 v35, v54, s73, -v133
	v_exp_f32_e32 v137, v35
	v_fma_f32 v35, v39, s73, -v133
	v_pk_add_f32 v[52:53], v[36:37], v[36:37] op_sel_hi:[0,1]
	v_exp_f32_e32 v138, v35
	v_fma_f32 v35, v55, s73, -v133
	v_exp_f32_e32 v52, v35
	v_add_f32_e32 v139, v51, v137
	v_fma_f32 v35, v40, s73, -v133
	v_pk_add_f32 v[36:37], v[138:139], v[52:53]
	v_exp_f32_e32 v53, v35
	v_fma_f32 v35, v56, s73, -v133
	v_exp_f32_e32 v139, v35
	v_fma_f32 v35, v41, s73, -v133
	v_pk_add_f32 v[54:55], v[36:37], v[36:37] op_sel_hi:[0,1]
	v_exp_f32_e32 v56, v35
	v_fma_f32 v35, v57, s73, -v133
	v_exp_f32_e32 v54, v35
	v_add_f32_e32 v57, v53, v139
	v_fma_f32 v35, v42, s73, -v133
	v_pk_add_f32 v[36:37], v[56:57], v[54:55]
	v_exp_f32_e32 v55, v35
	v_fma_f32 v35, v58, s73, -v133
	v_exp_f32_e32 v149, v35
	v_fma_f32 v35, v43, s73, -v133
	v_pk_add_f32 v[36:37], v[36:37], v[36:37] op_sel_hi:[0,1]
	v_exp_f32_e32 v140, v35
	v_fma_f32 v35, v59, s73, -v133
	v_exp_f32_e32 v36, v35
	v_add_f32_e32 v141, v55, v149
	v_fma_f32 v35, v44, s73, -v133
	v_pk_add_f32 v[38:39], v[140:141], v[36:37]
	v_exp_f32_e32 v37, v35
	v_fma_f32 v35, v60, s73, -v133
	v_exp_f32_e32 v141, v35
	v_fma_f32 v35, v45, s73, -v133
	v_pk_add_f32 v[38:39], v[38:39], v[38:39] op_sel_hi:[0,1]
	v_exp_f32_e32 v142, v35
	v_fma_f32 v35, v61, s73, -v133
	v_exp_f32_e32 v38, v35
	v_add_f32_e32 v143, v37, v141
	v_fma_f32 v35, v46, s73, -v133
	v_pk_add_f32 v[40:41], v[142:143], v[38:39]
	v_exp_f32_e32 v39, v35
	v_fma_f32 v35, v62, s73, -v133
	v_exp_f32_e32 v143, v35
	v_fma_f32 v35, v47, s73, -v133
	v_pk_add_f32 v[40:41], v[40:41], v[40:41] op_sel_hi:[0,1]
	v_exp_f32_e32 v144, v35
	v_fma_f32 v35, v63, s73, -v133
	v_exp_f32_e32 v40, v35
	v_add_f32_e32 v145, v39, v143
	v_fma_f32 v35, v48, s73, -v133
	v_pk_add_f32 v[42:43], v[144:145], v[40:41]
	v_exp_f32_e32 v41, v35
	v_fma_f32 v35, v64, s73, -v133
	v_exp_f32_e32 v64, v35
	v_fma_f32 v35, v49, s73, -v133
	v_pk_add_f32 v[42:43], v[42:43], v[42:43] op_sel_hi:[0,1]
	v_exp_f32_e32 v48, v35
	v_fma_f32 v35, v65, s73, -v133
	v_exp_f32_e32 v42, v35
	v_add_f32_e32 v49, v41, v64
	v_sub_f32_e32 v35, v132, v133
	v_exp_f32_e32 v46, v35
	v_pk_add_f32 v[44:45], v[48:49], v[42:43]
	v_pk_add_f32 v[44:45], v[44:45], v[44:45] op_sel:[0,1] op_sel_hi:[1,0]
	v_mov_b32_e32 v35, v44
	s_nop 1
	v_permlane32_swap_b32_e32 v44, v35
	v_add_f32_e32 v35, v44, v35
	v_fmac_f32_e32 v35, v127, v46
	v_cmp_neq_f32_e32 vcc, 1.0, v46
	s_cbranch_vccz .Lattn_norescale_d96
	v_pk_mul_f32 v[14:15], v[14:15], v[46:47] op_sel_hi:[1,0]
	v_pk_mul_f32 v[12:13], v[12:13], v[46:47] op_sel_hi:[1,0]
	v_pk_mul_f32 v[10:11], v[10:11], v[46:47] op_sel_hi:[1,0]
	v_pk_mul_f32 v[8:9], v[8:9], v[46:47] op_sel_hi:[1,0]
	v_pk_mul_f32 v[6:7], v[6:7], v[46:47] op_sel_hi:[1,0]
	v_pk_mul_f32 v[4:5], v[4:5], v[46:47] op_sel_hi:[1,0]
	v_pk_mul_f32 v[2:3], v[2:3], v[46:47] op_sel_hi:[1,0]
	v_pk_mul_f32 v[0:1], v[0:1], v[46:47] op_sel_hi:[1,0]
	v_pk_mul_f32 v[30:31], v[30:31], v[46:47] op_sel_hi:[1,0]
	v_pk_mul_f32 v[28:29], v[28:29], v[46:47] op_sel_hi:[1,0]
	v_pk_mul_f32 v[26:27], v[26:27], v[46:47] op_sel_hi:[1,0]
	v_pk_mul_f32 v[24:25], v[24:25], v[46:47] op_sel_hi:[1,0]
	v_pk_mul_f32 v[22:23], v[22:23], v[46:47] op_sel_hi:[1,0]
	v_pk_mul_f32 v[20:21], v[20:21], v[46:47] op_sel_hi:[1,0]
	v_pk_mul_f32 v[18:19], v[18:19], v[46:47] op_sel_hi:[1,0]
	v_pk_mul_f32 v[16:17], v[16:17], v[46:47] op_sel_hi:[1,0]
.Lattn_norescale_d96:
	s_setprio 1
	v_lshlrev_b32_e32 v43, 1, v112
	v_add3_u32 v43, s43, v117, v43
	v_cvt_pk_bf16_f32 v47, v53, v56
	v_add_u32_e32 v53, 0x3000, v43
	ds_read2_b64 v[56:59], v53 offset0:128 offset1:130
	ds_read2_b64 v[60:63], v53 offset0:132 offset1:134
	v_cvt_pk_bf16_f32 v44, v146, v134
	v_cvt_pk_bf16_f32 v45, v135, v136
	v_cvt_pk_bf16_f32 v46, v51, v138
	v_add_u32_e32 v65, 0x4000, v43
	v_cvt_pk_bf16_f32 v36, v149, v36
	s_waitcnt lgkmcnt(1)
	v_mfma_f32_32x32x16_bf16 v[0:15], v[56:59], v[44:47], v[0:15]
	ds_read2_b64 v[56:59], v65 offset0:192 offset1:194
	s_waitcnt lgkmcnt(0)
	v_mfma_f32_32x32x16_bf16 v[16:31], v[56:59], v[44:47], v[16:31]
	ds_read2_b64 v[56:59], v65 offset0:196 offset1:198
	v_cvt_pk_bf16_f32 v44, v55, v140
	v_cvt_pk_bf16_f32 v45, v37, v142
	v_cvt_pk_bf16_f32 v46, v39, v144
	v_cvt_pk_bf16_f32 v47, v41, v48
	v_cvt_pk_bf16_f32 v37, v141, v38
	v_cvt_pk_bf16_f32 v38, v143, v40
	v_mfma_f32_32x32x16_bf16 v[0:15], v[60:63], v[44:47], v[0:15]
	v_cvt_pk_bf16_f32 v39, v64, v42
	ds_read2_b64 v[40:43], v53 offset0:140 offset1:142
	s_waitcnt lgkmcnt(1)
	v_mfma_f32_32x32x16_bf16 v[16:31], v[56:59], v[44:47], v[16:31]
	v_cvt_pk_bf16_f32 v45, v148, v50
	ds_read2_b64 v[48:51], v53 offset0:136 offset1:138
	v_cvt_pk_bf16_f32 v44, v147, v34
	v_cvt_pk_bf16_f32 v46, v137, v52
	v_cvt_pk_bf16_f32 v47, v139, v54
	s_waitcnt lgkmcnt(0)
	s_nop 0
	v_mfma_f32_32x32x16_bf16 v[0:15], v[48:51], v[44:47], v[0:15]
	ds_read2_b64 v[48:51], v65 offset0:200 offset1:202
	v_mfma_f32_32x32x16_bf16 v[0:15], v[40:43], v[36:39], v[0:15]
	ds_read2_b64 v[40:43], v65 offset0:204 offset1:206
	s_waitcnt lgkmcnt(1)
	v_mfma_f32_32x32x16_bf16 v[16:31], v[48:51], v[44:47], v[16:31]
	s_waitcnt lgkmcnt(0)
	v_mfma_f32_32x32x16_bf16 v[16:31], v[40:43], v[36:39], v[16:31]
	s_setprio 0
	s_cmp_lg_u32 s27, s42
	v_mov_b32_e32 v132, v133
	s_mov_b32 s44, s42
	s_cbranch_scc1 .LBB0_185
	s_lshl_b64 s[30:31], s[2:3], 11
	s_add_u32 s2, s63, s30
	v_readlane_b32 s25, v235, 22
	s_addc_u32 s25, s25, s31
	s_lshl_b32 s27, s29, 1
	s_add_u32 s40, s2, s27
	s_addc_u32 s41, s25, 0
	s_barrier
	s_branch .LBB0_159

.LBB0_773:
	v_max_f32_e32 v44, v109, v109
	v_max_f32_e32 v45, v108, v108
	v_max_f32_e32 v44, v45, v44
	v_max_f32_e32 v45, v35, v35
	v_max_f32_e32 v46, v34, v34
	v_max_f32_e32 v45, v46, v45
	v_max3_f32 v44, v44, s53, v45
	v_max_f32_e32 v45, v51, v51
	v_max_f32_e32 v46, v50, v50
	v_max_f32_e32 v45, v46, v45
	v_max_f32_e32 v46, v37, v37
	v_max_f32_e32 v47, v36, v36
	v_max_f32_e32 v46, v47, v46
	v_max3_f32 v44, v44, v45, v46
	v_max_f32_e32 v45, v53, v53
	v_max_f32_e32 v46, v52, v52
	v_max_f32_e32 v45, v46, v45
	v_max_f32_e32 v46, v39, v39
	v_max_f32_e32 v47, v38, v38
	v_max_f32_e32 v46, v47, v46
	v_max3_f32 v44, v44, v45, v46
	v_max_f32_e32 v45, v55, v55
	v_max_f32_e32 v46, v54, v54
	v_max_f32_e32 v45, v46, v45
	v_max_f32_e32 v46, v41, v41
	v_max_f32_e32 v47, v40, v40
	v_max_f32_e32 v46, v47, v46
	v_max3_f32 v44, v44, v45, v46
	v_max_f32_e32 v45, v57, v57
	v_max_f32_e32 v46, v56, v56
	v_max_f32_e32 v45, v46, v45
	v_max_f32_e32 v46, v43, v43
	v_max_f32_e32 v47, v42, v42
	v_max_f32_e32 v46, v47, v46
	v_max3_f32 v44, v44, v45, v46
	v_max_f32_e32 v45, v59, v59
	v_max_f32_e32 v46, v58, v58
	v_max_f32_e32 v45, v46, v45
	v_max_f32_e32 v46, v61, v61
	v_max_f32_e32 v47, v60, v60
	v_max_f32_e32 v46, v47, v46
	v_max3_f32 v44, v44, v45, v46
	v_max_f32_e32 v45, v111, v111
	v_max_f32_e32 v46, v110, v110
	v_max_f32_e32 v45, v46, v45
	v_max_f32_e32 v46, v63, v63
	v_max_f32_e32 v47, v62, v62
	v_max_f32_e32 v46, v47, v46
	v_max3_f32 v44, v44, v45, v46
	v_max_f32_e32 v45, v113, v113
	v_max_f32_e32 v46, v112, v112
	v_max_f32_e32 v45, v46, v45
	v_max_f32_e32 v46, v65, v65
	v_max_f32_e32 v47, v64, v64
	v_max_f32_e32 v46, v47, v46
	v_max3_f32 v44, v44, v45, v46
	v_mov_b32_e32 v45, v44
	s_nop 1
	v_permlane32_swap_b32_e32 v44, v45
	v_max_f32_e32 v45, v45, v45
	v_max_f32_e32 v44, v44, v44
	v_max_f32_e32 v44, v44, v45
	v_add_f32_e32 v45, 0x41000000, v123
	v_cmp_gt_f32_e32 vcc, v44, v45
	s_nop 1
	v_cndmask_b32_e32 v125, v123, v44, vcc
	v_sub_f32_e32 v44, v108, v125
	v_exp_f32_e32 v130, v44
	v_sub_f32_e32 v44, v109, v125
	v_sub_f32_e32 v34, v34, v125
	v_exp_f32_e32 v131, v44
	v_exp_f32_e32 v108, v34
	v_sub_f32_e32 v34, v35, v125
	v_exp_f32_e32 v34, v34
	v_add_f32_e32 v109, v130, v131
	v_mov_b32_e32 v35, v33
	v_pk_add_f32 v[44:45], v[108:109], v[34:35]
	v_sub_f32_e32 v35, v50, v125
	v_exp_f32_e32 v109, v35
	v_sub_f32_e32 v35, v51, v125
	v_exp_f32_e32 v133, v35
	v_sub_f32_e32 v35, v36, v125
	v_pk_add_f32 v[44:45], v[44:45], v[44:45] op_sel_hi:[0,1]
	v_exp_f32_e32 v126, v35
	v_sub_f32_e32 v35, v37, v125
	v_exp_f32_e32 v44, v35
	v_add_f32_e32 v127, v109, v133
	v_sub_f32_e32 v35, v52, v125
	v_pk_add_f32 v[36:37], v[126:127], v[44:45]
	v_exp_f32_e32 v45, v35
	v_sub_f32_e32 v35, v53, v125
	v_exp_f32_e32 v127, v35
	v_sub_f32_e32 v35, v38, v125
	v_pk_add_f32 v[46:47], v[36:37], v[36:37] op_sel_hi:[0,1]
	v_exp_f32_e32 v52, v35
	v_sub_f32_e32 v35, v39, v125
	v_exp_f32_e32 v46, v35
	v_add_f32_e32 v53, v45, v127
	v_sub_f32_e32 v35, v54, v125
	v_pk_add_f32 v[36:37], v[52:53], v[46:47]
	v_exp_f32_e32 v47, v35
	v_sub_f32_e32 v35, v55, v125
	v_exp_f32_e32 v134, v35
	v_sub_f32_e32 v35, v40, v125
	v_pk_add_f32 v[48:49], v[36:37], v[36:37] op_sel_hi:[0,1]
	v_exp_f32_e32 v54, v35
	v_sub_f32_e32 v35, v41, v125
	v_exp_f32_e32 v48, v35
	v_add_f32_e32 v55, v47, v134
	v_sub_f32_e32 v35, v56, v125
	v_pk_add_f32 v[36:37], v[54:55], v[48:49]
	v_exp_f32_e32 v49, v35
	v_sub_f32_e32 v35, v57, v125
	v_exp_f32_e32 v135, v35
	v_sub_f32_e32 v35, v42, v125
	v_pk_add_f32 v[36:37], v[36:37], v[36:37] op_sel_hi:[0,1]
	v_exp_f32_e32 v42, v35
	v_sub_f32_e32 v35, v43, v125
	v_exp_f32_e32 v36, v35
	v_add_f32_e32 v43, v49, v135
	v_sub_f32_e32 v35, v58, v125
	v_pk_add_f32 v[38:39], v[42:43], v[36:37]
	v_exp_f32_e32 v37, v35
	v_sub_f32_e32 v35, v59, v125
	v_exp_f32_e32 v136, v35
	v_sub_f32_e32 v35, v60, v125
	v_pk_add_f32 v[38:39], v[38:39], v[38:39] op_sel_hi:[0,1]
	v_exp_f32_e32 v128, v35
	v_sub_f32_e32 v35, v61, v125
	v_exp_f32_e32 v38, v35
	v_add_f32_e32 v129, v37, v136
	v_sub_f32_e32 v35, v110, v125
	v_pk_add_f32 v[40:41], v[128:129], v[38:39]
	v_exp_f32_e32 v39, v35
	v_sub_f32_e32 v35, v111, v125
	v_exp_f32_e32 v129, v35
	v_sub_f32_e32 v35, v62, v125
	v_pk_add_f32 v[40:41], v[40:41], v[40:41] op_sel_hi:[0,1]
	v_exp_f32_e32 v62, v35
	v_sub_f32_e32 v35, v63, v125
	v_exp_f32_e32 v40, v35
	v_add_f32_e32 v63, v39, v129
	v_sub_f32_e32 v35, v112, v125
	v_pk_add_f32 v[50:51], v[62:63], v[40:41]
	v_exp_f32_e32 v41, v35
	v_sub_f32_e32 v35, v113, v125
	v_exp_f32_e32 v63, v35
	v_sub_f32_e32 v35, v64, v125
	v_pk_add_f32 v[110:111], v[50:51], v[50:51] op_sel_hi:[0,1]
	v_exp_f32_e32 v64, v35
	v_sub_f32_e32 v35, v65, v125
	v_exp_f32_e32 v110, v35
	v_add_f32_e32 v65, v41, v63
	v_sub_f32_e32 v35, v123, v125
	v_exp_f32_e32 v56, v35
	v_pk_add_f32 v[50:51], v[64:65], v[110:111]
	v_pk_add_f32 v[50:51], v[50:51], v[50:51] op_sel:[0,1] op_sel_hi:[1,0]
	v_mov_b32_e32 v35, v50
	s_nop 1
	v_permlane32_swap_b32_e32 v50, v35
	v_add_f32_e32 v35, v50, v35
	v_fmac_f32_e32 v35, v122, v56
	v_cmp_neq_f32_e32 vcc, 1.0, v56
	s_cbranch_vccz .Lattn_norescale_band
	v_pk_mul_f32 v[14:15], v[14:15], v[56:57] op_sel_hi:[1,0]
	v_pk_mul_f32 v[12:13], v[12:13], v[56:57] op_sel_hi:[1,0]
	v_pk_mul_f32 v[10:11], v[10:11], v[56:57] op_sel_hi:[1,0]
	v_pk_mul_f32 v[8:9], v[8:9], v[56:57] op_sel_hi:[1,0]
	v_pk_mul_f32 v[6:7], v[6:7], v[56:57] op_sel_hi:[1,0]
	v_pk_mul_f32 v[4:5], v[4:5], v[56:57] op_sel_hi:[1,0]
	v_pk_mul_f32 v[2:3], v[2:3], v[56:57] op_sel_hi:[1,0]
	v_pk_mul_f32 v[0:1], v[0:1], v[56:57] op_sel_hi:[1,0]
	v_pk_mul_f32 v[30:31], v[30:31], v[56:57] op_sel_hi:[1,0]
	v_pk_mul_f32 v[28:29], v[28:29], v[56:57] op_sel_hi:[1,0]
	v_pk_mul_f32 v[26:27], v[26:27], v[56:57] op_sel_hi:[1,0]
	v_pk_mul_f32 v[24:25], v[24:25], v[56:57] op_sel_hi:[1,0]
	v_pk_mul_f32 v[22:23], v[22:23], v[56:57] op_sel_hi:[1,0]
	v_pk_mul_f32 v[20:21], v[20:21], v[56:57] op_sel_hi:[1,0]
	v_pk_mul_f32 v[18:19], v[18:19], v[56:57] op_sel_hi:[1,0]
	v_pk_mul_f32 v[16:17], v[16:17], v[56:57] op_sel_hi:[1,0]
.Lattn_norescale_band:
	s_setprio 1
	v_add_u32_e32 v43, v124, v121
	v_add_u32_e32 v65, 0x2000, v43
	v_cvt_pk_bf16_f32 v53, v47, v54
	ds_read2_b64 v[54:57], v65 offset0:128 offset1:130
	ds_read2_b64 v[58:61], v65 offset0:132 offset1:134
	v_cvt_pk_bf16_f32 v50, v130, v108
	v_cvt_pk_bf16_f32 v51, v109, v126
	v_cvt_pk_bf16_f32 v52, v45, v52
	v_add_u32_e32 v108, 0x3000, v43
	v_cvt_pk_bf16_f32 v43, v133, v44
	s_waitcnt lgkmcnt(1)
	v_mfma_f32_32x32x16_bf16 v[0:15], v[54:57], v[50:53], v[0:15]
	ds_read2_b64 v[54:57], v108 offset0:192 offset1:194
	v_cvt_pk_bf16_f32 v44, v127, v46
	v_cvt_pk_bf16_f32 v45, v134, v48
	v_cvt_pk_bf16_f32 v36, v135, v36
	s_waitcnt lgkmcnt(0)
	v_mfma_f32_32x32x16_bf16 v[16:31], v[54:57], v[50:53], v[16:31]
	v_cvt_pk_bf16_f32 v50, v49, v42
	v_cvt_pk_bf16_f32 v51, v37, v128
	v_cvt_pk_bf16_f32 v52, v39, v62
	v_cvt_pk_bf16_f32 v53, v41, v64
	ds_read2_b64 v[46:49], v65 offset0:136 offset1:138
	ds_read2_b64 v[54:57], v108 offset0:196 offset1:198
	v_cvt_pk_bf16_f32 v42, v131, v34
	v_mfma_f32_32x32x16_bf16 v[0:15], v[58:61], v[50:53], v[0:15]
	v_cvt_pk_bf16_f32 v37, v136, v38
	v_cvt_pk_bf16_f32 v38, v129, v40
	v_cvt_pk_bf16_f32 v39, v63, v110
	s_waitcnt lgkmcnt(1)
	v_mfma_f32_32x32x16_bf16 v[0:15], v[46:49], v[42:45], v[0:15]
	ds_read2_b64 v[46:49], v108 offset0:200 offset1:202
	s_waitcnt lgkmcnt(1)
	v_mfma_f32_32x32x16_bf16 v[16:31], v[54:57], v[50:53], v[16:31]
	s_waitcnt lgkmcnt(0)
	v_mfma_f32_32x32x16_bf16 v[16:31], v[46:49], v[42:45], v[16:31]
	ds_read2_b64 v[40:43], v65 offset0:140 offset1:142
	s_waitcnt lgkmcnt(0)
	v_mfma_f32_32x32x16_bf16 v[0:15], v[40:43], v[36:39], v[0:15]
	ds_read2_b64 v[40:43], v108 offset0:204 offset1:206
	s_waitcnt lgkmcnt(0)
	v_mfma_f32_32x32x16_bf16 v[16:31], v[40:43], v[36:39], v[16:31]
	s_setprio 0
	s_add_i32 s44, s44, 64
	s_add_i32 s31, s31, 64
	s_cmp_lg_u32 s45, s30
	s_cbranch_scc0 .LBB0_776
	v_mov_b32_e32 v123, v125
	v_mov_b32_e32 v122, v35
	s_branch .LBB0_741

.LBB0_784:
	s_waitcnt lgkmcnt(0)
	s_barrier
	s_setprio 1
	v_add_u32_e32 v156, v137, v136
	ds_read_b128 v[80:83], v156 offset:8704
	ds_read_b128 v[84:87], v156
	ds_read_b128 v[96:99], v156 offset:32
	ds_read_b128 v[100:103], v156 offset:8736
	v_cvt_pk_bf16_f32 v184, v8, v9
	v_cvt_pk_bf16_f32 v185, v10, v11
	s_waitcnt lgkmcnt(2)
	v_mfma_f32_32x32x16_bf16 v[80:95], v[80:83], v[84:87], 0
	v_cvt_pk_bf16_f32 v186, v12, v13
	v_cvt_pk_bf16_f32 v187, v14, v15
	v_cvt_pk_bf16_f32 v188, v16, v17
	v_cvt_pk_bf16_f32 v189, v18, v19
	v_cvt_pk_bf16_f32 v190, v20, v21
	v_cvt_pk_bf16_f32 v191, v22, v23
	v_cvt_pk_bf16_f32 v196, v56, v57
	s_waitcnt lgkmcnt(0)
	v_mfma_f32_32x32x16_bf16 v[80:95], v[100:103], v[96:99], v[80:95]
	ds_read_b128 v[96:99], v156 offset:8768
	ds_read_b128 v[100:103], v156 offset:64
	ds_read_b128 v[104:107], v156 offset:8800
	ds_read_b128 v[108:111], v156 offset:96
	v_cvt_pk_bf16_f32 v197, v58, v59
	v_cvt_pk_bf16_f32 v198, v60, v61
	v_cvt_pk_bf16_f32 v199, v62, v63
	s_waitcnt lgkmcnt(2)
	v_mfma_f32_32x32x16_bf16 v[80:95], v[96:99], v[100:103], v[80:95]
	s_waitcnt lgkmcnt(0)
	v_mfma_f32_32x32x16_bf16 v[80:95], v[104:107], v[108:111], v[80:95]
	ds_read_b128 v[96:99], v156 offset:8832
	ds_read_b128 v[100:103], v156 offset:128
	ds_read_b128 v[104:107], v156 offset:8864
	ds_read_b128 v[108:111], v156 offset:160
	s_waitcnt lgkmcnt(2)
	v_mfma_f32_32x32x16_bf16 v[80:95], v[96:99], v[100:103], v[80:95]
	s_waitcnt lgkmcnt(0)
	v_mfma_f32_32x32x16_bf16 v[80:95], v[104:107], v[108:111], v[80:95]
	ds_read_b128 v[96:99], v156 offset:8896
	ds_read_b128 v[100:103], v156 offset:192
	ds_read_b128 v[104:107], v156 offset:8928
	ds_read_b128 v[108:111], v156 offset:224
	v_add_u32_e32 v156, v138, v136
	s_waitcnt lgkmcnt(2)
	v_mfma_f32_32x32x16_bf16 v[80:95], v[96:99], v[100:103], v[80:95]
	v_cvt_pk_bf16_f32 v96, v0, v1
	v_cvt_pk_bf16_f32 v97, v2, v3
	v_cvt_pk_bf16_f32 v98, v4, v5
	v_cvt_pk_bf16_f32 v99, v6, v7
	ds_read2_b64 v[100:103], v137 offset1:2
	ds_read2_b64 v[180:183], v137 offset0:4 offset1:6
	ds_read2_b64 v[192:195], v137 offset0:16 offset1:18
	s_waitcnt lgkmcnt(3)
	v_mfma_f32_32x32x16_bf16 v[80:95], v[104:107], v[108:111], v[80:95]
	s_waitcnt lgkmcnt(2)
	v_mfma_f32_32x32x16_bf16 v[96:111], v[96:99], v[100:103], 0
	s_nop 9
	v_cndmask_b32_e64 v157, 0, v81, s[42:43]
	v_cndmask_b32_e64 v160, v82, 0, s[44:45]
	v_cndmask_b32_e64 v161, v83, 0, s[46:47]
	v_cndmask_b32_e64 v92, v92, 0, s[64:65]
	s_waitcnt lgkmcnt(1)
	v_mfma_f32_32x32x16_bf16 v[96:111], v[184:187], v[180:183], v[96:111]
	ds_read2_b64 v[180:183], v137 offset0:8 offset1:10
	v_cvt_pk_bf16_f32 v184, v24, v25
	v_cvt_pk_bf16_f32 v185, v26, v27
	v_cvt_pk_bf16_f32 v186, v28, v29
	v_cvt_pk_bf16_f32 v187, v30, v31
	s_waitcnt lgkmcnt(0)
	v_mfma_f32_32x32x16_bf16 v[96:111], v[188:191], v[180:183], v[96:111]
	ds_read2_b64 v[180:183], v137 offset0:12 offset1:14
	v_cvt_pk_bf16_f32 v188, v48, v49
	v_cvt_pk_bf16_f32 v189, v50, v51
	v_cvt_pk_bf16_f32 v190, v52, v53
	v_cvt_pk_bf16_f32 v191, v54, v55
	s_waitcnt lgkmcnt(0)
	v_mfma_f32_32x32x16_bf16 v[96:111], v[184:187], v[180:183], v[96:111]
	ds_read2_b64 v[180:183], v137 offset0:20 offset1:22
	v_cvt_pk_bf16_f32 v184, v64, v65
	v_cvt_pk_bf16_f32 v185, v66, v67
	v_cvt_pk_bf16_f32 v186, v68, v69
	v_cvt_pk_bf16_f32 v187, v70, v71
	v_mfma_f32_32x32x16_bf16 v[96:111], v[188:191], v[192:195], v[96:111]
	ds_read_b128 v[188:191], v32 offset:37952
	ds_read_b128 v[192:195], v32 offset:37984
	ds_read_b128 v[200:203], v32 offset:37888
	ds_read_b128 v[204:207], v32 offset:37920
	ds_read2_b64 v[208:211], v137 offset0:24 offset1:26
	s_waitcnt lgkmcnt(4)
	v_pk_mul_f32 v[10:11], v[10:11], v[190:191]
	s_waitcnt lgkmcnt(3)
	v_pk_mul_f32 v[14:15], v[14:15], v[194:195]
	s_waitcnt lgkmcnt(1)
	v_pk_mul_f32 v[6:7], v[6:7], v[206:207]
	v_mfma_f32_32x32x16_bf16 v[96:111], v[196:199], v[180:183], v[96:111]
	ds_read_b128 v[180:183], v151 offset:17408
	v_mul_f32_e64 v2, v2, v202
	v_mul_f32_e64 v3, v3, v203
	v_mul_f32_e64 v12, v12, v192
	v_mul_f32_e64 v13, v13, v193
	v_pk_mul_f32 v[8:9], v[8:9], v[188:189]
	v_pk_mul_f32 v[4:5], v[4:5], v[204:205]
	v_pk_mul_f32 v[0:1], v[0:1], v[200:201]
	s_waitcnt lgkmcnt(1)
	v_mfma_f32_32x32x16_bf16 v[96:111], v[184:187], v[208:211], v[96:111]
	ds_read_b128 v[184:187], v156 offset:27648
	ds_read_b128 v[188:191], v151 offset:17440
	ds_read_b128 v[192:195], v156 offset:27680
	ds_read_b128 v[196:199], v32 offset:38080
	ds_read_b128 v[200:203], v32 offset:38112
	v_cvt_pk_bf16_f32 v208, v72, v73
	v_cvt_pk_bf16_f32 v209, v74, v75
	v_cndmask_b32_e64 v156, v80, 0, s[40:41]
	s_waitcnt lgkmcnt(1)
	v_pk_mul_f32 v[26:27], v[26:27], v[198:199]
	s_waitcnt lgkmcnt(0)
	v_pk_mul_f32 v[30:31], v[30:31], v[202:203]
	v_pk_mul_f32 v[28:29], v[28:29], v[200:201]
	v_mfma_f32_32x32x16_bf16 v[0:15], v[180:183], v[184:187], v[0:15]
	ds_read_b128 v[180:183], v32 offset:38048
	ds_read_b128 v[204:207], v32 offset:38016
	ds_read_b128 v[210:213], v151 offset:19968
	v_mul_f32_e64 v24, v24, v196
	v_mul_f32_e64 v25, v25, v197
	v_cndmask_b32_e64 v156, v156, v80, s[42:43]
	s_waitcnt lgkmcnt(2)
	v_pk_mul_f32 v[22:23], v[22:23], v[182:183]
	s_waitcnt lgkmcnt(1)
	v_pk_mul_f32 v[18:19], v[18:19], v[206:207]
	v_pk_mul_f32 v[20:21], v[20:21], v[180:181]
	v_pk_mul_f32 v[16:17], v[16:17], v[204:205]
	v_mfma_f32_32x32x16_bf16 v[0:15], v[188:191], v[192:195], v[0:15]
	ds_read_b128 v[180:183], v151 offset:20000
	ds_read_b128 v[188:191], v32 offset:38208
	ds_read_b128 v[196:199], v32 offset:38240
	ds_read_b128 v[200:203], v32 offset:38144
	ds_read_b128 v[204:207], v32 offset:38176
	s_waitcnt lgkmcnt(3)
	v_pk_mul_f32 v[58:59], v[58:59], v[190:191]
	s_waitcnt lgkmcnt(2)
	v_pk_mul_f32 v[62:63], v[62:63], v[198:199]
	s_waitcnt lgkmcnt(0)
	v_pk_mul_f32 v[54:55], v[54:55], v[206:207]
	v_mfma_f32_32x32x16_bf16 v[16:31], v[210:213], v[184:187], v[16:31]
	ds_read_b128 v[212:215], v151 offset:22528
	v_mul_f32_e64 v50, v50, v202
	v_mul_f32_e64 v51, v51, v203
	v_mul_f32_e64 v60, v60, v196
	v_mul_f32_e64 v61, v61, v197
	v_pk_mul_f32 v[56:57], v[56:57], v[188:189]
	v_pk_mul_f32 v[52:53], v[52:53], v[204:205]
	v_pk_mul_f32 v[48:49], v[48:49], v[200:201]
	v_cvt_pk_bf16_f32 v210, v76, v77
	v_mfma_f32_32x32x16_bf16 v[16:31], v[180:183], v[192:195], v[16:31]
	ds_read_b128 v[180:183], v151 offset:22560
	ds_read_b128 v[188:191], v32 offset:38336
	ds_read_b128 v[196:199], v32 offset:38368
	v_cvt_pk_bf16_f32 v211, v78, v79
	s_waitcnt lgkmcnt(1)
	v_pk_mul_f32 v[74:75], v[74:75], v[190:191]
	s_waitcnt lgkmcnt(0)
	v_pk_mul_f32 v[78:79], v[78:79], v[198:199]
	v_mfma_f32_32x32x16_bf16 v[48:63], v[212:215], v[184:187], v[48:63]
	ds_read2_b64 v[200:203], v137 offset0:28 offset1:30
	ds_read_b128 v[204:207], v32 offset:38272
	ds_read_b128 v[212:215], v32 offset:38304
	ds_read_b128 v[216:219], v151 offset:25088
	v_mul_f32_e64 v76, v76, v196
	v_mul_f32_e64 v77, v77, v197
	v_pk_mul_f32 v[72:73], v[72:73], v[188:189]
	s_waitcnt lgkmcnt(2)
	v_pk_mul_f32 v[66:67], v[66:67], v[206:207]
	s_waitcnt lgkmcnt(1)
	v_pk_mul_f32 v[70:71], v[70:71], v[214:215]
	v_pk_mul_f32 v[68:69], v[68:69], v[212:213]
	v_mfma_f32_32x32x16_bf16 v[48:63], v[180:183], v[192:195], v[48:63]
	v_mul_f32_e64 v64, v64, v204
	v_mul_f32_e64 v65, v65, v205
	ds_read_b128 v[180:183], v151 offset:25120
	s_waitcnt lgkmcnt(1)
	v_mfma_f32_32x32x16_bf16 v[64:79], v[216:219], v[184:187], v[64:79]
	v_cndmask_b32_e64 v184, v84, 0, s[48:49]
	v_add_u32_e32 v84, 0x6800, v138
	ds_read2_b64 v[80:83], v84 offset0:128 offset1:130
	v_cndmask_b32_e64 v185, v85, 0, s[50:51]
	v_cndmask_b32_e64 v186, v90, 0, s[60:61]
	v_cndmask_b32_e64 v187, v91, 0, s[62:63]
	v_cvt_pk_bf16_f32 v90, v184, v185
	v_mfma_f32_32x32x16_bf16 v[96:111], v[208:211], v[200:203], v[96:111]
	s_waitcnt lgkmcnt(1)
	v_mfma_f32_32x32x16_bf16 v[64:79], v[180:183], v[192:195], v[64:79]
	v_cndmask_b32_e64 v180, v86, 0, s[52:53]
	v_cndmask_b32_e64 v181, v87, 0, s[54:55]
	v_cndmask_b32_e64 v182, v88, 0, s[56:57]
	v_cndmask_b32_e64 v183, v89, 0, s[58:59]
	ds_read2_b64 v[84:87], v84 offset0:132 offset1:134
	v_cvt_pk_bf16_f32 v88, v156, v157
	v_cvt_pk_bf16_f32 v89, v160, v161
	v_cvt_pk_bf16_f32 v91, v180, v181
	s_waitcnt lgkmcnt(1)
	s_nop 0
	v_mfma_f32_32x32x16_bf16 v[96:111], v[80:83], v[88:91], v[96:111]
	v_cndmask_b32_e64 v82, v93, 0, s[66:67]
	v_cndmask_b32_e64 v83, v94, 0, s[68:69]
	v_cndmask_b32_e64 v88, v95, 0, s[70:71]
	v_cvt_pk_bf16_f32 v80, v182, v183
	v_cvt_pk_bf16_f32 v81, v186, v187
	v_cvt_pk_bf16_f32 v82, v92, v82
	v_cvt_pk_bf16_f32 v83, v83, v88
	s_waitcnt lgkmcnt(0)
	s_nop 0
	v_mfma_f32_32x32x16_bf16 v[96:111], v[84:87], v[80:83], v[96:111]
	s_setprio 0
	v_add_u32_e32 v80, s31, v133
	v_cndmask_b32_e32 v80, v148, v80, vcc
	v_add_u32_e32 v80, s97, v80
	v_ashrrev_i32_e32 v81, 31, v80
	v_lshlrev_b64 v[80:81], 11, v[80:81]
	s_add_i32 s31, s31, 32
	v_lshl_add_u64 v[80:81], v[126:127], 0, v[80:81]
	v_subrev_u32_e32 v148, 32, v148
	s_cmp_eq_u32 s30, s25
	v_subrev_u32_e32 v149, 32, v149
	s_nop 0
	global_store_dwordx4 v[80:81], v[96:99], off
	global_store_dwordx4 v[80:81], v[100:103], off offset:32
	global_store_dwordx4 v[80:81], v[104:107], off offset:64
	global_store_dwordx4 v[80:81], v[108:111], off offset:96
	s_barrier
	s_cbranch_scc1 .LBB0_789
	s_waitcnt vmcnt(4)
	v_lshl_or_b32 v113, v236, 16, v113
	v_lshl_or_b32 v34, v237, 16, v34
	v_lshl_or_b32 v115, v238, 16, v115
	v_lshl_or_b32 v35, v239, 16, v35
	v_lshl_or_b32 v134, v240, 16, v134
	v_lshl_or_b32 v36, v241, 16, v36
	v_lshl_or_b32 v140, v242, 16, v140
	v_lshl_or_b32 v37, v243, 16, v37
	v_lshl_or_b32 v38, v244, 16, v38
	v_lshl_or_b32 v152, v245, 16, v152
	v_lshl_or_b32 v39, v246, 16, v39
	v_lshl_or_b32 v153, v247, 16, v153
	v_lshl_or_b32 v40, v248, 16, v40
	v_lshl_or_b32 v154, v249, 16, v154
	v_lshl_or_b32 v155, v250, 16, v155
	v_lshl_or_b32 v41, v251, 16, v41
.LBB0_785:
	v_max_f32_e32 v80, 0xda24260, v44
	s_mov_b32 s21, 0x3f317217
	v_lshlrev_b32_e32 v101, 16, v113
	v_log_f32_e32 v80, v80
	v_mul_f32_e32 v101, 0x3db504f3, v101
	v_lshlrev_b32_e32 v103, 16, v115
	v_mul_f32_e32 v103, 0x3db504f3, v103
	v_mul_f32_e32 v81, 0x3f317217, v80
	v_fma_f32 v81, v80, s21, -v81
	v_fmac_f32_e32 v81, 0x3377d1cf, v80
	v_fmac_f32_e32 v81, 0x3f317217, v80
	v_lshlrev_b32_e32 v105, 16, v134
	v_mul_f32_e32 v105, 0x3db504f3, v105
	v_add_f32_e32 v80, 0, v81
	v_max_f32_e32 v81, 0xda24260, v45
	v_lshlrev_b32_e32 v107, 16, v140
	v_log_f32_e32 v81, v81
	v_mul_f32_e32 v107, 0x3db504f3, v107
	v_lshlrev_b32_e32 v109, 16, v152
	v_mul_f32_e32 v109, 0x3db504f3, v109
	v_mul_f32_e32 v82, 0x3f317217, v81
	v_fma_f32 v82, v81, s21, -v82
	v_fmac_f32_e32 v82, 0x3377d1cf, v81
	v_fmac_f32_e32 v82, 0x3f317217, v81
	v_lshlrev_b32_e32 v111, 16, v153
	v_mul_f32_e32 v111, 0x3db504f3, v111
	v_add_f32_e32 v86, v80, v82
	v_max_f32_e32 v81, 0xda24260, v46
	v_lshlrev_b32_e32 v157, 16, v154
	v_mul_f32_e32 v157, 0x3db504f3, v157
	v_log_f32_e32 v81, v81
	v_lshlrev_b32_e32 v161, 16, v155
	v_mul_f32_e32 v161, 0x3db504f3, v161
	v_mul_f32_e32 v82, 0x3f317217, v81
	v_fma_f32 v82, v81, s21, -v82
	v_fmac_f32_e32 v82, 0x3377d1cf, v81
	v_fmac_f32_e32 v82, 0x3f317217, v81
	v_add_f32_e32 v87, v86, v82
	v_max_f32_e32 v81, 0xda24260, v47
	v_log_f32_e32 v81, v81
	s_nop 0
	v_mul_f32_e32 v82, 0x3f317217, v81
	v_fma_f32 v82, v81, s21, -v82
	v_fmac_f32_e32 v82, 0x3377d1cf, v81
	v_fmac_f32_e32 v82, 0x3f317217, v81
	v_add_f32_e32 v88, v87, v82
	v_max_f32_e32 v81, 0xda24260, v118
	v_log_f32_e32 v81, v81
	s_nop 0
	v_mul_f32_e32 v82, 0x3f317217, v81
	v_fma_f32 v82, v81, s21, -v82
	v_fmac_f32_e32 v82, 0x3377d1cf, v81
	v_fmac_f32_e32 v82, 0x3f317217, v81
	v_add_f32_e32 v89, v88, v82
	v_max_f32_e32 v81, 0xda24260, v119
	v_log_f32_e32 v81, v81
	s_nop 0
	v_mul_f32_e32 v82, 0x3f317217, v81
	v_fma_f32 v82, v81, s21, -v82
	v_fmac_f32_e32 v82, 0x3377d1cf, v81
	v_fmac_f32_e32 v82, 0x3f317217, v81
	v_add_f32_e32 v90, v89, v82
	v_max_f32_e32 v81, 0xda24260, v120
	v_log_f32_e32 v81, v81
	s_nop 0
	v_mul_f32_e32 v82, 0x3f317217, v81
	v_fma_f32 v82, v81, s21, -v82
	v_fmac_f32_e32 v82, 0x3377d1cf, v81
	v_fmac_f32_e32 v82, 0x3f317217, v81
	v_add_f32_e32 v91, v90, v82
	v_max_f32_e32 v81, 0xda24260, v121
	v_log_f32_e32 v81, v81
	s_nop 0
	v_mul_f32_e32 v82, 0x3f317217, v81
	v_fma_f32 v82, v81, s21, -v82
	v_fmac_f32_e32 v82, 0x3377d1cf, v81
	v_fmac_f32_e32 v82, 0x3f317217, v81
	v_add_f32_e32 v92, v91, v82
	v_max_f32_e32 v81, 0xda24260, v122
	v_log_f32_e32 v81, v81
	s_nop 0
	v_mul_f32_e32 v82, 0x3f317217, v81
	v_fma_f32 v82, v81, s21, -v82
	v_fmac_f32_e32 v82, 0x3377d1cf, v81
	v_fmac_f32_e32 v82, 0x3f317217, v81
	v_add_f32_e32 v93, v92, v82
	v_max_f32_e32 v81, 0xda24260, v123
	v_log_f32_e32 v81, v81
	s_nop 0
	v_mul_f32_e32 v82, 0x3f317217, v81
	v_fma_f32 v82, v81, s21, -v82
	v_fmac_f32_e32 v82, 0x3377d1cf, v81
	v_fmac_f32_e32 v82, 0x3f317217, v81
	v_add_f32_e32 v94, v93, v82
	v_max_f32_e32 v81, 0xda24260, v124
	v_log_f32_e32 v81, v81
	s_nop 0
	v_mul_f32_e32 v82, 0x3f317217, v81
	v_fma_f32 v82, v81, s21, -v82
	v_fmac_f32_e32 v82, 0x3377d1cf, v81
	v_fmac_f32_e32 v82, 0x3f317217, v81
	v_add_f32_e32 v95, v94, v82
	v_max_f32_e32 v81, 0xda24260, v125
	v_log_f32_e32 v81, v81
	s_nop 0
	v_mul_f32_e32 v82, 0x3f317217, v81
	v_fma_f32 v82, v81, s21, -v82
	v_fmac_f32_e32 v82, 0x3377d1cf, v81
	v_fmac_f32_e32 v82, 0x3f317217, v81
	v_add_f32_e32 v96, v95, v82
	v_max_f32_e32 v81, 0xda24260, v128
	v_log_f32_e32 v81, v81
	s_nop 0
	v_mul_f32_e32 v82, 0x3f317217, v81
	v_fma_f32 v82, v81, s21, -v82
	v_fmac_f32_e32 v82, 0x3377d1cf, v81
	v_fmac_f32_e32 v82, 0x3f317217, v81
	v_add_f32_e32 v97, v96, v82
	v_max_f32_e32 v81, 0xda24260, v129
	v_log_f32_e32 v81, v81
	s_nop 0
	v_mul_f32_e32 v82, 0x3f317217, v81
	v_fma_f32 v82, v81, s21, -v82
	v_fmac_f32_e32 v82, 0x3377d1cf, v81
	v_fmac_f32_e32 v82, 0x3f317217, v81
	v_add_f32_e32 v98, v97, v82
	v_max_f32_e32 v81, 0xda24260, v130
	v_log_f32_e32 v81, v81
	s_nop 0
	v_mul_f32_e32 v82, 0x3f317217, v81
	v_fma_f32 v82, v81, s21, -v82
	v_fmac_f32_e32 v82, 0x3377d1cf, v81
	v_fmac_f32_e32 v82, 0x3f317217, v81
	v_add_f32_e32 v99, v98, v82
	s_waitcnt vmcnt(4)
	v_max_f32_e32 v81, 0xda24260, v131
	v_log_f32_e32 v81, v81
	s_nop 0
	v_mul_f32_e32 v82, 0x3f317217, v81
	v_fma_f32 v82, v81, s21, -v82
	v_fmac_f32_e32 v82, 0x3377d1cf, v81
	v_fmac_f32_e32 v82, 0x3f317217, v81
	v_add_f32_e32 v83, v99, v82
	v_mov_b32_e32 v82, v83
	v_mov_b32_e32 v84, v83
	s_nop 1
	v_permlane32_swap_b32_e32 v82, v84
	v_cndmask_b32_e64 v85, v82, 0, s[38:39]
	v_add_f32_e32 v100, v80, v85
	v_mul_f32_e32 v102, 0x3fb8aa3b, v100
	v_exp_f32_e32 v102, v102
	v_pk_add_f32 v[80:81], v[44:45], 1.0 op_sel_hi:[1,0] neg_lo:[1,0] neg_hi:[1,0]
	v_pk_add_f32 v[82:83], v[82:83], v[84:85]
	v_mul_f32_e32 v101, v101, v102
	v_cvt_pk_bf16_f32 v101, v101, s0
	ds_write_b16 v139, v101
	v_min_f32_e64 v101, -v100, s96
	v_mul_f32_e32 v101, 0x3fb8aa3b, v101
	v_exp_f32_e32 v101, v101
	v_sub_f32_e32 v84, v82, v100
	v_mul_f32_e32 v84, 0x3fb8aa3b, v84
	v_exp_f32_e32 v84, v84
	v_mul_f32_e32 v101, v80, v101
	v_cvt_pk_bf16_f32 v101, v101, s0
	ds_write_b16 v139, v101 offset:8704
	v_add_f32_e32 v101, v86, v85
	v_mul_f32_e32 v102, 0x3fb8aa3b, v101
	v_exp_f32_e32 v102, v102
	v_and_b32_e32 v86, 0xffff0000, v113
	v_mul_f32_e32 v86, 0x3db504f3, v86
	v_mul_f32_e32 v86, v86, v102
	v_cvt_pk_bf16_f32 v86, v86, s0
	ds_write_b16 v139, v86 offset:272
	v_min_f32_e64 v86, -v101, s96
	v_add_f32_e32 v102, v87, v85
	v_mul_f32_e32 v86, 0x3fb8aa3b, v86
	v_mul_f32_e32 v104, 0x3fb8aa3b, v102
	v_exp_f32_e32 v86, v86
	v_exp_f32_e32 v104, v104
	v_mul_f32_e32 v86, v81, v86
	v_mul_f32_e32 v103, v103, v104
	v_cvt_pk_bf16_f32 v86, v86, s0
	v_cvt_pk_bf16_f32 v103, v103, s0
	ds_write_b16 v139, v86 offset:8976
	ds_write_b16 v141, v103
	v_min_f32_e64 v103, -v102, s96
	v_mul_f32_e32 v103, 0x3fb8aa3b, v103
	v_exp_f32_e32 v103, v103
	v_pk_add_f32 v[86:87], v[46:47], 1.0 op_sel_hi:[1,0] neg_lo:[1,0] neg_hi:[1,0]
	s_nop 0
	v_mul_f32_e32 v103, v86, v103
	v_cvt_pk_bf16_f32 v103, v103, s0
	ds_write_b16 v141, v103 offset:8704
	v_add_f32_e32 v103, v88, v85
	v_mul_f32_e32 v104, 0x3fb8aa3b, v103
	v_exp_f32_e32 v104, v104
	v_and_b32_e32 v88, 0xffff0000, v115
	v_mul_f32_e32 v88, 0x3db504f3, v88
	v_mul_f32_e32 v88, v88, v104
	v_cvt_pk_bf16_f32 v88, v88, s0
	ds_write_b16 v139, v88 offset:816
	v_min_f32_e64 v88, -v103, s96
	v_add_f32_e32 v104, v89, v85
	v_mul_f32_e32 v88, 0x3fb8aa3b, v88
	v_mul_f32_e32 v106, 0x3fb8aa3b, v104
	v_exp_f32_e32 v88, v88
	v_exp_f32_e32 v106, v106
	v_mul_f32_e32 v88, v87, v88
	v_mul_f32_e32 v105, v105, v106
	v_cvt_pk_bf16_f32 v88, v88, s0
	v_cvt_pk_bf16_f32 v105, v105, s0
	ds_write_b16 v139, v88 offset:9520
	ds_write_b16 v142, v105
	v_min_f32_e64 v105, -v104, s96
	v_mul_f32_e32 v105, 0x3fb8aa3b, v105
	v_exp_f32_e32 v105, v105
	v_pk_add_f32 v[88:89], v[118:119], 1.0 op_sel_hi:[1,0] neg_lo:[1,0] neg_hi:[1,0]
	s_nop 0
	v_mul_f32_e32 v105, v88, v105
	v_cvt_pk_bf16_f32 v105, v105, s0
	ds_write_b16 v142, v105 offset:8704
	v_add_f32_e32 v105, v90, v85
	v_mul_f32_e32 v106, 0x3fb8aa3b, v105
	v_exp_f32_e32 v106, v106
	v_and_b32_e32 v90, 0xffff0000, v134
	v_mul_f32_e32 v90, 0x3db504f3, v90
	v_mul_f32_e32 v90, v90, v106
	v_cvt_pk_bf16_f32 v90, v90, s0
	ds_write_b16 v139, v90 offset:1360
	v_min_f32_e64 v90, -v105, s96
	v_add_f32_e32 v106, v91, v85
	v_mul_f32_e32 v90, 0x3fb8aa3b, v90
	v_mul_f32_e32 v108, 0x3fb8aa3b, v106
	v_exp_f32_e32 v90, v90
	v_exp_f32_e32 v108, v108
	v_mul_f32_e32 v90, v89, v90
	v_mul_f32_e32 v107, v107, v108
	v_cvt_pk_bf16_f32 v90, v90, s0
	v_cvt_pk_bf16_f32 v107, v107, s0
	ds_write_b16 v139, v90 offset:10064
	ds_write_b16 v143, v107
	v_min_f32_e64 v107, -v106, s96
	v_mul_f32_e32 v107, 0x3fb8aa3b, v107
	v_exp_f32_e32 v107, v107
	v_pk_add_f32 v[90:91], v[120:121], 1.0 op_sel_hi:[1,0] neg_lo:[1,0] neg_hi:[1,0]
	s_nop 0
	v_mul_f32_e32 v107, v90, v107
	v_cvt_pk_bf16_f32 v107, v107, s0
	ds_write_b16 v143, v107 offset:8704
	v_add_f32_e32 v107, v92, v85
	v_mul_f32_e32 v108, 0x3fb8aa3b, v107
	v_exp_f32_e32 v108, v108
	v_and_b32_e32 v92, 0xffff0000, v140
	v_mul_f32_e32 v92, 0x3db504f3, v92
	v_mul_f32_e32 v92, v92, v108
	v_cvt_pk_bf16_f32 v92, v92, s0
	ds_write_b16 v139, v92 offset:1904
	v_min_f32_e64 v92, -v107, s96
	v_add_f32_e32 v108, v93, v85
	v_mul_f32_e32 v92, 0x3fb8aa3b, v92
	v_mul_f32_e32 v110, 0x3fb8aa3b, v108
	v_exp_f32_e32 v92, v92
	v_exp_f32_e32 v110, v110
	v_mul_f32_e32 v92, v91, v92
	v_mul_f32_e32 v109, v109, v110
	v_cvt_pk_bf16_f32 v92, v92, s0
	v_cvt_pk_bf16_f32 v109, v109, s0
	ds_write_b16 v139, v92 offset:10608
	ds_write_b16 v144, v109
	v_min_f32_e64 v109, -v108, s96
	v_mul_f32_e32 v109, 0x3fb8aa3b, v109
	v_exp_f32_e32 v109, v109
	v_pk_add_f32 v[92:93], v[122:123], 1.0 op_sel_hi:[1,0] neg_lo:[1,0] neg_hi:[1,0]
	s_nop 0
	v_mul_f32_e32 v109, v92, v109
	v_cvt_pk_bf16_f32 v109, v109, s0
	ds_write_b16 v144, v109 offset:8704
	v_add_f32_e32 v109, v94, v85
	v_mul_f32_e32 v110, 0x3fb8aa3b, v109
	v_exp_f32_e32 v110, v110
	v_and_b32_e32 v94, 0xffff0000, v152
	v_mul_f32_e32 v94, 0x3db504f3, v94
	v_mul_f32_e32 v94, v94, v110
	v_cvt_pk_bf16_f32 v94, v94, s0
	ds_write_b16 v139, v94 offset:2448
	v_min_f32_e64 v94, -v109, s96
	v_add_f32_e32 v110, v95, v85
	v_mul_f32_e32 v94, 0x3fb8aa3b, v94
	v_mul_f32_e32 v156, 0x3fb8aa3b, v110
	v_exp_f32_e32 v94, v94
	v_exp_f32_e32 v156, v156
	v_mul_f32_e32 v94, v93, v94
	v_mul_f32_e32 v111, v111, v156
	v_cvt_pk_bf16_f32 v94, v94, s0
	v_cvt_pk_bf16_f32 v111, v111, s0
	ds_write_b16 v139, v94 offset:11152
	ds_write_b16 v145, v111
	v_min_f32_e64 v111, -v110, s96
	v_mul_f32_e32 v111, 0x3fb8aa3b, v111
	v_exp_f32_e32 v111, v111
	v_pk_add_f32 v[94:95], v[124:125], 1.0 op_sel_hi:[1,0] neg_lo:[1,0] neg_hi:[1,0]
	s_nop 0
	v_mul_f32_e32 v111, v94, v111
	v_cvt_pk_bf16_f32 v111, v111, s0
	ds_write_b16 v145, v111 offset:8704
	v_add_f32_e32 v111, v96, v85
	v_mul_f32_e32 v156, 0x3fb8aa3b, v111
	v_exp_f32_e32 v156, v156
	v_and_b32_e32 v96, 0xffff0000, v153
	v_mul_f32_e32 v96, 0x3db504f3, v96
	v_mul_f32_e32 v96, v96, v156
	v_cvt_pk_bf16_f32 v96, v96, s0
	ds_write_b16 v139, v96 offset:2992
	v_min_f32_e64 v96, -v111, s96
	v_add_f32_e32 v156, v97, v85
	v_mul_f32_e32 v96, 0x3fb8aa3b, v96
	v_mul_f32_e32 v160, 0x3fb8aa3b, v156
	v_exp_f32_e32 v96, v96
	v_exp_f32_e32 v160, v160
	v_mul_f32_e32 v96, v95, v96
	v_mul_f32_e32 v157, v157, v160
	v_cvt_pk_bf16_f32 v96, v96, s0
	v_cvt_pk_bf16_f32 v157, v157, s0
	ds_write_b16 v139, v96 offset:11696
	ds_write_b16 v146, v157
	v_min_f32_e64 v157, -v156, s96
	v_mul_f32_e32 v157, 0x3fb8aa3b, v157
	v_exp_f32_e32 v157, v157
	v_pk_add_f32 v[96:97], v[128:129], 1.0 op_sel_hi:[1,0] neg_lo:[1,0] neg_hi:[1,0]
	s_nop 0
	v_mul_f32_e32 v157, v96, v157
	v_cvt_pk_bf16_f32 v157, v157, s0
	ds_write_b16 v146, v157 offset:8704
	v_add_f32_e32 v157, v98, v85
	v_mul_f32_e32 v160, 0x3fb8aa3b, v157
	v_exp_f32_e32 v160, v160
	v_and_b32_e32 v98, 0xffff0000, v154
	v_mul_f32_e32 v98, 0x3db504f3, v98
	v_mul_f32_e32 v98, v98, v160
	v_add_f32_e32 v160, v99, v85
	v_sub_f32_e32 v85, v82, v101
	v_mul_f32_e32 v85, 0x3fb8aa3b, v85
	v_exp_f32_e32 v85, v85
	v_cvt_pk_bf16_f32 v98, v98, s0
	ds_write_b16 v139, v98 offset:3536
	v_min_f32_e64 v98, -v157, s96
	v_pk_mul_f32 v[80:81], v[80:81], v[84:85]
	v_sub_f32_e32 v84, v82, v102
	v_sub_f32_e32 v85, v82, v103
	v_mul_f32_e32 v84, 0x3fb8aa3b, v84
	v_mul_f32_e32 v85, 0x3fb8aa3b, v85
	v_exp_f32_e32 v84, v84
	v_exp_f32_e32 v85, v85
	v_mul_f32_e32 v98, 0x3fb8aa3b, v98
	v_mul_f32_e32 v180, 0x3fb8aa3b, v160
	v_exp_f32_e32 v98, v98
	v_pk_mul_f32 v[86:87], v[86:87], v[84:85]
	v_sub_f32_e32 v84, v82, v104
	v_sub_f32_e32 v85, v82, v105
	v_mul_f32_e32 v84, 0x3fb8aa3b, v84
	v_mul_f32_e32 v85, 0x3fb8aa3b, v85
	v_exp_f32_e32 v84, v84
	v_exp_f32_e32 v85, v85
	v_exp_f32_e32 v180, v180
	v_mul_f32_e32 v98, v97, v98
	v_cvt_pk_bf16_f32 v98, v98, s0
	v_pk_mul_f32 v[100:101], v[88:89], v[84:85]
	v_sub_f32_e32 v84, v82, v106
	v_sub_f32_e32 v85, v82, v107
	v_mul_f32_e32 v84, 0x3fb8aa3b, v84
	v_mul_f32_e32 v85, 0x3fb8aa3b, v85
	v_exp_f32_e32 v84, v84
	v_exp_f32_e32 v85, v85
	v_mul_f32_e32 v161, v161, v180
	v_cvt_pk_bf16_f32 v161, v161, s0
	ds_write_b16 v139, v98 offset:12240
	v_pk_mul_f32 v[102:103], v[90:91], v[84:85]
	v_sub_f32_e32 v84, v82, v108
	v_sub_f32_e32 v85, v82, v109
	v_mul_f32_e32 v84, 0x3fb8aa3b, v84
	v_mul_f32_e32 v85, 0x3fb8aa3b, v85
	v_exp_f32_e32 v84, v84
	v_exp_f32_e32 v85, v85
	ds_write_b16 v147, v161
	v_min_f32_e64 v161, -v160, s96
	v_mul_f32_e32 v161, 0x3fb8aa3b, v161
	v_pk_mul_f32 v[88:89], v[92:93], v[84:85]
	v_sub_f32_e32 v84, v82, v110
	v_sub_f32_e32 v85, v82, v111
	v_mul_f32_e32 v84, 0x3fb8aa3b, v84
	v_mul_f32_e32 v85, 0x3fb8aa3b, v85
	v_exp_f32_e32 v84, v84
	v_exp_f32_e32 v85, v85
	v_exp_f32_e32 v161, v161
	v_pk_add_f32 v[98:99], v[130:131], 1.0 op_sel_hi:[1,0] neg_lo:[1,0] neg_hi:[1,0]
	v_cvt_pk_bf16_f32 v88, v88, v89
	v_pk_mul_f32 v[90:91], v[94:95], v[84:85]
	v_sub_f32_e32 v84, v82, v156
	v_sub_f32_e32 v85, v82, v157
	v_mul_f32_e32 v84, 0x3fb8aa3b, v84
	v_mul_f32_e32 v85, 0x3fb8aa3b, v85
	v_exp_f32_e32 v84, v84
	v_exp_f32_e32 v85, v85
	v_mul_f32_e32 v94, 0x3fb8aa3b, v83
	v_exp_f32_e32 v94, v94
	v_mul_f32_e32 v161, v98, v161
	v_pk_mul_f32 v[92:93], v[96:97], v[84:85]
	v_and_b32_e32 v85, 0xffff0000, v155
	v_mul_f32_e32 v85, 0x3db504f3, v85
	v_mul_f32_e32 v85, v85, v94
	v_cvt_pk_bf16_f32 v161, v161, s0
	v_cvt_pk_bf16_f32 v85, v85, s0
	ds_write_b16 v147, v161 offset:8704
	ds_write_b16 v139, v85 offset:4080
	v_min_f32_e64 v85, -v83, s96
	v_mul_f32_e32 v85, 0x3fb8aa3b, v85
	v_exp_f32_e32 v85, v85
	v_sub_f32_e32 v84, v82, v160
	v_sub_f32_e32 v83, v82, v83
	v_mul_f32_e32 v84, 0x3fb8aa3b, v84
	v_mul_f32_e32 v85, v99, v85
	v_cvt_pk_bf16_f32 v85, v85, s0
	v_mul_f32_e32 v83, 0x3fb8aa3b, v83
	v_exp_f32_e32 v84, v84
	ds_write_b16 v139, v85 offset:12784
	v_exp_f32_e32 v85, v83
	v_cvt_pk_bf16_f32 v89, v90, v91
	v_cvt_pk_bf16_f32 v90, v92, v93
	v_pk_mul_f32 v[94:95], v[98:99], v[84:85]
	v_cvt_pk_bf16_f32 v84, v80, v81
	v_cvt_pk_bf16_f32 v85, v86, v87
	v_cvt_pk_bf16_f32 v86, v100, v101
	v_cvt_pk_bf16_f32 v87, v102, v103
	v_cvt_pk_bf16_f32 v91, v94, v95
	ds_write_b128 v135, v[84:87] offset:17408
	ds_write_b128 v135, v[88:91] offset:17424
	ds_write_b128 v135, v[34:37] offset:27648
	ds_write_b128 v135, v[38:41] offset:27664
	s_and_saveexec_b64 s[74:75], s[38:39]
	s_cbranch_execz .LBB0_787
	v_mul_f32_e32 v80, 0x3fb8aa3b, v82
	v_exp_f32_e32 v80, v80
	ds_write_b32 v150, v80 offset:37888
.LBB0_787:
	s_or_b64 exec, exec, s[74:75]
	s_add_i32 s25, s25, 1
	v_readlane_b32 s74, v232, 17
	v_readlane_b32 s76, v232, 19
	s_cmp_ge_u32 s25, s30
	v_readlane_b32 s75, v232, 18
	v_readlane_b32 s77, v232, 20
	s_cbranch_scc1 .LBB0_784
	v_add_u32_e32 v226, s31, v32
	v_add_u32_e32 v227, 32, v226
	v_cndmask_b32_e32 v220, v149, v227, vcc
	v_add_u32_e32 v220, s97, v220
	v_add_u32_e32 v222, s24, v220
	v_ashrrev_i32_e32 v221, 31, v220
	v_lshlrev_b64 v[220:221], 9, v[220:221]
	v_ashrrev_i32_e32 v223, 31, v222
	v_lshl_add_u64 v[220:221], v[220:221], 0, v[42:43]
	v_lshlrev_b64 v[222:223], 9, v[222:223]
	v_lshl_add_u64 v[224:225], v[220:221], 2, s[36:37]
	v_lshl_add_u64 v[222:223], v[222:223], 0, v[42:43]
	global_load_dword v44, v[224:225], off
	v_lshl_add_u64 v[224:225], v[222:223], 2, s[36:37]
	v_lshlrev_b64 v[220:221], 1, v[220:221]
	global_load_dword v45, v[224:225], off
	v_lshl_add_u64 v[224:225], s[28:29], 0, v[220:221]
	v_lshlrev_b64 v[222:223], 1, v[222:223]
	v_lshl_add_u64 v[220:221], s[0:1], 0, v[220:221]
	global_load_ushort v34, v[220:221], off
	v_lshl_add_u64 v[220:221], s[0:1], 0, v[222:223]
	global_load_ushort v237, v[220:221], off
	v_add_u32_e32 v220, 34, v226
	v_xad_u32 v221, v227, -3, s27
	v_cndmask_b32_e32 v220, v221, v220, vcc
	v_add_u32_e32 v220, s97, v220
	global_load_ushort v113, v[224:225], off
	v_lshl_add_u64 v[224:225], s[28:29], 0, v[222:223]
	v_add_u32_e32 v222, s24, v220
	v_ashrrev_i32_e32 v221, 31, v220
	v_lshlrev_b64 v[220:221], 9, v[220:221]
	v_ashrrev_i32_e32 v223, 31, v222
	v_lshl_add_u64 v[220:221], v[220:221], 0, v[42:43]
	v_lshlrev_b64 v[222:223], 9, v[222:223]
	global_load_ushort v236, v[224:225], off
	v_lshl_add_u64 v[224:225], v[220:221], 2, s[36:37]
	v_lshl_add_u64 v[222:223], v[222:223], 0, v[42:43]
	global_load_dword v46, v[224:225], off
	v_lshl_add_u64 v[224:225], v[222:223], 2, s[36:37]
	v_lshlrev_b64 v[220:221], 1, v[220:221]
	global_load_dword v47, v[224:225], off
	v_lshl_add_u64 v[224:225], s[28:29], 0, v[220:221]
	v_lshlrev_b64 v[222:223], 1, v[222:223]
	v_lshl_add_u64 v[220:221], s[0:1], 0, v[220:221]
	global_load_ushort v35, v[220:221], off
	v_lshl_add_u64 v[220:221], s[0:1], 0, v[222:223]
	global_load_ushort v239, v[220:221], off
	v_add_u32_e32 v220, 36, v226
	v_xad_u32 v221, v227, -5, s27
	v_cndmask_b32_e32 v220, v221, v220, vcc
	v_add_u32_e32 v220, s97, v220
	global_load_ushort v115, v[224:225], off
	v_lshl_add_u64 v[224:225], s[28:29], 0, v[222:223]
	v_add_u32_e32 v222, s24, v220
	v_ashrrev_i32_e32 v221, 31, v220
	v_lshlrev_b64 v[220:221], 9, v[220:221]
	v_ashrrev_i32_e32 v223, 31, v222
	v_lshl_add_u64 v[220:221], v[220:221], 0, v[42:43]
	v_lshlrev_b64 v[222:223], 9, v[222:223]
	global_load_ushort v238, v[224:225], off
	v_lshl_add_u64 v[224:225], v[220:221], 2, s[36:37]
	v_lshl_add_u64 v[222:223], v[222:223], 0, v[42:43]
	global_load_dword v118, v[224:225], off
	v_lshl_add_u64 v[224:225], v[222:223], 2, s[36:37]
	v_lshlrev_b64 v[220:221], 1, v[220:221]
	global_load_dword v119, v[224:225], off
	v_lshl_add_u64 v[224:225], s[28:29], 0, v[220:221]
	v_lshlrev_b64 v[222:223], 1, v[222:223]
	v_lshl_add_u64 v[220:221], s[0:1], 0, v[220:221]
	global_load_ushort v36, v[220:221], off
	v_lshl_add_u64 v[220:221], s[0:1], 0, v[222:223]
	global_load_ushort v241, v[220:221], off
	v_add_u32_e32 v220, 38, v226
	v_xad_u32 v221, v227, -7, s27
	v_cndmask_b32_e32 v220, v221, v220, vcc
	v_add_u32_e32 v220, s97, v220
	global_load_ushort v134, v[224:225], off
	v_lshl_add_u64 v[224:225], s[28:29], 0, v[222:223]
	v_add_u32_e32 v222, s24, v220
	v_ashrrev_i32_e32 v221, 31, v220
	v_lshlrev_b64 v[220:221], 9, v[220:221]
	v_ashrrev_i32_e32 v223, 31, v222
	v_lshl_add_u64 v[220:221], v[220:221], 0, v[42:43]
	v_lshlrev_b64 v[222:223], 9, v[222:223]
	global_load_ushort v240, v[224:225], off
	v_lshl_add_u64 v[224:225], v[220:221], 2, s[36:37]
	v_lshl_add_u64 v[222:223], v[222:223], 0, v[42:43]
	global_load_dword v120, v[224:225], off
	v_lshl_add_u64 v[224:225], v[222:223], 2, s[36:37]
	v_lshlrev_b64 v[220:221], 1, v[220:221]
	global_load_dword v121, v[224:225], off
	v_lshl_add_u64 v[224:225], s[28:29], 0, v[220:221]
	v_lshlrev_b64 v[222:223], 1, v[222:223]
	v_lshl_add_u64 v[220:221], s[0:1], 0, v[220:221]
	global_load_ushort v37, v[220:221], off
	v_lshl_add_u64 v[220:221], s[0:1], 0, v[222:223]
	global_load_ushort v243, v[220:221], off
	v_add_u32_e32 v220, 40, v226
	v_xad_u32 v221, v227, -9, s27
	v_cndmask_b32_e32 v220, v221, v220, vcc
	v_add_u32_e32 v220, s97, v220
	global_load_ushort v140, v[224:225], off
	v_lshl_add_u64 v[224:225], s[28:29], 0, v[222:223]
	v_add_u32_e32 v222, s24, v220
	v_ashrrev_i32_e32 v221, 31, v220
	v_lshlrev_b64 v[220:221], 9, v[220:221]
	v_ashrrev_i32_e32 v223, 31, v222
	v_lshl_add_u64 v[220:221], v[220:221], 0, v[42:43]
	v_lshlrev_b64 v[222:223], 9, v[222:223]
	global_load_ushort v242, v[224:225], off
	v_lshl_add_u64 v[224:225], v[220:221], 2, s[36:37]
	v_lshl_add_u64 v[222:223], v[222:223], 0, v[42:43]
	global_load_dword v122, v[224:225], off
	v_lshl_add_u64 v[224:225], v[222:223], 2, s[36:37]
	v_lshlrev_b64 v[220:221], 1, v[220:221]
	global_load_dword v123, v[224:225], off
	v_lshl_add_u64 v[224:225], s[28:29], 0, v[220:221]
	v_lshlrev_b64 v[222:223], 1, v[222:223]
	v_lshl_add_u64 v[220:221], s[0:1], 0, v[220:221]
	global_load_ushort v38, v[220:221], off
	v_lshl_add_u64 v[220:221], s[0:1], 0, v[222:223]
	global_load_ushort v244, v[220:221], off
	v_add_u32_e32 v220, 42, v226
	v_xad_u32 v221, v227, -11, s27
	v_cndmask_b32_e32 v220, v221, v220, vcc
	v_add_u32_e32 v220, s97, v220
	global_load_ushort v152, v[224:225], off
	v_lshl_add_u64 v[224:225], s[28:29], 0, v[222:223]
	v_add_u32_e32 v222, s24, v220
	v_ashrrev_i32_e32 v221, 31, v220
	v_lshlrev_b64 v[220:221], 9, v[220:221]
	v_ashrrev_i32_e32 v223, 31, v222
	v_lshl_add_u64 v[220:221], v[220:221], 0, v[42:43]
	v_lshlrev_b64 v[222:223], 9, v[222:223]
	global_load_ushort v245, v[224:225], off
	v_lshl_add_u64 v[224:225], v[220:221], 2, s[36:37]
	v_lshl_add_u64 v[222:223], v[222:223], 0, v[42:43]
	global_load_dword v124, v[224:225], off
	v_lshl_add_u64 v[224:225], v[222:223], 2, s[36:37]
	v_lshlrev_b64 v[220:221], 1, v[220:221]
	global_load_dword v125, v[224:225], off
	v_lshl_add_u64 v[224:225], s[28:29], 0, v[220:221]
	v_lshlrev_b64 v[222:223], 1, v[222:223]
	v_lshl_add_u64 v[220:221], s[0:1], 0, v[220:221]
	global_load_ushort v39, v[220:221], off
	v_lshl_add_u64 v[220:221], s[0:1], 0, v[222:223]
	global_load_ushort v246, v[220:221], off
	v_add_u32_e32 v220, 44, v226
	v_xad_u32 v221, v227, -13, s27
	v_cndmask_b32_e32 v220, v221, v220, vcc
	v_add_u32_e32 v220, s97, v220
	global_load_ushort v153, v[224:225], off
	v_lshl_add_u64 v[224:225], s[28:29], 0, v[222:223]
	v_add_u32_e32 v222, s24, v220
	v_ashrrev_i32_e32 v221, 31, v220
	v_lshlrev_b64 v[220:221], 9, v[220:221]
	v_ashrrev_i32_e32 v223, 31, v222
	v_lshl_add_u64 v[220:221], v[220:221], 0, v[42:43]
	v_lshlrev_b64 v[222:223], 9, v[222:223]
	global_load_ushort v247, v[224:225], off
	v_lshl_add_u64 v[224:225], v[220:221], 2, s[36:37]
	v_lshl_add_u64 v[222:223], v[222:223], 0, v[42:43]
	global_load_dword v128, v[224:225], off
	v_lshl_add_u64 v[224:225], v[222:223], 2, s[36:37]
	v_lshlrev_b64 v[220:221], 1, v[220:221]
	global_load_dword v129, v[224:225], off
	v_lshl_add_u64 v[224:225], s[28:29], 0, v[220:221]
	v_lshlrev_b64 v[222:223], 1, v[222:223]
	v_lshl_add_u64 v[220:221], s[0:1], 0, v[220:221]
	global_load_ushort v40, v[220:221], off
	v_lshl_add_u64 v[220:221], s[0:1], 0, v[222:223]
	global_load_ushort v248, v[220:221], off
	v_add_u32_e32 v220, 46, v226
	v_xad_u32 v221, v227, -15, s27
	v_cndmask_b32_e32 v220, v221, v220, vcc
	v_add_u32_e32 v220, s97, v220
	global_load_ushort v154, v[224:225], off
	v_lshl_add_u64 v[224:225], s[28:29], 0, v[222:223]
	v_add_u32_e32 v222, s24, v220
	v_ashrrev_i32_e32 v221, 31, v220
	v_lshlrev_b64 v[220:221], 9, v[220:221]
	v_ashrrev_i32_e32 v223, 31, v222
	v_lshl_add_u64 v[220:221], v[220:221], 0, v[42:43]
	v_lshlrev_b64 v[222:223], 9, v[222:223]
	global_load_ushort v249, v[224:225], off
	v_lshl_add_u64 v[224:225], v[220:221], 2, s[36:37]
	v_lshl_add_u64 v[222:223], v[222:223], 0, v[42:43]
	v_lshlrev_b64 v[220:221], 1, v[220:221]
	global_load_dword v130, v[224:225], off
	v_lshl_add_u64 v[224:225], v[222:223], 2, s[36:37]
	v_lshl_add_u64 v[226:227], s[28:29], 0, v[220:221]
	v_lshlrev_b64 v[222:223], 1, v[222:223]
	global_load_ushort v155, v[226:227], off
	v_lshl_add_u64 v[226:227], s[28:29], 0, v[222:223]
	v_lshl_add_u64 v[220:221], s[0:1], 0, v[220:221]
	global_load_ushort v250, v[226:227], off
	global_load_ushort v41, v[220:221], off
	v_lshl_add_u64 v[220:221], s[0:1], 0, v[222:223]
	global_load_ushort v251, v[220:221], off
	global_load_dword v131, v[224:225], off
	s_branch .LBB0_784

.LBB0_815:
	ds_read_b128 v[146:149], v130
	ds_read_b128 v[150:153], v130 offset:32
	ds_read_b128 v[154:157], v131 offset:36864
	ds_read_b128 v[180:183], v131 offset:36896
	ds_read_b128 v[184:187], v130 offset:4608
	ds_read_b128 v[188:191], v130 offset:4640
	ds_read_b128 v[192:195], v131 offset:41472
	ds_read_b128 v[196:199], v131 offset:41504
	s_waitcnt lgkmcnt(5)
	v_mfma_f32_32x32x16_bf16 v[50:65], v[146:149], v[154:157], v[50:65]
	s_waitcnt vmcnt(15)
	ds_write_b128 v142, v[66:69] offset:18432
	s_add_i32 s20, s39, -1
	s_cmp_lt_u32 s20, s36
	s_cselect_b64 vcc, -1, 0
	s_and_b64 s[20:21], vcc, exec
	s_cselect_b32 s45, 0, s36
	s_lshl_b32 s46, s45, 7
	s_waitcnt lgkmcnt(2)
	v_mfma_f32_32x32x16_bf16 v[16:31], v[146:149], v[192:195], v[16:31]
	s_waitcnt vmcnt(14)
	ds_write_b128 v142, v[70:73] offset:55296
	s_sub_i32 s20, s41, s46
	s_add_i32 s47, s20, 0xffffff80
	s_and_b64 s[20:21], vcc, exec
	s_cselect_b32 s21, s62, s38
	s_cselect_b32 s20, s40, s37
	s_and_b32 s21, s21, 0xffff
	s_waitcnt lgkmcnt(5)
	v_mfma_f32_32x32x16_bf16 v[34:49], v[184:187], v[154:157], v[34:49]
	s_waitcnt vmcnt(13)
	ds_write_b128 v143, v[74:77] offset:18432
	s_and_b64 s[42:43], vcc, exec
	s_cselect_b32 s42, s63, s29
	s_cselect_b32 s48, s44, s28
	s_and_b32 s49, s42, 0xffff
	s_and_b64 s[42:43], vcc, exec
	s_mov_b32 s50, s22
	s_waitcnt lgkmcnt(4)
	v_mfma_f32_32x32x16_bf16 v[0:15], v[184:187], v[192:195], v[0:15]
	s_waitcnt vmcnt(12)
	ds_write_b128 v143, v[78:81] offset:55296
	s_mov_b32 s51, s23
	v_cndmask_b32_e32 v146, v135, v132, vcc
	s_cselect_b32 s64, s30, s59
	s_waitcnt lgkmcnt(8)
	v_mfma_f32_32x32x16_bf16 v[50:65], v[150:153], v[180:183], v[50:65]
	ds_read_b128 v[200:203], v130 offset:64
	ds_read_b128 v[204:207], v130 offset:96
	s_waitcnt vmcnt(11)
	ds_write_b128 v144, v[82:85] offset:18432
	s_waitcnt lgkmcnt(7)
	v_mfma_f32_32x32x16_bf16 v[16:31], v[150:153], v[196:199], v[16:31]
	ds_read_b128 v[208:211], v131 offset:36928
	ds_read_b128 v[212:215], v131 offset:36960
	s_waitcnt vmcnt(10)
	ds_write_b128 v144, v[90:93] offset:55296
	s_waitcnt lgkmcnt(12)
	v_mfma_f32_32x32x16_bf16 v[34:49], v[188:191], v[180:183], v[34:49]
	ds_read_b128 v[216:219], v130 offset:4672
	ds_read_b128 v[220:223], v130 offset:4704
	s_waitcnt vmcnt(9)
	ds_write_b128 v145, v[86:89] offset:18432
	v_cndmask_b32_e32 v86, v134, v32, vcc
	s_waitcnt lgkmcnt(13)
	v_mfma_f32_32x32x16_bf16 v[0:15], v[188:191], v[196:199], v[0:15]
	ds_read_b128 v[224:227], v131 offset:41536
	ds_read_b128 v[228:231], v131 offset:41568
	s_waitcnt vmcnt(8)
	ds_write_b128 v145, v[94:97] offset:55296
	s_waitcnt lgkmcnt(8)
	v_mfma_f32_32x32x16_bf16 v[50:65], v[200:203], v[208:211], v[50:65]
	buffer_load_dwordx4 v[66:69], v86, s[20:23], s47 offen
	s_waitcnt lgkmcnt(2)
	v_mfma_f32_32x32x16_bf16 v[16:31], v[200:203], v[224:227], v[16:31]
	buffer_load_dwordx4 v[70:73], v146, s[48:51], s47 offen
	s_lshl_b32 s47, s64, 6
	s_and_b64 s[42:43], vcc, exec
	s_cselect_b32 s42, s31, s60
	s_sub_i32 s43, s47, s46
	s_add_i32 s43, s41, s43
	s_addk_i32 s43, 0xff80
	s_waitcnt lgkmcnt(5)
	v_mfma_f32_32x32x16_bf16 v[34:49], v[216:219], v[208:211], v[34:49]
	buffer_load_dwordx4 v[74:77], v86, s[20:23], s43 offen
	s_lshl_b32 s43, s42, 6
	s_sub_i32 s43, s43, s46
	s_add_i32 s43, s41, s43
	s_addk_i32 s43, 0xff80
	s_waitcnt lgkmcnt(2)
	v_mfma_f32_32x32x16_bf16 v[0:15], v[216:219], v[224:227], v[0:15]
	buffer_load_dwordx4 v[78:81], v146, s[48:51], s43 offen
	s_sub_i32 s43, s64, s45
	s_add_i32 s43, s39, s43
	s_lshl_b32 s43, s43, 7
	s_addk_i32 s43, 0xff80
	s_mulk_i32 s64, 0xc0
	s_sub_i32 s45, s42, s45
	s_mulk_i32 s42, 0xc0
	s_waitcnt lgkmcnt(7)
	v_mfma_f32_32x32x16_bf16 v[50:65], v[204:207], v[212:215], v[50:65]
	buffer_load_dwordx4 v[82:85], v86, s[20:23], s43 offen
	s_sub_i32 s43, s64, s46
	s_add_i32 s45, s39, s45
	s_sub_i32 s42, s42, s46
	s_lshl_b32 s45, s45, 7
	s_add_i32 s43, s41, s43
	s_add_i32 s42, s41, s42
	s_addk_i32 s45, 0xff80
	s_addk_i32 s43, 0xff80
	s_addk_i32 s42, 0xff80
	s_waitcnt lgkmcnt(1)
	v_mfma_f32_32x32x16_bf16 v[16:31], v[204:207], v[228:231], v[16:31]
	buffer_load_dwordx4 v[90:93], v146, s[48:51], s45 offen
	s_waitcnt lgkmcnt(4)
	v_mfma_f32_32x32x16_bf16 v[34:49], v[220:223], v[212:215], v[34:49]
	buffer_load_dwordx4 v[86:89], v86, s[20:23], s43 offen
	s_waitcnt lgkmcnt(1)
	v_mfma_f32_32x32x16_bf16 v[0:15], v[220:223], v[228:231], v[0:15]
	buffer_load_dwordx4 v[94:97], v146, s[48:51], s42 offen
	s_waitcnt lgkmcnt(0)
	s_barrier
	ds_read_b128 v[146:149], v130 offset:18432
	ds_read_b128 v[150:153], v130 offset:18464
	ds_read_b128 v[154:157], v131 offset:55296
	ds_read_b128 v[180:183], v131 offset:55328
	ds_read_b128 v[184:187], v130 offset:23040
	ds_read_b128 v[188:191], v130 offset:23072
	ds_read_b128 v[192:195], v131 offset:59904
	ds_read_b128 v[196:199], v131 offset:59936
	s_waitcnt lgkmcnt(5)
	v_mfma_f32_32x32x16_bf16 v[50:65], v[146:149], v[154:157], v[50:65]
	s_waitcnt vmcnt(15)
	ds_write_b128 v142, v[98:101]
	s_cmp_lt_u32 s39, s36
	s_cselect_b64 vcc, -1, 0
	s_and_b64 s[20:21], vcc, exec
	s_cselect_b32 s45, 0, s36
	s_lshl_b32 s46, s45, 7
	s_sub_i32 s47, s41, s46
	s_waitcnt lgkmcnt(2)
	v_mfma_f32_32x32x16_bf16 v[16:31], v[146:149], v[192:195], v[16:31]
	s_waitcnt vmcnt(14)
	ds_write_b128 v142, v[102:105] offset:36864
	s_and_b64 s[20:21], vcc, exec
	s_cselect_b32 s21, s62, s38
	s_cselect_b32 s20, s40, s37
	s_and_b32 s21, s21, 0xffff
	s_and_b64 s[42:43], vcc, exec
	s_cselect_b32 s42, s63, s29
	s_waitcnt lgkmcnt(5)
	v_mfma_f32_32x32x16_bf16 v[34:49], v[184:187], v[154:157], v[34:49]
	s_waitcnt vmcnt(13)
	ds_write_b128 v143, v[106:109]
	s_cselect_b32 s48, s44, s28
	s_and_b32 s49, s42, 0xffff
	s_and_b64 s[42:43], vcc, exec
	s_waitcnt lgkmcnt(4)
	v_mfma_f32_32x32x16_bf16 v[0:15], v[184:187], v[192:195], v[0:15]
	s_waitcnt vmcnt(12)
	ds_write_b128 v143, v[114:117] offset:36864
	s_waitcnt lgkmcnt(8)
	v_mfma_f32_32x32x16_bf16 v[50:65], v[150:153], v[180:183], v[50:65]
	ds_read_b128 v[200:203], v130 offset:18496
	ds_read_b128 v[204:207], v130 offset:18528
	s_waitcnt vmcnt(11)
	ds_write_b128 v144, v[110:113]
	s_waitcnt lgkmcnt(7)
	v_mfma_f32_32x32x16_bf16 v[16:31], v[150:153], v[196:199], v[16:31]
	ds_read_b128 v[208:211], v131 offset:55360
	ds_read_b128 v[212:215], v131 offset:55392
	s_waitcnt vmcnt(10)
	ds_write_b128 v144, v[118:121] offset:36864
	s_waitcnt lgkmcnt(12)
	v_mfma_f32_32x32x16_bf16 v[34:49], v[188:191], v[180:183], v[34:49]
	ds_read_b128 v[216:219], v130 offset:23104
	ds_read_b128 v[220:223], v130 offset:23136
	s_waitcnt vmcnt(9)
	ds_write_b128 v145, v[122:125]
	v_cndmask_b32_e32 v122, v134, v32, vcc
	s_waitcnt lgkmcnt(13)
	v_mfma_f32_32x32x16_bf16 v[0:15], v[188:191], v[196:199], v[0:15]
	ds_read_b128 v[224:227], v131 offset:59968
	ds_read_b128 v[228:231], v131 offset:60000
	s_waitcnt vmcnt(8)
	ds_write_b128 v145, v[126:129] offset:36864
	v_cndmask_b32_e32 v126, v135, v132, vcc
	s_waitcnt lgkmcnt(8)
	v_mfma_f32_32x32x16_bf16 v[50:65], v[200:203], v[208:211], v[50:65]
	buffer_load_dwordx4 v[98:101], v122, s[20:23], s47 offen
	s_waitcnt lgkmcnt(2)
	v_mfma_f32_32x32x16_bf16 v[16:31], v[200:203], v[224:227], v[16:31]
	buffer_load_dwordx4 v[102:105], v126, s[48:51], s47 offen
	s_cselect_b32 s47, s30, s59
	s_lshl_b32 s64, s47, 6
	s_and_b64 s[42:43], vcc, exec
	s_cselect_b32 s42, s31, s60
	s_sub_i32 s43, s64, s46
	s_add_i32 s43, s41, s43
	s_waitcnt lgkmcnt(5)
	v_mfma_f32_32x32x16_bf16 v[34:49], v[216:219], v[208:211], v[34:49]
	buffer_load_dwordx4 v[106:109], v122, s[20:23], s43 offen
	s_lshl_b32 s43, s42, 6
	s_sub_i32 s43, s43, s46
	s_add_i32 s43, s41, s43
	s_waitcnt lgkmcnt(2)
	v_mfma_f32_32x32x16_bf16 v[0:15], v[216:219], v[224:227], v[0:15]
	buffer_load_dwordx4 v[114:117], v126, s[48:51], s43 offen
	s_sub_i32 s43, s47, s45
	s_add_i32 s43, s39, s43
	s_lshl_b32 s43, s43, 7
	s_mulk_i32 s47, 0xc0
	s_waitcnt lgkmcnt(7)
	v_mfma_f32_32x32x16_bf16 v[50:65], v[204:207], v[212:215], v[50:65]
	buffer_load_dwordx4 v[110:113], v122, s[20:23], s43 offen
	s_sub_i32 s43, s42, s45
	s_add_i32 s43, s39, s43
	s_lshl_b32 s43, s43, 7
	s_mulk_i32 s42, 0xc0
	s_sub_i32 s42, s42, s46
	s_add_i32 s42, s41, s42
	s_waitcnt lgkmcnt(1)
	v_mfma_f32_32x32x16_bf16 v[16:31], v[204:207], v[228:231], v[16:31]
	buffer_load_dwordx4 v[118:121], v126, s[48:51], s43 offen
	s_sub_i32 s43, s47, s46
	s_add_i32 s43, s41, s43
	s_waitcnt lgkmcnt(4)
	v_mfma_f32_32x32x16_bf16 v[34:49], v[220:223], v[212:215], v[34:49]
	buffer_load_dwordx4 v[122:125], v122, s[20:23], s43 offen
	s_waitcnt lgkmcnt(1)
	v_mfma_f32_32x32x16_bf16 v[0:15], v[220:223], v[228:231], v[0:15]
	buffer_load_dwordx4 v[126:129], v126, s[48:51], s42 offen
	s_add_i32 s20, s39, 2
	s_add_i32 s21, s39, -2
	s_addk_i32 s41, 0x100
	s_cmp_ge_u32 s21, s36
	s_mov_b32 s39, s20
	s_waitcnt lgkmcnt(0)
	s_barrier
	s_cbranch_scc0 .LBB0_815
	v_readlane_b32 s36, v234, 20
	v_add_u32_e32 v136, s61, v136
	s_mov_b64 s[20:21], -1
	s_and_b64 vcc, exec, s[0:1]
	v_readlane_b32 s63, v235, 21
	v_readlane_b32 s37, v234, 21
	s_movk_i32 s40, 0x3fff
	s_movk_i32 s41, 0x1fff
	v_readlane_b32 s62, v232, 31
	s_cbranch_vccz .LBB0_888
	v_ashrrev_i32_e32 v32, 5, v136
	v_and_b32_e32 v32, -8, v32
	v_add_u32_e32 v130, s27, v32
	v_ashrrev_i32_e32 v131, 31, v130
	v_cmp_ne_u32_e32 vcc, 0, v133
	v_lshl_or_b32 v142, v140, 2, v136
	v_lshlrev_b64 v[130:131], 15, v[130:131]
	s_and_saveexec_b64 s[0:1], vcc
	s_xor_b64 s[0:1], exec, s[0:1]
	s_cbranch_execz .LBB0_883
	v_subrev_u32_e32 v143, 64, v141
	v_cmp_lt_i32_e64 s[38:39], s41, v142
	s_and_saveexec_b64 s[20:21], s[38:39]
	s_xor_b64 s[20:21], exec, s[20:21]
	s_cbranch_execz .LBB0_824
	v_cmp_lt_u32_e64 s[38:39], s40, v136
	s_and_saveexec_b64 s[28:29], s[38:39]
	s_xor_b64 s[28:29], exec, s[28:29]
	s_cbranch_execz .LBB0_821
	v_add_u32_e32 v32, 0xffffc000, v136
	v_lshrrev_b32_e32 v32, 6, v32
	v_and_b32_e32 v32, 0x3fffff8, v32
	v_add_u32_e32 v132, s27, v32
	v_ashrrev_i32_e32 v133, 31, v132
	v_lshlrev_b64 v[132:133], 6, v[132:133]
	v_or_b32_e32 v32, v132, v143
	v_mov_b64_e32 v[134:135], s[94:95]
	s_movk_i32 s38, 0xc00
	v_mad_u64_u32 v[134:135], s[30:31], v32, s38, v[134:135]
	v_mad_i32_i24 v135, v133, s38, v135
	s_mov_b64 s[30:31], 0x16e0d800
	v_lshl_add_u64 v[134:135], v[134:135], 0, s[30:31]

.LBB0_1201:
	ds_read_b128 v[188:191], v160
	ds_read_b128 v[192:195], v160 offset:32
	ds_read_b128 v[196:199], v161 offset:36864
	ds_read_b128 v[200:203], v161 offset:36896
	ds_read_b128 v[204:207], v160 offset:4608
	ds_read_b128 v[208:211], v160 offset:4640
	ds_read_b128 v[212:215], v161 offset:41472
	ds_read_b128 v[216:219], v161 offset:41504
	s_add_i32 s31, s36, 2
	s_waitcnt lgkmcnt(5)
	v_mfma_f32_32x32x16_bf16 v[50:65], v[188:191], v[196:199], v[50:65]
	s_waitcnt vmcnt(15)
	ds_write_b128 v184, v[66:69] offset:18432
	s_cmp_lt_u32 s31, 13
	s_cselect_b64 s[38:39], -1, 0
	s_and_b64 s[20:21], s[38:39], exec
	s_cselect_b32 s20, 0, 0x1fffff0
	s_add_i32 s20, s20, s36
	s_lshl_b32 s37, s20, 7
	s_waitcnt lgkmcnt(2)
	v_mfma_f32_32x32x16_bf16 v[16:31], v[188:191], v[212:215], v[16:31]
	s_waitcnt vmcnt(14)
	ds_write_b128 v184, v[74:77] offset:55296
	s_add_i32 s41, s37, 0x280
	s_and_b64 s[20:21], s[38:39], exec
	s_cselect_b32 s21, s1, s28
	s_cselect_b32 s20, s40, s27
	s_and_b32 s21, s21, 0xffff
	s_and_b64 s[38:39], s[38:39], exec
	s_waitcnt lgkmcnt(5)
	v_mfma_f32_32x32x16_bf16 v[34:49], v[204:207], v[196:199], v[34:49]
	s_waitcnt vmcnt(13)
	ds_write_b128 v185, v[70:73] offset:18432
	s_cselect_b32 s38, s25, s30
	s_cselect_b32 s64, s44, s29
	s_and_b32 s65, s38, 0xffff
	s_mov_b32 s66, s22
	s_mov_b32 s67, s23
	s_add_i32 s38, s37, 0x10280
	s_waitcnt lgkmcnt(4)
	v_mfma_f32_32x32x16_bf16 v[0:15], v[204:207], v[212:215], v[0:15]
	s_waitcnt vmcnt(12)
	ds_write_b128 v185, v[82:85] offset:55296
	s_waitcnt lgkmcnt(8)
	v_mfma_f32_32x32x16_bf16 v[50:65], v[192:195], v[200:203], v[50:65]
	ds_read_b128 v[220:223], v160 offset:64
	ds_read_b128 v[142:145], v160 offset:96
	s_waitcnt vmcnt(11)
	ds_write_b128 v186, v[78:81] offset:18432
	s_waitcnt lgkmcnt(7)
	v_mfma_f32_32x32x16_bf16 v[16:31], v[192:195], v[216:219], v[16:31]
	ds_read_b128 v[154:157], v161 offset:36928
	ds_read_b128 v[138:141], v161 offset:36960
	s_waitcnt vmcnt(10)
	ds_write_b128 v186, v[90:93] offset:55296
	s_waitcnt lgkmcnt(12)
	v_mfma_f32_32x32x16_bf16 v[34:49], v[208:211], v[200:203], v[34:49]
	ds_read_b128 v[146:149], v160 offset:4672
	ds_read_b128 v[130:133], v160 offset:4704
	s_waitcnt vmcnt(9)
	ds_write_b128 v187, v[86:89] offset:18432
	s_waitcnt lgkmcnt(13)
	v_mfma_f32_32x32x16_bf16 v[0:15], v[208:211], v[216:219], v[0:15]
	ds_read_b128 v[150:153], v161 offset:41536
	ds_read_b128 v[134:137], v161 offset:41568
	s_waitcnt vmcnt(8)
	ds_write_b128 v187, v[94:97] offset:55296
	s_waitcnt lgkmcnt(8)
	v_mfma_f32_32x32x16_bf16 v[50:65], v[220:223], v[154:157], v[50:65]
	buffer_load_dwordx4 v[66:69], v32, s[20:23], s41 offen
	s_waitcnt lgkmcnt(2)
	v_mfma_f32_32x32x16_bf16 v[16:31], v[220:223], v[150:153], v[16:31]
	buffer_load_dwordx4 v[74:77], v32, s[64:67], s41 offen
	s_waitcnt lgkmcnt(5)
	v_mfma_f32_32x32x16_bf16 v[34:49], v[146:149], v[154:157], v[34:49]
	buffer_load_dwordx4 v[70:73], v32, s[20:23], s38 offen
	s_waitcnt lgkmcnt(2)
	v_mfma_f32_32x32x16_bf16 v[0:15], v[146:149], v[150:153], v[0:15]
	buffer_load_dwordx4 v[82:85], v32, s[64:67], s38 offen
	s_add_i32 s38, s37, 0x20280
	s_add_i32 s37, s37, 0x30280
	s_waitcnt lgkmcnt(7)
	v_mfma_f32_32x32x16_bf16 v[50:65], v[142:145], v[138:141], v[50:65]
	buffer_load_dwordx4 v[78:81], v32, s[20:23], s38 offen
	s_waitcnt lgkmcnt(1)
	v_mfma_f32_32x32x16_bf16 v[16:31], v[142:145], v[134:137], v[16:31]
	buffer_load_dwordx4 v[90:93], v32, s[64:67], s38 offen
	s_waitcnt lgkmcnt(4)
	v_mfma_f32_32x32x16_bf16 v[34:49], v[130:133], v[138:141], v[34:49]
	buffer_load_dwordx4 v[86:89], v32, s[20:23], s37 offen
	s_waitcnt lgkmcnt(1)
	v_mfma_f32_32x32x16_bf16 v[0:15], v[130:133], v[134:137], v[0:15]
	buffer_load_dwordx4 v[94:97], v32, s[64:67], s37 offen
	s_waitcnt lgkmcnt(0)
	s_barrier
	ds_read_b128 v[188:191], v160 offset:18432
	ds_read_b128 v[192:195], v160 offset:18464
	ds_read_b128 v[196:199], v161 offset:55296
	ds_read_b128 v[200:203], v161 offset:55328
	ds_read_b128 v[204:207], v160 offset:23040
	ds_read_b128 v[208:211], v160 offset:23072
	ds_read_b128 v[212:215], v161 offset:59904
	ds_read_b128 v[216:219], v161 offset:59936
	s_waitcnt lgkmcnt(5)
	v_mfma_f32_32x32x16_bf16 v[50:65], v[188:191], v[196:199], v[50:65]
	s_waitcnt vmcnt(15)
	ds_write_b128 v184, v[98:101]
	s_cmp_lt_u32 s31, 12
	s_cselect_b64 s[38:39], -1, 0
	s_and_b64 s[20:21], s[38:39], exec
	s_cselect_b32 s20, 0, 0x1fffff0
	s_add_i32 s20, s20, s36
	s_lshl_b32 s41, s20, 7
	s_waitcnt lgkmcnt(2)
	v_mfma_f32_32x32x16_bf16 v[16:31], v[188:191], v[212:215], v[16:31]
	s_waitcnt vmcnt(14)
	ds_write_b128 v184, v[106:109] offset:36864
	s_add_i32 s42, s41, 0x300
	s_and_b64 s[20:21], s[38:39], exec
	s_cselect_b32 s21, s1, s28
	s_cselect_b32 s20, s40, s27
	s_and_b32 s21, s21, 0xffff
	s_and_b64 s[36:37], s[38:39], exec
	s_waitcnt lgkmcnt(5)
	v_mfma_f32_32x32x16_bf16 v[34:49], v[204:207], v[196:199], v[34:49]
	s_waitcnt vmcnt(13)
	ds_write_b128 v185, v[102:105]
	s_cselect_b32 s37, s25, s30
	s_cselect_b32 s36, s44, s29
	s_and_b32 s37, s37, 0xffff
	s_mov_b32 s38, s22
	s_mov_b32 s39, s23
	s_waitcnt lgkmcnt(4)
	v_mfma_f32_32x32x16_bf16 v[0:15], v[204:207], v[212:215], v[0:15]
	s_waitcnt vmcnt(12)
	ds_write_b128 v185, v[114:117] offset:36864
	s_waitcnt lgkmcnt(8)
	v_mfma_f32_32x32x16_bf16 v[50:65], v[192:195], v[200:203], v[50:65]
	ds_read_b128 v[220:223], v160 offset:18496
	ds_read_b128 v[142:145], v160 offset:18528
	s_waitcnt vmcnt(11)
	ds_write_b128 v186, v[110:113]
	s_waitcnt lgkmcnt(7)
	v_mfma_f32_32x32x16_bf16 v[16:31], v[192:195], v[216:219], v[16:31]
	ds_read_b128 v[154:157], v161 offset:55360
	ds_read_b128 v[138:141], v161 offset:55392
	s_waitcnt vmcnt(10)
	ds_write_b128 v186, v[122:125] offset:36864
	s_waitcnt lgkmcnt(12)
	v_mfma_f32_32x32x16_bf16 v[34:49], v[208:211], v[200:203], v[34:49]
	ds_read_b128 v[146:149], v160 offset:23104
	ds_read_b128 v[130:133], v160 offset:23136
	s_waitcnt vmcnt(9)
	ds_write_b128 v187, v[118:121]
	s_waitcnt lgkmcnt(13)
	v_mfma_f32_32x32x16_bf16 v[0:15], v[208:211], v[216:219], v[0:15]
	ds_read_b128 v[150:153], v161 offset:59968
	ds_read_b128 v[134:137], v161 offset:60000
	s_waitcnt vmcnt(8)
	ds_write_b128 v187, v[126:129] offset:36864
	s_waitcnt lgkmcnt(8)
	v_mfma_f32_32x32x16_bf16 v[50:65], v[220:223], v[154:157], v[50:65]
	buffer_load_dwordx4 v[98:101], v32, s[20:23], s42 offen
	s_waitcnt lgkmcnt(2)
	v_mfma_f32_32x32x16_bf16 v[16:31], v[220:223], v[150:153], v[16:31]
	buffer_load_dwordx4 v[106:109], v32, s[36:39], s42 offen
	s_add_i32 s42, s41, 0x10300
	s_waitcnt lgkmcnt(5)
	v_mfma_f32_32x32x16_bf16 v[34:49], v[146:149], v[154:157], v[34:49]
	buffer_load_dwordx4 v[102:105], v32, s[20:23], s42 offen
	s_waitcnt lgkmcnt(2)
	v_mfma_f32_32x32x16_bf16 v[0:15], v[146:149], v[150:153], v[0:15]
	buffer_load_dwordx4 v[114:117], v32, s[36:39], s42 offen
	s_add_i32 s42, s41, 0x20300
	s_add_i32 s41, s41, 0x30300
	s_waitcnt lgkmcnt(7)
	v_mfma_f32_32x32x16_bf16 v[50:65], v[142:145], v[138:141], v[50:65]
	buffer_load_dwordx4 v[110:113], v32, s[20:23], s42 offen
	s_waitcnt lgkmcnt(1)
	v_mfma_f32_32x32x16_bf16 v[16:31], v[142:145], v[134:137], v[16:31]
	buffer_load_dwordx4 v[122:125], v32, s[36:39], s42 offen
	s_waitcnt lgkmcnt(4)
	v_mfma_f32_32x32x16_bf16 v[34:49], v[130:133], v[138:141], v[34:49]
	buffer_load_dwordx4 v[118:121], v32, s[20:23], s41 offen
	s_waitcnt lgkmcnt(1)
	v_mfma_f32_32x32x16_bf16 v[0:15], v[130:133], v[134:137], v[0:15]
	buffer_load_dwordx4 v[126:129], v32, s[36:39], s41 offen
	s_cmp_gt_u32 s31, 13
	s_mov_b32 s36, s31
	s_waitcnt lgkmcnt(0)
	s_barrier
	s_cbranch_scc0 .LBB0_1201
	s_andn2_b32 s24, s24, 63
	v_add_u32_e32 v142, s0, v183
	v_and_or_b32 v143, v182, 64, s54
	s_cmp_lg_u32 s24, 64
	s_mov_b64 s[0:1], -1
	s_cselect_b64 s[20:21], -1, 0
	s_and_b64 vcc, exec, s[48:49]
	v_ashrrev_i32_e32 v130, 8, v142
	v_or_b32_e32 v146, v143, v181
	s_movk_i32 s44, 0xc00
	s_cbranch_vccz .LBB0_1278
	v_lshl_or_b32 v144, v180, 2, v142
	s_movk_i32 s0, 0x700
	v_mul_lo_u32 v145, v144, s0
	s_add_i32 s0, s54, 0xfffffa80
	s_cmpk_gt_u32 s0, 0xff
	s_mov_b64 s[0:1], -1
	s_cbranch_scc0 .LBB0_1207
	s_movk_i32 s0, 0x6a0
	v_cmp_gt_i32_e32 vcc, s0, v143
	s_and_saveexec_b64 s[0:1], vcc
	s_cbranch_execz .LBB0_1206
	v_readlane_b32 s24, v235, 34
	v_add_lshl_u32 v32, v145, v146, 1
	v_cvt_pk_bf16_f32 v131, v50, s0
	v_readlane_b32 s25, v235, 35
	v_cvt_pk_bf16_f32 v132, v51, s0
	s_nop 3
	global_store_short v32, v131, s[24:25]
	v_add_u32_e32 v131, 0xe00, v32
	global_store_short v131, v132, s[24:25]
	v_add_u32_e32 v131, 0x1c00, v32
	v_cvt_pk_bf16_f32 v132, v52, s0
	global_store_short v131, v132, s[24:25]
	v_add_u32_e32 v131, 0x2a00, v32
	v_cvt_pk_bf16_f32 v132, v53, s0
	global_store_short v131, v132, s[24:25]
	v_add_u32_e32 v131, 0x7000, v32
	v_cvt_pk_bf16_f32 v132, v54, s0
	global_store_short v131, v132, s[24:25]
	v_add_u32_e32 v131, 0x7e00, v32
	v_cvt_pk_bf16_f32 v132, v55, s0
	global_store_short v131, v132, s[24:25]
	v_add_u32_e32 v131, 0x8c00, v32
	v_cvt_pk_bf16_f32 v132, v56, s0
	global_store_short v131, v132, s[24:25]
	v_add_u32_e32 v131, 0x9a00, v32
	v_cvt_pk_bf16_f32 v132, v57, s0
	global_store_short v131, v132, s[24:25]
	v_add_u32_e32 v131, 0xe000, v32
	v_cvt_pk_bf16_f32 v132, v58, s0
	global_store_short v131, v132, s[24:25]
	v_add_u32_e32 v131, 0xee00, v32
	v_cvt_pk_bf16_f32 v132, v59, s0
	global_store_short v131, v132, s[24:25]
	v_add_u32_e32 v131, 0xfc00, v32
	v_cvt_pk_bf16_f32 v132, v60, s0
	global_store_short v131, v132, s[24:25]
	v_add_u32_e32 v131, 0x10a00, v32
	v_cvt_pk_bf16_f32 v132, v61, s0
	global_store_short v131, v132, s[24:25]
	v_add_u32_e32 v131, 0x15000, v32
	v_cvt_pk_bf16_f32 v132, v62, s0
	global_store_short v131, v132, s[24:25]
	v_add_u32_e32 v131, 0x15e00, v32
	v_cvt_pk_bf16_f32 v132, v63, s0
	global_store_short v131, v132, s[24:25]
	v_add_u32_e32 v131, 0x16c00, v32
	v_cvt_pk_bf16_f32 v132, v64, s0
	global_store_short v131, v132, s[24:25]
	v_add_u32_e32 v131, 0x17a00, v32
	v_cvt_pk_bf16_f32 v132, v65, s0
	global_store_short v131, v132, s[24:25]
	v_add_u32_e32 v131, 0x1c000, v32
	v_cvt_pk_bf16_f32 v132, v34, s0
	global_store_short v131, v132, s[24:25]
	v_add_u32_e32 v131, 0x1ce00, v32
	v_cvt_pk_bf16_f32 v132, v35, s0
	global_store_short v131, v132, s[24:25]
	v_add_u32_e32 v131, 0x1dc00, v32
	v_cvt_pk_bf16_f32 v132, v36, s0
	global_store_short v131, v132, s[24:25]
	v_add_u32_e32 v131, 0x1ea00, v32
	v_cvt_pk_bf16_f32 v132, v37, s0
	global_store_short v131, v132, s[24:25]
	v_add_u32_e32 v131, 0x23000, v32
	v_cvt_pk_bf16_f32 v132, v38, s0
	global_store_short v131, v132, s[24:25]
	v_add_u32_e32 v131, 0x23e00, v32
	v_cvt_pk_bf16_f32 v132, v39, s0
	global_store_short v131, v132, s[24:25]
	v_add_u32_e32 v131, 0x24c00, v32
	v_cvt_pk_bf16_f32 v132, v40, s0
	global_store_short v131, v132, s[24:25]
	v_add_u32_e32 v131, 0x25a00, v32
	v_cvt_pk_bf16_f32 v132, v41, s0
	global_store_short v131, v132, s[24:25]
	v_add_u32_e32 v131, 0x2a000, v32
	v_cvt_pk_bf16_f32 v132, v42, s0
	global_store_short v131, v132, s[24:25]
	v_add_u32_e32 v131, 0x2ae00, v32
	v_cvt_pk_bf16_f32 v132, v43, s0
	global_store_short v131, v132, s[24:25]
	v_add_u32_e32 v131, 0x2bc00, v32
	v_cvt_pk_bf16_f32 v132, v44, s0
	global_store_short v131, v132, s[24:25]
	v_add_u32_e32 v131, 0x2ca00, v32
	v_cvt_pk_bf16_f32 v132, v45, s0
	global_store_short v131, v132, s[24:25]
	v_add_u32_e32 v131, 0x31000, v32
	v_cvt_pk_bf16_f32 v132, v46, s0
	global_store_short v131, v132, s[24:25]
	v_add_u32_e32 v131, 0x31e00, v32
	v_cvt_pk_bf16_f32 v132, v47, s0
	global_store_short v131, v132, s[24:25]
	v_add_u32_e32 v131, 0x32c00, v32
	v_cvt_pk_bf16_f32 v132, v48, s0
	global_store_short v131, v132, s[24:25]
	v_add_u32_e32 v32, 0x33a00, v32
	v_cvt_pk_bf16_f32 v131, v49, s0
	global_store_short v32, v131, s[24:25]

	.amdhsa_kernel _Z4mega1Pii
		.amdhsa_group_segment_fixed_size 73744
		.amdhsa_private_segment_fixed_size 0
		.amdhsa_kernarg_size 520
		.amdhsa_user_sgpr_count 2
		.amdhsa_user_sgpr_dispatch_ptr 0
		.amdhsa_user_sgpr_queue_ptr 0
		.amdhsa_user_sgpr_kernarg_segment_ptr 1
		.amdhsa_user_sgpr_dispatch_id 0
		.amdhsa_user_sgpr_kernarg_preload_length 0
		.amdhsa_user_sgpr_kernarg_preload_offset 0
		.amdhsa_user_sgpr_private_segment_size 0
		.amdhsa_uses_dynamic_stack 0
		.amdhsa_enable_private_segment 0
		.amdhsa_system_sgpr_workgroup_id_x 1
		.amdhsa_system_sgpr_workgroup_id_y 0
		.amdhsa_system_sgpr_workgroup_id_z 0
		.amdhsa_system_sgpr_workgroup_info 0
		.amdhsa_system_vgpr_workitem_id 2
		.amdhsa_next_free_vgpr 252
		.amdhsa_next_free_sgpr 100
		.amdhsa_accum_offset 252
		.amdhsa_reserve_vcc 1
		.amdhsa_float_round_mode_32 0
		.amdhsa_float_round_mode_16_64 0
		.amdhsa_float_denorm_mode_32 3
		.amdhsa_float_denorm_mode_16_64 3
		.amdhsa_dx10_clamp 1
		.amdhsa_ieee_mode 1
		.amdhsa_fp16_overflow 0
		.amdhsa_tg_split 0
		.amdhsa_exception_fp_ieee_invalid_op 0
		.amdhsa_exception_fp_denorm_src 0
		.amdhsa_exception_fp_ieee_div_zero 0
		.amdhsa_exception_fp_ieee_overflow 0
		.amdhsa_exception_fp_ieee_underflow 0
		.amdhsa_exception_fp_ieee_inexact 0
		.amdhsa_exception_int_div_zero 0
	.end_amdhsa_kernel

amdhsa.kernels:
  - .agpr_count:     0
    .args:
      - .offset:         0
        .size:           256
        .value_kind:     by_value
      - .offset:         256
        .size:           4
        .value_kind:     by_value
      - .offset:         260
        .size:           4
        .value_kind:     by_value
      - .offset:         264
        .size:           4
        .value_kind:     hidden_block_count_x
      - .offset:         268
        .size:           4
        .value_kind:     hidden_block_count_y
      - .offset:         272
        .size:           4
        .value_kind:     hidden_block_count_z
      - .offset:         276
        .size:           2
        .value_kind:     hidden_group_size_x
      - .offset:         278
        .size:           2
        .value_kind:     hidden_group_size_y
      - .offset:         280
        .size:           2
        .value_kind:     hidden_group_size_z
      - .offset:         282
        .size:           2
        .value_kind:     hidden_remainder_x
      - .offset:         284
        .size:           2
        .value_kind:     hidden_remainder_y
      - .offset:         286
        .size:           2
        .value_kind:     hidden_remainder_z
      - .offset:         304
        .size:           8
        .value_kind:     hidden_global_offset_x
      - .offset:         312
        .size:           8
        .value_kind:     hidden_global_offset_y
      - .offset:         320
        .size:           8
        .value_kind:     hidden_global_offset_z
      - .offset:         328
        .size:           2
        .value_kind:     hidden_grid_dims
      - .offset:         352
        .size:           8
        .value_kind:     hidden_multigrid_sync_arg
    .group_segment_fixed_size: 73744
    .kernarg_segment_align: 8
    .kernarg_segment_size: 520
    .language:       OpenCL C
    .language_version:
      - 2
      - 0
    .max_flat_workgroup_size: 256
    .name:           _Z4mega1Pii
    .private_segment_fixed_size: 0
    .sgpr_count:     106
    .sgpr_spill_count: 268
    .symbol:         _Z4mega1Pii.kd
    .uniform_work_group_size: 1
    .uses_dynamic_stack: false
    .vgpr_count:     252
    .vgpr_spill_count: 0
    .wavefront_size: 64
